# non-temporal hint on the read-once row loads of the GroupNorm loop and the LayerNorm phases
# speedup vs baseline: 1.0037x; 1.0037x over previous
.LBB0_412:
	s_cmp_lt_i32 s30, 4
	s_cselect_b64 s[8:9], -1, 0
	s_and_b64 s[10:11], s[8:9], s[6:7]
	s_andn2_b64 vcc, exec, s[10:11]
	v_and_b32_e32 v136, 63, v231
	s_cbranch_vccnz .LBB0_427
	s_load_dwordx4 s[12:15], s[0:1], 0x58
	s_load_dwordx2 s[16:17], s[0:1], 0x8
	v_lshl_add_u32 v32, s2, 3, v230
	s_movk_i32 s3, 0x2000
	v_cmp_gt_i32_e32 vcc, s3, v32
	s_and_saveexec_b64 s[18:19], vcc
	s_cbranch_execz .LBB0_418
	s_load_dwordx4 s[60:63], s[0:1], 0x58
	v_lshl_add_u32 v2, s2, 3, v230
	v_lshlrev_b32_e32 v137, 4, v136
	v_lshlrev_b32_e32 v1, 3, v136
	v_lshl_add_u32 v1, v2, 12, v1
	v_add_u32_e32 v4, 0x1000, v137
	s_add_u32 s88, s28, 0xe600000
	s_addc_u32 s89, s29, 0
	s_add_u32 s90, s28, 0xc500000
	s_addc_u32 s91, s29, 0
	global_load_dwordx2 v[204:205], v1, s[88:89] offset:0 nt
	global_load_dwordx2 v[206:207], v1, s[88:89] offset:512 nt
	global_load_dwordx2 v[208:209], v1, s[88:89] offset:1024 nt
	global_load_dwordx2 v[210:211], v1, s[88:89] offset:1536 nt
	global_load_dwordx2 v[212:213], v1, s[88:89] offset:2048 nt
	global_load_dwordx2 v[214:215], v1, s[88:89] offset:2560 nt
	global_load_dwordx2 v[216:217], v1, s[88:89] offset:3072 nt
	global_load_dwordx2 v[218:219], v1, s[88:89] offset:3584 nt
	s_add_u32 s88, s88, 0x800000
	s_addc_u32 s89, s89, 0
	s_waitcnt lgkmcnt(0)
	global_load_dwordx4 v[140:143], v137, s[60:61] offset:0
	global_load_dwordx4 v[144:147], v137, s[60:61] offset:1024
	global_load_dwordx4 v[148:151], v137, s[60:61] offset:2048
	global_load_dwordx4 v[152:155], v137, s[60:61] offset:3072
	global_load_dwordx4 v[156:159], v4, s[60:61] offset:0
	global_load_dwordx4 v[160:163], v4, s[60:61] offset:1024
	global_load_dwordx4 v[164:167], v4, s[60:61] offset:2048
	global_load_dwordx4 v[168:171], v4, s[60:61] offset:3072
	global_load_dwordx4 v[172:175], v137, s[62:63] offset:0
	global_load_dwordx4 v[176:179], v137, s[62:63] offset:1024
	global_load_dwordx4 v[180:183], v137, s[62:63] offset:2048
	global_load_dwordx4 v[184:187], v137, s[62:63] offset:3072
	global_load_dwordx4 v[188:191], v4, s[62:63] offset:0
	global_load_dwordx4 v[192:195], v4, s[62:63] offset:1024
	global_load_dwordx4 v[196:199], v4, s[62:63] offset:2048
	global_load_dwordx4 v[200:203], v4, s[62:63] offset:3072
	global_load_dwordx2 v[110:111], v1, s[88:89] offset:0 nt
	global_load_dwordx2 v[112:113], v1, s[88:89] offset:512 nt
	global_load_dwordx2 v[114:115], v1, s[88:89] offset:1024 nt
	global_load_dwordx2 v[116:117], v1, s[88:89] offset:1536 nt
	global_load_dwordx2 v[118:119], v1, s[88:89] offset:2048 nt
	global_load_dwordx2 v[120:121], v1, s[88:89] offset:2560 nt
	global_load_dwordx2 v[122:123], v1, s[88:89] offset:3072 nt
	global_load_dwordx2 v[124:125], v1, s[88:89] offset:3584 nt
	s_add_u32 s88, s88, 0x800000
	s_addc_u32 s89, s89, 0
	global_load_dwordx2 v[24:25], v1, s[88:89] offset:0 nt
	global_load_dwordx2 v[26:27], v1, s[88:89] offset:512 nt
	global_load_dwordx2 v[8:9], v1, s[88:89] offset:1024 nt
	global_load_dwordx2 v[10:11], v1, s[88:89] offset:1536 nt
	global_load_dwordx2 v[220:221], v1, s[88:89] offset:2048 nt
	global_load_dwordx2 v[222:223], v1, s[88:89] offset:2560 nt
	global_load_dwordx2 v[224:225], v1, s[88:89] offset:3072 nt
	global_load_dwordx2 v[226:227], v1, s[88:89] offset:3584 nt
	s_add_u32 s88, s88, 0x800000
	s_addc_u32 s89, s89, 0
	s_waitcnt vmcnt(32)
	v_lshlrev_b32_e32 v126, 16, v204
	v_and_b32_e32 v127, 0xffff0000, v204
	v_lshlrev_b32_e32 v128, 16, v205
	v_and_b32_e32 v129, 0xffff0000, v205
	v_lshlrev_b32_e32 v130, 16, v206
	v_and_b32_e32 v131, 0xffff0000, v206
	v_lshlrev_b32_e32 v132, 16, v207
	v_and_b32_e32 v133, 0xffff0000, v207
	v_lshlrev_b32_e32 v240, 16, v208
	v_and_b32_e32 v241, 0xffff0000, v208
	v_lshlrev_b32_e32 v242, 16, v209
	v_and_b32_e32 v243, 0xffff0000, v209
	v_lshlrev_b32_e32 v244, 16, v210
	v_and_b32_e32 v245, 0xffff0000, v210
	v_lshlrev_b32_e32 v246, 16, v211
	v_and_b32_e32 v247, 0xffff0000, v211
	v_lshlrev_b32_e32 v248, 16, v212
	v_and_b32_e32 v249, 0xffff0000, v212
	v_lshlrev_b32_e32 v250, 16, v213
	v_and_b32_e32 v251, 0xffff0000, v213
	v_lshlrev_b32_e32 v32, 16, v214
	v_and_b32_e32 v33, 0xffff0000, v214
	v_lshlrev_b32_e32 v34, 16, v215
	v_and_b32_e32 v35, 0xffff0000, v215
	v_lshlrev_b32_e32 v36, 16, v216
	v_and_b32_e32 v37, 0xffff0000, v216
	v_lshlrev_b32_e32 v38, 16, v217
	v_and_b32_e32 v39, 0xffff0000, v217
	v_lshlrev_b32_e32 v20, 16, v218
	v_and_b32_e32 v21, 0xffff0000, v218
	v_lshlrev_b32_e32 v22, 16, v219
	v_and_b32_e32 v23, 0xffff0000, v219
	v_pk_add_f32 v[228:229], v[126:127], v[128:129]
	v_pk_add_f32 v[228:229], v[228:229], v[130:131]
	v_pk_add_f32 v[228:229], v[228:229], v[132:133]
	v_pk_add_f32 v[228:229], v[228:229], v[240:241]
	v_pk_add_f32 v[228:229], v[228:229], v[242:243]
	v_pk_add_f32 v[228:229], v[228:229], v[244:245]
	v_pk_add_f32 v[228:229], v[228:229], v[246:247]
	v_pk_add_f32 v[228:229], v[228:229], v[248:249]
	v_pk_add_f32 v[228:229], v[228:229], v[250:251]
	v_pk_add_f32 v[228:229], v[228:229], v[32:33]
	v_pk_add_f32 v[228:229], v[228:229], v[34:35]
	v_pk_add_f32 v[228:229], v[228:229], v[36:37]
	v_pk_add_f32 v[228:229], v[228:229], v[38:39]
	v_pk_add_f32 v[228:229], v[228:229], v[20:21]
	v_pk_add_f32 v[228:229], v[228:229], v[22:23]
	v_add_f32_e32 v228, v228, v229
	s_nop 1
	v_add_f32_dpp v228, v228, v228 quad_perm:[1,0,3,2] row_mask:0xf bank_mask:0xf bound_ctrl:1
	s_nop 1
	v_add_f32_dpp v228, v228, v228 quad_perm:[2,3,0,1] row_mask:0xf bank_mask:0xf bound_ctrl:1
	s_nop 1
	v_add_f32_dpp v228, v228, v228 row_half_mirror row_mask:0xf bank_mask:0xf bound_ctrl:1
	s_nop 1
	v_add_f32_dpp v228, v228, v228 row_mirror row_mask:0xf bank_mask:0xf bound_ctrl:1
	v_mov_b32_e32 v2, v228
	s_nop 1
	v_permlane16_swap_b32 v228, v2
	s_nop 0
	v_add_f32_e32 v228, v228, v2
	v_mov_b32_e32 v2, v228
	s_nop 1
	v_permlane32_swap_b32 v228, v2
	s_nop 0
	v_add_f32_e32 v228, v228, v2
	v_mul_f32_e32 v134, 0x3a000000, v228
	v_pk_add_f32 v[126:127], v[126:127], v[134:135] op_sel_hi:[1,0] neg_lo:[0,1] neg_hi:[0,1]
	v_pk_add_f32 v[128:129], v[128:129], v[134:135] op_sel_hi:[1,0] neg_lo:[0,1] neg_hi:[0,1]
	v_pk_add_f32 v[130:131], v[130:131], v[134:135] op_sel_hi:[1,0] neg_lo:[0,1] neg_hi:[0,1]
	v_pk_add_f32 v[132:133], v[132:133], v[134:135] op_sel_hi:[1,0] neg_lo:[0,1] neg_hi:[0,1]
	v_pk_add_f32 v[240:241], v[240:241], v[134:135] op_sel_hi:[1,0] neg_lo:[0,1] neg_hi:[0,1]
	v_pk_add_f32 v[242:243], v[242:243], v[134:135] op_sel_hi:[1,0] neg_lo:[0,1] neg_hi:[0,1]
	v_pk_add_f32 v[244:245], v[244:245], v[134:135] op_sel_hi:[1,0] neg_lo:[0,1] neg_hi:[0,1]
	v_pk_add_f32 v[246:247], v[246:247], v[134:135] op_sel_hi:[1,0] neg_lo:[0,1] neg_hi:[0,1]
	v_pk_add_f32 v[248:249], v[248:249], v[134:135] op_sel_hi:[1,0] neg_lo:[0,1] neg_hi:[0,1]
	v_pk_add_f32 v[250:251], v[250:251], v[134:135] op_sel_hi:[1,0] neg_lo:[0,1] neg_hi:[0,1]
	v_pk_add_f32 v[32:33], v[32:33], v[134:135] op_sel_hi:[1,0] neg_lo:[0,1] neg_hi:[0,1]
	v_pk_add_f32 v[34:35], v[34:35], v[134:135] op_sel_hi:[1,0] neg_lo:[0,1] neg_hi:[0,1]
	v_pk_add_f32 v[36:37], v[36:37], v[134:135] op_sel_hi:[1,0] neg_lo:[0,1] neg_hi:[0,1]
	v_pk_add_f32 v[38:39], v[38:39], v[134:135] op_sel_hi:[1,0] neg_lo:[0,1] neg_hi:[0,1]
	v_pk_add_f32 v[20:21], v[20:21], v[134:135] op_sel_hi:[1,0] neg_lo:[0,1] neg_hi:[0,1]
	v_pk_add_f32 v[22:23], v[22:23], v[134:135] op_sel_hi:[1,0] neg_lo:[0,1] neg_hi:[0,1]
	v_pk_mul_f32 v[228:229], v[126:127], v[126:127]
	v_pk_fma_f32 v[228:229], v[128:129], v[128:129], v[228:229]
	v_pk_fma_f32 v[228:229], v[130:131], v[130:131], v[228:229]
	v_pk_fma_f32 v[228:229], v[132:133], v[132:133], v[228:229]
	v_pk_fma_f32 v[228:229], v[240:241], v[240:241], v[228:229]
	v_pk_fma_f32 v[228:229], v[242:243], v[242:243], v[228:229]
	v_pk_fma_f32 v[228:229], v[244:245], v[244:245], v[228:229]
	v_pk_fma_f32 v[228:229], v[246:247], v[246:247], v[228:229]
	v_pk_fma_f32 v[228:229], v[248:249], v[248:249], v[228:229]
	v_pk_fma_f32 v[228:229], v[250:251], v[250:251], v[228:229]
	v_pk_fma_f32 v[228:229], v[32:33], v[32:33], v[228:229]
	v_pk_fma_f32 v[228:229], v[34:35], v[34:35], v[228:229]
	v_pk_fma_f32 v[228:229], v[36:37], v[36:37], v[228:229]
	v_pk_fma_f32 v[228:229], v[38:39], v[38:39], v[228:229]
	v_pk_fma_f32 v[228:229], v[20:21], v[20:21], v[228:229]
	v_pk_fma_f32 v[228:229], v[22:23], v[22:23], v[228:229]
	v_add_f32_e32 v228, v228, v229
	s_nop 1
	v_add_f32_dpp v228, v228, v228 quad_perm:[1,0,3,2] row_mask:0xf bank_mask:0xf bound_ctrl:1
	s_nop 1
	v_add_f32_dpp v228, v228, v228 quad_perm:[2,3,0,1] row_mask:0xf bank_mask:0xf bound_ctrl:1
	s_nop 1
	v_add_f32_dpp v228, v228, v228 row_half_mirror row_mask:0xf bank_mask:0xf bound_ctrl:1
	s_nop 1
	v_add_f32_dpp v228, v228, v228 row_mirror row_mask:0xf bank_mask:0xf bound_ctrl:1
	v_mov_b32_e32 v2, v228
	s_nop 1
	v_permlane16_swap_b32 v228, v2
	s_nop 0
	v_add_f32_e32 v228, v228, v2
	v_mov_b32_e32 v2, v228
	s_nop 1
	v_permlane32_swap_b32 v228, v2
	s_nop 0
	v_add_f32_e32 v228, v228, v2
	v_mul_f32_e32 v0, 0x3a000000, v228
	v_add_f32_e32 v0, 0x3727c5ac, v0
	v_rsq_f32_e32 v0, v0
	s_waitcnt vmcnt(16)
	v_pk_mul_f32 v[228:229], v[140:141], v[0:1] op_sel_hi:[1,0]
	v_pk_fma_f32 v[126:127], v[126:127], v[228:229], v[172:173]
	v_pk_mul_f32 v[228:229], v[142:143], v[0:1] op_sel_hi:[1,0]
	v_pk_fma_f32 v[128:129], v[128:129], v[228:229], v[174:175]
	v_pk_mul_f32 v[228:229], v[144:145], v[0:1] op_sel_hi:[1,0]
	v_pk_fma_f32 v[130:131], v[130:131], v[228:229], v[176:177]
	v_pk_mul_f32 v[228:229], v[146:147], v[0:1] op_sel_hi:[1,0]
	v_pk_fma_f32 v[132:133], v[132:133], v[228:229], v[178:179]
	v_pk_mul_f32 v[228:229], v[148:149], v[0:1] op_sel_hi:[1,0]
	v_pk_fma_f32 v[240:241], v[240:241], v[228:229], v[180:181]
	v_pk_mul_f32 v[228:229], v[150:151], v[0:1] op_sel_hi:[1,0]
	v_pk_fma_f32 v[242:243], v[242:243], v[228:229], v[182:183]
	v_pk_mul_f32 v[228:229], v[152:153], v[0:1] op_sel_hi:[1,0]
	v_pk_fma_f32 v[244:245], v[244:245], v[228:229], v[184:185]
	v_pk_mul_f32 v[228:229], v[154:155], v[0:1] op_sel_hi:[1,0]
	v_pk_fma_f32 v[246:247], v[246:247], v[228:229], v[186:187]
	v_pk_mul_f32 v[228:229], v[156:157], v[0:1] op_sel_hi:[1,0]
	v_pk_fma_f32 v[248:249], v[248:249], v[228:229], v[188:189]
	v_pk_mul_f32 v[228:229], v[158:159], v[0:1] op_sel_hi:[1,0]
	v_pk_fma_f32 v[250:251], v[250:251], v[228:229], v[190:191]
	v_pk_mul_f32 v[228:229], v[160:161], v[0:1] op_sel_hi:[1,0]
	v_pk_fma_f32 v[32:33], v[32:33], v[228:229], v[192:193]
	v_pk_mul_f32 v[228:229], v[162:163], v[0:1] op_sel_hi:[1,0]
	v_pk_fma_f32 v[34:35], v[34:35], v[228:229], v[194:195]
	v_pk_mul_f32 v[228:229], v[164:165], v[0:1] op_sel_hi:[1,0]
	v_pk_fma_f32 v[36:37], v[36:37], v[228:229], v[196:197]
	v_pk_mul_f32 v[228:229], v[166:167], v[0:1] op_sel_hi:[1,0]
	v_pk_fma_f32 v[38:39], v[38:39], v[228:229], v[198:199]
	v_pk_mul_f32 v[228:229], v[168:169], v[0:1] op_sel_hi:[1,0]
	v_pk_fma_f32 v[20:21], v[20:21], v[228:229], v[200:201]
	v_pk_mul_f32 v[228:229], v[170:171], v[0:1] op_sel_hi:[1,0]
	v_pk_fma_f32 v[22:23], v[22:23], v[228:229], v[202:203]
	v_cvt_pk_bf16_f32 v204, v126, v127
	v_cvt_pk_bf16_f32 v205, v128, v129
	v_cvt_pk_bf16_f32 v206, v130, v131
	v_cvt_pk_bf16_f32 v207, v132, v133
	v_cvt_pk_bf16_f32 v208, v240, v241
	v_cvt_pk_bf16_f32 v209, v242, v243
	v_cvt_pk_bf16_f32 v210, v244, v245
	v_cvt_pk_bf16_f32 v211, v246, v247
	v_cvt_pk_bf16_f32 v212, v248, v249
	v_cvt_pk_bf16_f32 v213, v250, v251
	v_cvt_pk_bf16_f32 v214, v32, v33
	v_cvt_pk_bf16_f32 v215, v34, v35
	v_cvt_pk_bf16_f32 v216, v36, v37
	v_cvt_pk_bf16_f32 v217, v38, v39
	v_cvt_pk_bf16_f32 v218, v20, v21
	v_cvt_pk_bf16_f32 v219, v22, v23
	global_store_dwordx2 v1, v[204:205], s[90:91] offset:0
	global_store_dwordx2 v1, v[206:207], s[90:91] offset:512
	global_store_dwordx2 v1, v[208:209], s[90:91] offset:1024
	global_store_dwordx2 v1, v[210:211], s[90:91] offset:1536
	global_store_dwordx2 v1, v[212:213], s[90:91] offset:2048
	global_store_dwordx2 v1, v[214:215], s[90:91] offset:2560
	global_store_dwordx2 v1, v[216:217], s[90:91] offset:3072
	global_store_dwordx2 v1, v[218:219], s[90:91] offset:3584
	s_add_u32 s90, s90, 0x800000
	s_addc_u32 s91, s91, 0
	global_load_dwordx2 v[204:205], v1, s[88:89] offset:0 nt
	global_load_dwordx2 v[206:207], v1, s[88:89] offset:512 nt
	global_load_dwordx2 v[208:209], v1, s[88:89] offset:1024 nt
	global_load_dwordx2 v[210:211], v1, s[88:89] offset:1536 nt
	global_load_dwordx2 v[212:213], v1, s[88:89] offset:2048 nt
	global_load_dwordx2 v[214:215], v1, s[88:89] offset:2560 nt
	global_load_dwordx2 v[216:217], v1, s[88:89] offset:3072 nt
	global_load_dwordx2 v[218:219], v1, s[88:89] offset:3584 nt
	s_add_u32 s88, s88, 0x800000
	s_addc_u32 s89, s89, 0
	s_waitcnt vmcnt(24)
	v_lshlrev_b32_e32 v126, 16, v110
	v_and_b32_e32 v127, 0xffff0000, v110
	v_lshlrev_b32_e32 v128, 16, v111
	v_and_b32_e32 v129, 0xffff0000, v111
	v_lshlrev_b32_e32 v130, 16, v112
	v_and_b32_e32 v131, 0xffff0000, v112
	v_lshlrev_b32_e32 v132, 16, v113
	v_and_b32_e32 v133, 0xffff0000, v113
	v_lshlrev_b32_e32 v240, 16, v114
	v_and_b32_e32 v241, 0xffff0000, v114
	v_lshlrev_b32_e32 v242, 16, v115
	v_and_b32_e32 v243, 0xffff0000, v115
	v_lshlrev_b32_e32 v244, 16, v116
	v_and_b32_e32 v245, 0xffff0000, v116
	v_lshlrev_b32_e32 v246, 16, v117
	v_and_b32_e32 v247, 0xffff0000, v117
	v_lshlrev_b32_e32 v248, 16, v118
	v_and_b32_e32 v249, 0xffff0000, v118
	v_lshlrev_b32_e32 v250, 16, v119
	v_and_b32_e32 v251, 0xffff0000, v119
	v_lshlrev_b32_e32 v32, 16, v120
	v_and_b32_e32 v33, 0xffff0000, v120
	v_lshlrev_b32_e32 v34, 16, v121
	v_and_b32_e32 v35, 0xffff0000, v121
	v_lshlrev_b32_e32 v36, 16, v122
	v_and_b32_e32 v37, 0xffff0000, v122
	v_lshlrev_b32_e32 v38, 16, v123
	v_and_b32_e32 v39, 0xffff0000, v123
	v_lshlrev_b32_e32 v20, 16, v124
	v_and_b32_e32 v21, 0xffff0000, v124
	v_lshlrev_b32_e32 v22, 16, v125
	v_and_b32_e32 v23, 0xffff0000, v125
	v_pk_add_f32 v[228:229], v[126:127], v[128:129]
	v_pk_add_f32 v[228:229], v[228:229], v[130:131]
	v_pk_add_f32 v[228:229], v[228:229], v[132:133]
	v_pk_add_f32 v[228:229], v[228:229], v[240:241]
	v_pk_add_f32 v[228:229], v[228:229], v[242:243]
	v_pk_add_f32 v[228:229], v[228:229], v[244:245]
	v_pk_add_f32 v[228:229], v[228:229], v[246:247]
	v_pk_add_f32 v[228:229], v[228:229], v[248:249]
	v_pk_add_f32 v[228:229], v[228:229], v[250:251]
	v_pk_add_f32 v[228:229], v[228:229], v[32:33]
	v_pk_add_f32 v[228:229], v[228:229], v[34:35]
	v_pk_add_f32 v[228:229], v[228:229], v[36:37]
	v_pk_add_f32 v[228:229], v[228:229], v[38:39]
	v_pk_add_f32 v[228:229], v[228:229], v[20:21]
	v_pk_add_f32 v[228:229], v[228:229], v[22:23]
	v_add_f32_e32 v228, v228, v229
	s_nop 1
	v_add_f32_dpp v228, v228, v228 quad_perm:[1,0,3,2] row_mask:0xf bank_mask:0xf bound_ctrl:1
	s_nop 1
	v_add_f32_dpp v228, v228, v228 quad_perm:[2,3,0,1] row_mask:0xf bank_mask:0xf bound_ctrl:1
	s_nop 1
	v_add_f32_dpp v228, v228, v228 row_half_mirror row_mask:0xf bank_mask:0xf bound_ctrl:1
	s_nop 1
	v_add_f32_dpp v228, v228, v228 row_mirror row_mask:0xf bank_mask:0xf bound_ctrl:1
	v_mov_b32_e32 v2, v228
	s_nop 1
	v_permlane16_swap_b32 v228, v2
	s_nop 0
	v_add_f32_e32 v228, v228, v2
	v_mov_b32_e32 v2, v228
	s_nop 1
	v_permlane32_swap_b32 v228, v2
	s_nop 0
	v_add_f32_e32 v228, v228, v2
	v_mul_f32_e32 v134, 0x3a000000, v228
	v_pk_add_f32 v[126:127], v[126:127], v[134:135] op_sel_hi:[1,0] neg_lo:[0,1] neg_hi:[0,1]
	v_pk_add_f32 v[128:129], v[128:129], v[134:135] op_sel_hi:[1,0] neg_lo:[0,1] neg_hi:[0,1]
	v_pk_add_f32 v[130:131], v[130:131], v[134:135] op_sel_hi:[1,0] neg_lo:[0,1] neg_hi:[0,1]
	v_pk_add_f32 v[132:133], v[132:133], v[134:135] op_sel_hi:[1,0] neg_lo:[0,1] neg_hi:[0,1]
	v_pk_add_f32 v[240:241], v[240:241], v[134:135] op_sel_hi:[1,0] neg_lo:[0,1] neg_hi:[0,1]
	v_pk_add_f32 v[242:243], v[242:243], v[134:135] op_sel_hi:[1,0] neg_lo:[0,1] neg_hi:[0,1]
	v_pk_add_f32 v[244:245], v[244:245], v[134:135] op_sel_hi:[1,0] neg_lo:[0,1] neg_hi:[0,1]
	v_pk_add_f32 v[246:247], v[246:247], v[134:135] op_sel_hi:[1,0] neg_lo:[0,1] neg_hi:[0,1]
	v_pk_add_f32 v[248:249], v[248:249], v[134:135] op_sel_hi:[1,0] neg_lo:[0,1] neg_hi:[0,1]
	v_pk_add_f32 v[250:251], v[250:251], v[134:135] op_sel_hi:[1,0] neg_lo:[0,1] neg_hi:[0,1]
	v_pk_add_f32 v[32:33], v[32:33], v[134:135] op_sel_hi:[1,0] neg_lo:[0,1] neg_hi:[0,1]
	v_pk_add_f32 v[34:35], v[34:35], v[134:135] op_sel_hi:[1,0] neg_lo:[0,1] neg_hi:[0,1]
	v_pk_add_f32 v[36:37], v[36:37], v[134:135] op_sel_hi:[1,0] neg_lo:[0,1] neg_hi:[0,1]
	v_pk_add_f32 v[38:39], v[38:39], v[134:135] op_sel_hi:[1,0] neg_lo:[0,1] neg_hi:[0,1]
	v_pk_add_f32 v[20:21], v[20:21], v[134:135] op_sel_hi:[1,0] neg_lo:[0,1] neg_hi:[0,1]
	v_pk_add_f32 v[22:23], v[22:23], v[134:135] op_sel_hi:[1,0] neg_lo:[0,1] neg_hi:[0,1]
	v_pk_mul_f32 v[228:229], v[126:127], v[126:127]
	v_pk_fma_f32 v[228:229], v[128:129], v[128:129], v[228:229]
	v_pk_fma_f32 v[228:229], v[130:131], v[130:131], v[228:229]
	v_pk_fma_f32 v[228:229], v[132:133], v[132:133], v[228:229]
	v_pk_fma_f32 v[228:229], v[240:241], v[240:241], v[228:229]
	v_pk_fma_f32 v[228:229], v[242:243], v[242:243], v[228:229]
	v_pk_fma_f32 v[228:229], v[244:245], v[244:245], v[228:229]
	v_pk_fma_f32 v[228:229], v[246:247], v[246:247], v[228:229]
	v_pk_fma_f32 v[228:229], v[248:249], v[248:249], v[228:229]
	v_pk_fma_f32 v[228:229], v[250:251], v[250:251], v[228:229]
	v_pk_fma_f32 v[228:229], v[32:33], v[32:33], v[228:229]
	v_pk_fma_f32 v[228:229], v[34:35], v[34:35], v[228:229]
	v_pk_fma_f32 v[228:229], v[36:37], v[36:37], v[228:229]
	v_pk_fma_f32 v[228:229], v[38:39], v[38:39], v[228:229]
	v_pk_fma_f32 v[228:229], v[20:21], v[20:21], v[228:229]
	v_pk_fma_f32 v[228:229], v[22:23], v[22:23], v[228:229]
	v_add_f32_e32 v228, v228, v229
	s_nop 1
	v_add_f32_dpp v228, v228, v228 quad_perm:[1,0,3,2] row_mask:0xf bank_mask:0xf bound_ctrl:1
	s_nop 1
	v_add_f32_dpp v228, v228, v228 quad_perm:[2,3,0,1] row_mask:0xf bank_mask:0xf bound_ctrl:1
	s_nop 1
	v_add_f32_dpp v228, v228, v228 row_half_mirror row_mask:0xf bank_mask:0xf bound_ctrl:1
	s_nop 1
	v_add_f32_dpp v228, v228, v228 row_mirror row_mask:0xf bank_mask:0xf bound_ctrl:1
	v_mov_b32_e32 v2, v228
	s_nop 1
	v_permlane16_swap_b32 v228, v2
	s_nop 0
	v_add_f32_e32 v228, v228, v2
	v_mov_b32_e32 v2, v228
	s_nop 1
	v_permlane32_swap_b32 v228, v2
	s_nop 0
	v_add_f32_e32 v228, v228, v2
	v_mul_f32_e32 v0, 0x3a000000, v228
	v_add_f32_e32 v0, 0x3727c5ac, v0
	v_rsq_f32_e32 v0, v0
	s_nop 0
	v_pk_mul_f32 v[228:229], v[140:141], v[0:1] op_sel_hi:[1,0]
	v_pk_fma_f32 v[126:127], v[126:127], v[228:229], v[172:173]
	v_pk_mul_f32 v[228:229], v[142:143], v[0:1] op_sel_hi:[1,0]
	v_pk_fma_f32 v[128:129], v[128:129], v[228:229], v[174:175]
	v_pk_mul_f32 v[228:229], v[144:145], v[0:1] op_sel_hi:[1,0]
	v_pk_fma_f32 v[130:131], v[130:131], v[228:229], v[176:177]
	v_pk_mul_f32 v[228:229], v[146:147], v[0:1] op_sel_hi:[1,0]
	v_pk_fma_f32 v[132:133], v[132:133], v[228:229], v[178:179]
	v_pk_mul_f32 v[228:229], v[148:149], v[0:1] op_sel_hi:[1,0]
	v_pk_fma_f32 v[240:241], v[240:241], v[228:229], v[180:181]
	v_pk_mul_f32 v[228:229], v[150:151], v[0:1] op_sel_hi:[1,0]
	v_pk_fma_f32 v[242:243], v[242:243], v[228:229], v[182:183]
	v_pk_mul_f32 v[228:229], v[152:153], v[0:1] op_sel_hi:[1,0]
	v_pk_fma_f32 v[244:245], v[244:245], v[228:229], v[184:185]
	v_pk_mul_f32 v[228:229], v[154:155], v[0:1] op_sel_hi:[1,0]
	v_pk_fma_f32 v[246:247], v[246:247], v[228:229], v[186:187]
	v_pk_mul_f32 v[228:229], v[156:157], v[0:1] op_sel_hi:[1,0]
	v_pk_fma_f32 v[248:249], v[248:249], v[228:229], v[188:189]
	v_pk_mul_f32 v[228:229], v[158:159], v[0:1] op_sel_hi:[1,0]
	v_pk_fma_f32 v[250:251], v[250:251], v[228:229], v[190:191]
	v_pk_mul_f32 v[228:229], v[160:161], v[0:1] op_sel_hi:[1,0]
	v_pk_fma_f32 v[32:33], v[32:33], v[228:229], v[192:193]
	v_pk_mul_f32 v[228:229], v[162:163], v[0:1] op_sel_hi:[1,0]
	v_pk_fma_f32 v[34:35], v[34:35], v[228:229], v[194:195]
	v_pk_mul_f32 v[228:229], v[164:165], v[0:1] op_sel_hi:[1,0]
	v_pk_fma_f32 v[36:37], v[36:37], v[228:229], v[196:197]
	v_pk_mul_f32 v[228:229], v[166:167], v[0:1] op_sel_hi:[1,0]
	v_pk_fma_f32 v[38:39], v[38:39], v[228:229], v[198:199]
	v_pk_mul_f32 v[228:229], v[168:169], v[0:1] op_sel_hi:[1,0]
	v_pk_fma_f32 v[20:21], v[20:21], v[228:229], v[200:201]
	v_pk_mul_f32 v[228:229], v[170:171], v[0:1] op_sel_hi:[1,0]
	v_pk_fma_f32 v[22:23], v[22:23], v[228:229], v[202:203]
	v_cvt_pk_bf16_f32 v110, v126, v127
	v_cvt_pk_bf16_f32 v111, v128, v129
	v_cvt_pk_bf16_f32 v112, v130, v131
	v_cvt_pk_bf16_f32 v113, v132, v133
	v_cvt_pk_bf16_f32 v114, v240, v241
	v_cvt_pk_bf16_f32 v115, v242, v243
	v_cvt_pk_bf16_f32 v116, v244, v245
	v_cvt_pk_bf16_f32 v117, v246, v247
	v_cvt_pk_bf16_f32 v118, v248, v249
	v_cvt_pk_bf16_f32 v119, v250, v251
	v_cvt_pk_bf16_f32 v120, v32, v33
	v_cvt_pk_bf16_f32 v121, v34, v35
	v_cvt_pk_bf16_f32 v122, v36, v37
	v_cvt_pk_bf16_f32 v123, v38, v39
	v_cvt_pk_bf16_f32 v124, v20, v21
	v_cvt_pk_bf16_f32 v125, v22, v23
	global_store_dwordx2 v1, v[110:111], s[90:91] offset:0
	global_store_dwordx2 v1, v[112:113], s[90:91] offset:512
	global_store_dwordx2 v1, v[114:115], s[90:91] offset:1024
	global_store_dwordx2 v1, v[116:117], s[90:91] offset:1536
	global_store_dwordx2 v1, v[118:119], s[90:91] offset:2048
	global_store_dwordx2 v1, v[120:121], s[90:91] offset:2560
	global_store_dwordx2 v1, v[122:123], s[90:91] offset:3072
	global_store_dwordx2 v1, v[124:125], s[90:91] offset:3584
	s_add_u32 s90, s90, 0x800000
	s_addc_u32 s91, s91, 0
	s_waitcnt vmcnt(24)
	v_lshlrev_b32_e32 v126, 16, v24
	v_and_b32_e32 v127, 0xffff0000, v24
	v_lshlrev_b32_e32 v128, 16, v25
	v_and_b32_e32 v129, 0xffff0000, v25
	v_lshlrev_b32_e32 v130, 16, v26
	v_and_b32_e32 v131, 0xffff0000, v26
	v_lshlrev_b32_e32 v132, 16, v27
	v_and_b32_e32 v133, 0xffff0000, v27
	v_lshlrev_b32_e32 v240, 16, v8
	v_and_b32_e32 v241, 0xffff0000, v8
	v_lshlrev_b32_e32 v242, 16, v9
	v_and_b32_e32 v243, 0xffff0000, v9
	v_lshlrev_b32_e32 v244, 16, v10
	v_and_b32_e32 v245, 0xffff0000, v10
	v_lshlrev_b32_e32 v246, 16, v11
	v_and_b32_e32 v247, 0xffff0000, v11
	v_lshlrev_b32_e32 v248, 16, v220
	v_and_b32_e32 v249, 0xffff0000, v220
	v_lshlrev_b32_e32 v250, 16, v221
	v_and_b32_e32 v251, 0xffff0000, v221
	v_lshlrev_b32_e32 v32, 16, v222
	v_and_b32_e32 v33, 0xffff0000, v222
	v_lshlrev_b32_e32 v34, 16, v223
	v_and_b32_e32 v35, 0xffff0000, v223
	v_lshlrev_b32_e32 v36, 16, v224
	v_and_b32_e32 v37, 0xffff0000, v224
	v_lshlrev_b32_e32 v38, 16, v225
	v_and_b32_e32 v39, 0xffff0000, v225
	v_lshlrev_b32_e32 v20, 16, v226
	v_and_b32_e32 v21, 0xffff0000, v226
	v_lshlrev_b32_e32 v22, 16, v227
	v_and_b32_e32 v23, 0xffff0000, v227
	v_pk_add_f32 v[228:229], v[126:127], v[128:129]
	v_pk_add_f32 v[228:229], v[228:229], v[130:131]
	v_pk_add_f32 v[228:229], v[228:229], v[132:133]
	v_pk_add_f32 v[228:229], v[228:229], v[240:241]
	v_pk_add_f32 v[228:229], v[228:229], v[242:243]
	v_pk_add_f32 v[228:229], v[228:229], v[244:245]
	v_pk_add_f32 v[228:229], v[228:229], v[246:247]
	v_pk_add_f32 v[228:229], v[228:229], v[248:249]
	v_pk_add_f32 v[228:229], v[228:229], v[250:251]
	v_pk_add_f32 v[228:229], v[228:229], v[32:33]
	v_pk_add_f32 v[228:229], v[228:229], v[34:35]
	v_pk_add_f32 v[228:229], v[228:229], v[36:37]
	v_pk_add_f32 v[228:229], v[228:229], v[38:39]
	v_pk_add_f32 v[228:229], v[228:229], v[20:21]
	v_pk_add_f32 v[228:229], v[228:229], v[22:23]
	v_add_f32_e32 v228, v228, v229
	s_nop 1
	v_add_f32_dpp v228, v228, v228 quad_perm:[1,0,3,2] row_mask:0xf bank_mask:0xf bound_ctrl:1
	s_nop 1
	v_add_f32_dpp v228, v228, v228 quad_perm:[2,3,0,1] row_mask:0xf bank_mask:0xf bound_ctrl:1
	s_nop 1
	v_add_f32_dpp v228, v228, v228 row_half_mirror row_mask:0xf bank_mask:0xf bound_ctrl:1
	s_nop 1
	v_add_f32_dpp v228, v228, v228 row_mirror row_mask:0xf bank_mask:0xf bound_ctrl:1
	v_mov_b32_e32 v2, v228
	s_nop 1
	v_permlane16_swap_b32 v228, v2
	s_nop 0
	v_add_f32_e32 v228, v228, v2
	v_mov_b32_e32 v2, v228
	s_nop 1
	v_permlane32_swap_b32 v228, v2
	s_nop 0
	v_add_f32_e32 v228, v228, v2
	v_mul_f32_e32 v134, 0x3a000000, v228
	v_pk_add_f32 v[126:127], v[126:127], v[134:135] op_sel_hi:[1,0] neg_lo:[0,1] neg_hi:[0,1]
	v_pk_add_f32 v[128:129], v[128:129], v[134:135] op_sel_hi:[1,0] neg_lo:[0,1] neg_hi:[0,1]
	v_pk_add_f32 v[130:131], v[130:131], v[134:135] op_sel_hi:[1,0] neg_lo:[0,1] neg_hi:[0,1]
	v_pk_add_f32 v[132:133], v[132:133], v[134:135] op_sel_hi:[1,0] neg_lo:[0,1] neg_hi:[0,1]
	v_pk_add_f32 v[240:241], v[240:241], v[134:135] op_sel_hi:[1,0] neg_lo:[0,1] neg_hi:[0,1]
	v_pk_add_f32 v[242:243], v[242:243], v[134:135] op_sel_hi:[1,0] neg_lo:[0,1] neg_hi:[0,1]
	v_pk_add_f32 v[244:245], v[244:245], v[134:135] op_sel_hi:[1,0] neg_lo:[0,1] neg_hi:[0,1]
	v_pk_add_f32 v[246:247], v[246:247], v[134:135] op_sel_hi:[1,0] neg_lo:[0,1] neg_hi:[0,1]
	v_pk_add_f32 v[248:249], v[248:249], v[134:135] op_sel_hi:[1,0] neg_lo:[0,1] neg_hi:[0,1]
	v_pk_add_f32 v[250:251], v[250:251], v[134:135] op_sel_hi:[1,0] neg_lo:[0,1] neg_hi:[0,1]
	v_pk_add_f32 v[32:33], v[32:33], v[134:135] op_sel_hi:[1,0] neg_lo:[0,1] neg_hi:[0,1]
	v_pk_add_f32 v[34:35], v[34:35], v[134:135] op_sel_hi:[1,0] neg_lo:[0,1] neg_hi:[0,1]
	v_pk_add_f32 v[36:37], v[36:37], v[134:135] op_sel_hi:[1,0] neg_lo:[0,1] neg_hi:[0,1]
	v_pk_add_f32 v[38:39], v[38:39], v[134:135] op_sel_hi:[1,0] neg_lo:[0,1] neg_hi:[0,1]
	v_pk_add_f32 v[20:21], v[20:21], v[134:135] op_sel_hi:[1,0] neg_lo:[0,1] neg_hi:[0,1]
	v_pk_add_f32 v[22:23], v[22:23], v[134:135] op_sel_hi:[1,0] neg_lo:[0,1] neg_hi:[0,1]
	v_pk_mul_f32 v[228:229], v[126:127], v[126:127]
	v_pk_fma_f32 v[228:229], v[128:129], v[128:129], v[228:229]
	v_pk_fma_f32 v[228:229], v[130:131], v[130:131], v[228:229]
	v_pk_fma_f32 v[228:229], v[132:133], v[132:133], v[228:229]
	v_pk_fma_f32 v[228:229], v[240:241], v[240:241], v[228:229]
	v_pk_fma_f32 v[228:229], v[242:243], v[242:243], v[228:229]
	v_pk_fma_f32 v[228:229], v[244:245], v[244:245], v[228:229]
	v_pk_fma_f32 v[228:229], v[246:247], v[246:247], v[228:229]
	v_pk_fma_f32 v[228:229], v[248:249], v[248:249], v[228:229]
	v_pk_fma_f32 v[228:229], v[250:251], v[250:251], v[228:229]
	v_pk_fma_f32 v[228:229], v[32:33], v[32:33], v[228:229]
	v_pk_fma_f32 v[228:229], v[34:35], v[34:35], v[228:229]
	v_pk_fma_f32 v[228:229], v[36:37], v[36:37], v[228:229]
	v_pk_fma_f32 v[228:229], v[38:39], v[38:39], v[228:229]
	v_pk_fma_f32 v[228:229], v[20:21], v[20:21], v[228:229]
	v_pk_fma_f32 v[228:229], v[22:23], v[22:23], v[228:229]
	v_add_f32_e32 v228, v228, v229
	s_nop 1
	v_add_f32_dpp v228, v228, v228 quad_perm:[1,0,3,2] row_mask:0xf bank_mask:0xf bound_ctrl:1
	s_nop 1
	v_add_f32_dpp v228, v228, v228 quad_perm:[2,3,0,1] row_mask:0xf bank_mask:0xf bound_ctrl:1
	s_nop 1
	v_add_f32_dpp v228, v228, v228 row_half_mirror row_mask:0xf bank_mask:0xf bound_ctrl:1
	s_nop 1
	v_add_f32_dpp v228, v228, v228 row_mirror row_mask:0xf bank_mask:0xf bound_ctrl:1
	v_mov_b32_e32 v2, v228
	s_nop 1
	v_permlane16_swap_b32 v228, v2
	s_nop 0
	v_add_f32_e32 v228, v228, v2
	v_mov_b32_e32 v2, v228
	s_nop 1
	v_permlane32_swap_b32 v228, v2
	s_nop 0
	v_add_f32_e32 v228, v228, v2
	v_mul_f32_e32 v0, 0x3a000000, v228
	v_add_f32_e32 v0, 0x3727c5ac, v0
	v_rsq_f32_e32 v0, v0
	s_nop 0
	v_pk_mul_f32 v[228:229], v[140:141], v[0:1] op_sel_hi:[1,0]
	v_pk_fma_f32 v[126:127], v[126:127], v[228:229], v[172:173]
	v_pk_mul_f32 v[228:229], v[142:143], v[0:1] op_sel_hi:[1,0]
	v_pk_fma_f32 v[128:129], v[128:129], v[228:229], v[174:175]
	v_pk_mul_f32 v[228:229], v[144:145], v[0:1] op_sel_hi:[1,0]
	v_pk_fma_f32 v[130:131], v[130:131], v[228:229], v[176:177]
	v_pk_mul_f32 v[228:229], v[146:147], v[0:1] op_sel_hi:[1,0]
	v_pk_fma_f32 v[132:133], v[132:133], v[228:229], v[178:179]
	v_pk_mul_f32 v[228:229], v[148:149], v[0:1] op_sel_hi:[1,0]
	v_pk_fma_f32 v[240:241], v[240:241], v[228:229], v[180:181]
	v_pk_mul_f32 v[228:229], v[150:151], v[0:1] op_sel_hi:[1,0]
	v_pk_fma_f32 v[242:243], v[242:243], v[228:229], v[182:183]
	v_pk_mul_f32 v[228:229], v[152:153], v[0:1] op_sel_hi:[1,0]
	v_pk_fma_f32 v[244:245], v[244:245], v[228:229], v[184:185]
	v_pk_mul_f32 v[228:229], v[154:155], v[0:1] op_sel_hi:[1,0]
	v_pk_fma_f32 v[246:247], v[246:247], v[228:229], v[186:187]
	v_pk_mul_f32 v[228:229], v[156:157], v[0:1] op_sel_hi:[1,0]
	v_pk_fma_f32 v[248:249], v[248:249], v[228:229], v[188:189]
	v_pk_mul_f32 v[228:229], v[158:159], v[0:1] op_sel_hi:[1,0]
	v_pk_fma_f32 v[250:251], v[250:251], v[228:229], v[190:191]
	v_pk_mul_f32 v[228:229], v[160:161], v[0:1] op_sel_hi:[1,0]
	v_pk_fma_f32 v[32:33], v[32:33], v[228:229], v[192:193]
	v_pk_mul_f32 v[228:229], v[162:163], v[0:1] op_sel_hi:[1,0]
	v_pk_fma_f32 v[34:35], v[34:35], v[228:229], v[194:195]
	v_pk_mul_f32 v[228:229], v[164:165], v[0:1] op_sel_hi:[1,0]
	v_pk_fma_f32 v[36:37], v[36:37], v[228:229], v[196:197]
	v_pk_mul_f32 v[228:229], v[166:167], v[0:1] op_sel_hi:[1,0]
	v_pk_fma_f32 v[38:39], v[38:39], v[228:229], v[198:199]
	v_pk_mul_f32 v[228:229], v[168:169], v[0:1] op_sel_hi:[1,0]
	v_pk_fma_f32 v[20:21], v[20:21], v[228:229], v[200:201]
	v_pk_mul_f32 v[228:229], v[170:171], v[0:1] op_sel_hi:[1,0]
	v_pk_fma_f32 v[22:23], v[22:23], v[228:229], v[202:203]
	v_cvt_pk_bf16_f32 v24, v126, v127
	v_cvt_pk_bf16_f32 v25, v128, v129
	v_cvt_pk_bf16_f32 v26, v130, v131
	v_cvt_pk_bf16_f32 v27, v132, v133
	v_cvt_pk_bf16_f32 v8, v240, v241
	v_cvt_pk_bf16_f32 v9, v242, v243
	v_cvt_pk_bf16_f32 v10, v244, v245
	v_cvt_pk_bf16_f32 v11, v246, v247
	v_cvt_pk_bf16_f32 v220, v248, v249
	v_cvt_pk_bf16_f32 v221, v250, v251
	v_cvt_pk_bf16_f32 v222, v32, v33
	v_cvt_pk_bf16_f32 v223, v34, v35
	v_cvt_pk_bf16_f32 v224, v36, v37
	v_cvt_pk_bf16_f32 v225, v38, v39
	v_cvt_pk_bf16_f32 v226, v20, v21
	v_cvt_pk_bf16_f32 v227, v22, v23
	global_store_dwordx2 v1, v[24:25], s[90:91] offset:0
	global_store_dwordx2 v1, v[26:27], s[90:91] offset:512
	global_store_dwordx2 v1, v[8:9], s[90:91] offset:1024
	global_store_dwordx2 v1, v[10:11], s[90:91] offset:1536
	global_store_dwordx2 v1, v[220:221], s[90:91] offset:2048
	global_store_dwordx2 v1, v[222:223], s[90:91] offset:2560
	global_store_dwordx2 v1, v[224:225], s[90:91] offset:3072
	global_store_dwordx2 v1, v[226:227], s[90:91] offset:3584
	s_add_u32 s90, s90, 0x800000
	s_addc_u32 s91, s91, 0
	s_waitcnt vmcnt(16)
	v_lshlrev_b32_e32 v126, 16, v204
	v_and_b32_e32 v127, 0xffff0000, v204
	v_lshlrev_b32_e32 v128, 16, v205
	v_and_b32_e32 v129, 0xffff0000, v205
	v_lshlrev_b32_e32 v130, 16, v206
	v_and_b32_e32 v131, 0xffff0000, v206
	v_lshlrev_b32_e32 v132, 16, v207
	v_and_b32_e32 v133, 0xffff0000, v207
	v_lshlrev_b32_e32 v240, 16, v208
	v_and_b32_e32 v241, 0xffff0000, v208
	v_lshlrev_b32_e32 v242, 16, v209
	v_and_b32_e32 v243, 0xffff0000, v209
	v_lshlrev_b32_e32 v244, 16, v210
	v_and_b32_e32 v245, 0xffff0000, v210
	v_lshlrev_b32_e32 v246, 16, v211
	v_and_b32_e32 v247, 0xffff0000, v211
	v_lshlrev_b32_e32 v248, 16, v212
	v_and_b32_e32 v249, 0xffff0000, v212
	v_lshlrev_b32_e32 v250, 16, v213
	v_and_b32_e32 v251, 0xffff0000, v213
	v_lshlrev_b32_e32 v32, 16, v214
	v_and_b32_e32 v33, 0xffff0000, v214
	v_lshlrev_b32_e32 v34, 16, v215
	v_and_b32_e32 v35, 0xffff0000, v215
	v_lshlrev_b32_e32 v36, 16, v216
	v_and_b32_e32 v37, 0xffff0000, v216
	v_lshlrev_b32_e32 v38, 16, v217
	v_and_b32_e32 v39, 0xffff0000, v217
	v_lshlrev_b32_e32 v20, 16, v218
	v_and_b32_e32 v21, 0xffff0000, v218
	v_lshlrev_b32_e32 v22, 16, v219
	v_and_b32_e32 v23, 0xffff0000, v219
	v_pk_add_f32 v[228:229], v[126:127], v[128:129]
	v_pk_add_f32 v[228:229], v[228:229], v[130:131]
	v_pk_add_f32 v[228:229], v[228:229], v[132:133]
	v_pk_add_f32 v[228:229], v[228:229], v[240:241]
	v_pk_add_f32 v[228:229], v[228:229], v[242:243]
	v_pk_add_f32 v[228:229], v[228:229], v[244:245]
	v_pk_add_f32 v[228:229], v[228:229], v[246:247]
	v_pk_add_f32 v[228:229], v[228:229], v[248:249]
	v_pk_add_f32 v[228:229], v[228:229], v[250:251]
	v_pk_add_f32 v[228:229], v[228:229], v[32:33]
	v_pk_add_f32 v[228:229], v[228:229], v[34:35]
	v_pk_add_f32 v[228:229], v[228:229], v[36:37]
	v_pk_add_f32 v[228:229], v[228:229], v[38:39]
	v_pk_add_f32 v[228:229], v[228:229], v[20:21]
	v_pk_add_f32 v[228:229], v[228:229], v[22:23]
	v_add_f32_e32 v228, v228, v229
	s_nop 1
	v_add_f32_dpp v228, v228, v228 quad_perm:[1,0,3,2] row_mask:0xf bank_mask:0xf bound_ctrl:1
	s_nop 1
	v_add_f32_dpp v228, v228, v228 quad_perm:[2,3,0,1] row_mask:0xf bank_mask:0xf bound_ctrl:1
	s_nop 1
	v_add_f32_dpp v228, v228, v228 row_half_mirror row_mask:0xf bank_mask:0xf bound_ctrl:1
	s_nop 1
	v_add_f32_dpp v228, v228, v228 row_mirror row_mask:0xf bank_mask:0xf bound_ctrl:1
	v_mov_b32_e32 v2, v228
	s_nop 1
	v_permlane16_swap_b32 v228, v2
	s_nop 0
	v_add_f32_e32 v228, v228, v2
	v_mov_b32_e32 v2, v228
	s_nop 1
	v_permlane32_swap_b32 v228, v2
	s_nop 0
	v_add_f32_e32 v228, v228, v2
	v_mul_f32_e32 v134, 0x3a000000, v228
	v_pk_add_f32 v[126:127], v[126:127], v[134:135] op_sel_hi:[1,0] neg_lo:[0,1] neg_hi:[0,1]
	v_pk_add_f32 v[128:129], v[128:129], v[134:135] op_sel_hi:[1,0] neg_lo:[0,1] neg_hi:[0,1]
	v_pk_add_f32 v[130:131], v[130:131], v[134:135] op_sel_hi:[1,0] neg_lo:[0,1] neg_hi:[0,1]
	v_pk_add_f32 v[132:133], v[132:133], v[134:135] op_sel_hi:[1,0] neg_lo:[0,1] neg_hi:[0,1]
	v_pk_add_f32 v[240:241], v[240:241], v[134:135] op_sel_hi:[1,0] neg_lo:[0,1] neg_hi:[0,1]
	v_pk_add_f32 v[242:243], v[242:243], v[134:135] op_sel_hi:[1,0] neg_lo:[0,1] neg_hi:[0,1]
	v_pk_add_f32 v[244:245], v[244:245], v[134:135] op_sel_hi:[1,0] neg_lo:[0,1] neg_hi:[0,1]
	v_pk_add_f32 v[246:247], v[246:247], v[134:135] op_sel_hi:[1,0] neg_lo:[0,1] neg_hi:[0,1]
	v_pk_add_f32 v[248:249], v[248:249], v[134:135] op_sel_hi:[1,0] neg_lo:[0,1] neg_hi:[0,1]
	v_pk_add_f32 v[250:251], v[250:251], v[134:135] op_sel_hi:[1,0] neg_lo:[0,1] neg_hi:[0,1]
	v_pk_add_f32 v[32:33], v[32:33], v[134:135] op_sel_hi:[1,0] neg_lo:[0,1] neg_hi:[0,1]
	v_pk_add_f32 v[34:35], v[34:35], v[134:135] op_sel_hi:[1,0] neg_lo:[0,1] neg_hi:[0,1]
	v_pk_add_f32 v[36:37], v[36:37], v[134:135] op_sel_hi:[1,0] neg_lo:[0,1] neg_hi:[0,1]
	v_pk_add_f32 v[38:39], v[38:39], v[134:135] op_sel_hi:[1,0] neg_lo:[0,1] neg_hi:[0,1]
	v_pk_add_f32 v[20:21], v[20:21], v[134:135] op_sel_hi:[1,0] neg_lo:[0,1] neg_hi:[0,1]
	v_pk_add_f32 v[22:23], v[22:23], v[134:135] op_sel_hi:[1,0] neg_lo:[0,1] neg_hi:[0,1]
	v_pk_mul_f32 v[228:229], v[126:127], v[126:127]
	v_pk_fma_f32 v[228:229], v[128:129], v[128:129], v[228:229]
	v_pk_fma_f32 v[228:229], v[130:131], v[130:131], v[228:229]
	v_pk_fma_f32 v[228:229], v[132:133], v[132:133], v[228:229]
	v_pk_fma_f32 v[228:229], v[240:241], v[240:241], v[228:229]
	v_pk_fma_f32 v[228:229], v[242:243], v[242:243], v[228:229]
	v_pk_fma_f32 v[228:229], v[244:245], v[244:245], v[228:229]
	v_pk_fma_f32 v[228:229], v[246:247], v[246:247], v[228:229]
	v_pk_fma_f32 v[228:229], v[248:249], v[248:249], v[228:229]
	v_pk_fma_f32 v[228:229], v[250:251], v[250:251], v[228:229]
	v_pk_fma_f32 v[228:229], v[32:33], v[32:33], v[228:229]
	v_pk_fma_f32 v[228:229], v[34:35], v[34:35], v[228:229]
	v_pk_fma_f32 v[228:229], v[36:37], v[36:37], v[228:229]
	v_pk_fma_f32 v[228:229], v[38:39], v[38:39], v[228:229]
	v_pk_fma_f32 v[228:229], v[20:21], v[20:21], v[228:229]
	v_pk_fma_f32 v[228:229], v[22:23], v[22:23], v[228:229]
	v_add_f32_e32 v228, v228, v229
	s_nop 1
	v_add_f32_dpp v228, v228, v228 quad_perm:[1,0,3,2] row_mask:0xf bank_mask:0xf bound_ctrl:1
	s_nop 1
	v_add_f32_dpp v228, v228, v228 quad_perm:[2,3,0,1] row_mask:0xf bank_mask:0xf bound_ctrl:1
	s_nop 1
	v_add_f32_dpp v228, v228, v228 row_half_mirror row_mask:0xf bank_mask:0xf bound_ctrl:1
	s_nop 1
	v_add_f32_dpp v228, v228, v228 row_mirror row_mask:0xf bank_mask:0xf bound_ctrl:1
	v_mov_b32_e32 v2, v228
	s_nop 1
	v_permlane16_swap_b32 v228, v2
	s_nop 0
	v_add_f32_e32 v228, v228, v2
	v_mov_b32_e32 v2, v228
	s_nop 1
	v_permlane32_swap_b32 v228, v2
	s_nop 0
	v_add_f32_e32 v228, v228, v2
	v_mul_f32_e32 v0, 0x3a000000, v228
	v_add_f32_e32 v0, 0x3727c5ac, v0
	v_rsq_f32_e32 v0, v0
	s_nop 0
	v_pk_mul_f32 v[228:229], v[140:141], v[0:1] op_sel_hi:[1,0]
	v_pk_fma_f32 v[126:127], v[126:127], v[228:229], v[172:173]
	v_pk_mul_f32 v[228:229], v[142:143], v[0:1] op_sel_hi:[1,0]
	v_pk_fma_f32 v[128:129], v[128:129], v[228:229], v[174:175]
	v_pk_mul_f32 v[228:229], v[144:145], v[0:1] op_sel_hi:[1,0]
	v_pk_fma_f32 v[130:131], v[130:131], v[228:229], v[176:177]
	v_pk_mul_f32 v[228:229], v[146:147], v[0:1] op_sel_hi:[1,0]
	v_pk_fma_f32 v[132:133], v[132:133], v[228:229], v[178:179]
	v_pk_mul_f32 v[228:229], v[148:149], v[0:1] op_sel_hi:[1,0]
	v_pk_fma_f32 v[240:241], v[240:241], v[228:229], v[180:181]
	v_pk_mul_f32 v[228:229], v[150:151], v[0:1] op_sel_hi:[1,0]
	v_pk_fma_f32 v[242:243], v[242:243], v[228:229], v[182:183]
	v_pk_mul_f32 v[228:229], v[152:153], v[0:1] op_sel_hi:[1,0]
	v_pk_fma_f32 v[244:245], v[244:245], v[228:229], v[184:185]
	v_pk_mul_f32 v[228:229], v[154:155], v[0:1] op_sel_hi:[1,0]
	v_pk_fma_f32 v[246:247], v[246:247], v[228:229], v[186:187]
	v_pk_mul_f32 v[228:229], v[156:157], v[0:1] op_sel_hi:[1,0]
	v_pk_fma_f32 v[248:249], v[248:249], v[228:229], v[188:189]
	v_pk_mul_f32 v[228:229], v[158:159], v[0:1] op_sel_hi:[1,0]
	v_pk_fma_f32 v[250:251], v[250:251], v[228:229], v[190:191]
	v_pk_mul_f32 v[228:229], v[160:161], v[0:1] op_sel_hi:[1,0]
	v_pk_fma_f32 v[32:33], v[32:33], v[228:229], v[192:193]
	v_pk_mul_f32 v[228:229], v[162:163], v[0:1] op_sel_hi:[1,0]
	v_pk_fma_f32 v[34:35], v[34:35], v[228:229], v[194:195]
	v_pk_mul_f32 v[228:229], v[164:165], v[0:1] op_sel_hi:[1,0]
	v_pk_fma_f32 v[36:37], v[36:37], v[228:229], v[196:197]
	v_pk_mul_f32 v[228:229], v[166:167], v[0:1] op_sel_hi:[1,0]
	v_pk_fma_f32 v[38:39], v[38:39], v[228:229], v[198:199]
	v_pk_mul_f32 v[228:229], v[168:169], v[0:1] op_sel_hi:[1,0]
	v_pk_fma_f32 v[20:21], v[20:21], v[228:229], v[200:201]
	v_pk_mul_f32 v[228:229], v[170:171], v[0:1] op_sel_hi:[1,0]
	v_pk_fma_f32 v[22:23], v[22:23], v[228:229], v[202:203]
	v_cvt_pk_bf16_f32 v204, v126, v127
	v_cvt_pk_bf16_f32 v205, v128, v129
	v_cvt_pk_bf16_f32 v206, v130, v131
	v_cvt_pk_bf16_f32 v207, v132, v133
	v_cvt_pk_bf16_f32 v208, v240, v241
	v_cvt_pk_bf16_f32 v209, v242, v243
	v_cvt_pk_bf16_f32 v210, v244, v245
	v_cvt_pk_bf16_f32 v211, v246, v247
	v_cvt_pk_bf16_f32 v212, v248, v249
	v_cvt_pk_bf16_f32 v213, v250, v251
	v_cvt_pk_bf16_f32 v214, v32, v33
	v_cvt_pk_bf16_f32 v215, v34, v35
	v_cvt_pk_bf16_f32 v216, v36, v37
	v_cvt_pk_bf16_f32 v217, v38, v39
	v_cvt_pk_bf16_f32 v218, v20, v21
	v_cvt_pk_bf16_f32 v219, v22, v23
	global_store_dwordx2 v1, v[204:205], s[90:91] offset:0
	global_store_dwordx2 v1, v[206:207], s[90:91] offset:512
	global_store_dwordx2 v1, v[208:209], s[90:91] offset:1024
	global_store_dwordx2 v1, v[210:211], s[90:91] offset:1536
	global_store_dwordx2 v1, v[212:213], s[90:91] offset:2048
	global_store_dwordx2 v1, v[214:215], s[90:91] offset:2560
	global_store_dwordx2 v1, v[216:217], s[90:91] offset:3072
	global_store_dwordx2 v1, v[218:219], s[90:91] offset:3584
	s_add_u32 s90, s90, 0x800000
	s_addc_u32 s91, s91, 0

.LBB0_1304:
	v_add_u32_e32 v12, 1, v8
	v_mad_i64_i32 v[34:35], s[6:7], v12, s77, v[4:5]
	v_add_u32_e32 v14, 2, v8
	v_add_co_u32_e64 v46, s[8:9], s3, v34
	v_mad_i64_i32 v[36:37], s[6:7], v14, s77, v[4:5]
	s_nop 0
	v_addc_co_u32_e64 v47, s[8:9], 0, v35, s[8:9]
	v_mad_i64_i32 v[10:11], s[6:7], v8, s77, v[4:5]
	v_add_u32_e32 v16, 3, v8
	v_add_co_u32_e64 v48, s[8:9], s3, v36
	v_add_co_u32_e32 v32, vcc, 0x1000, v10
	v_mad_i64_i32 v[38:39], s[6:7], v16, s77, v[4:5]
	v_addc_co_u32_e64 v49, s[8:9], 0, v37, s[8:9]
	v_ashrrev_i32_e32 v9, 31, v8
	v_and_b32_e32 v62, 0x1ff, v19
	v_addc_co_u32_e32 v33, vcc, 0, v11, vcc
	v_add_co_u32_e64 v50, s[8:9], s3, v38
	v_lshlrev_b64 v[30:31], 12, v[8:9]
	global_load_dword v9, v[10:11], off nt
	global_load_dword v63, v[32:33], off nt
	v_cmp_ne_u32_e64 s[6:7], 0, v62
	v_addc_co_u32_e64 v51, s[8:9], 0, v39, s[8:9]
	global_load_dword v64, v[46:47], off offset:-4096 nt
	global_load_dword v65, v[46:47], off nt
	global_load_dword v66, v[48:49], off offset:-4096 nt
	global_load_dword v67, v[48:49], off nt
	global_load_dword v68, v[50:51], off offset:-4096 nt
	global_load_dword v69, v[50:51], off nt
	v_ashrrev_i32_e32 v13, 31, v12
	v_ashrrev_i32_e32 v17, 31, v16
	v_subbrev_co_u32_e64 v41, s[6:7], 0, v8, s[6:7]
	v_add_co_u32_e32 v40, vcc, 0x2000, v10
	v_ashrrev_i32_e32 v15, 31, v14
	v_lshlrev_b64 v[12:13], 12, v[12:13]
	v_lshlrev_b64 v[16:17], 12, v[16:17]
	v_mad_i64_i32 v[52:53], s[8:9], v41, s77, v[4:5]
	v_addc_co_u32_e32 v41, vcc, 0, v11, vcc
	v_lshl_add_u64 v[42:43], v[0:1], 0, v[30:31]
	v_lshl_add_u64 v[44:45], v[6:7], 0, v[30:31]
	v_lshlrev_b64 v[14:15], 12, v[14:15]
	v_lshl_add_u64 v[32:33], v[0:1], 0, v[12:13]
	v_lshl_add_u64 v[54:55], v[6:7], 0, v[12:13]
	v_lshl_add_u64 v[48:49], v[6:7], 0, v[16:17]
	v_add_co_u32_e32 v50, vcc, s3, v52
	v_lshl_add_u64 v[56:57], v[0:1], 0, v[14:15]
	v_lshl_add_u64 v[58:59], v[6:7], 0, v[14:15]
	v_lshl_add_u64 v[46:47], v[0:1], 0, v[16:17]
	v_addc_co_u32_e32 v51, vcc, 0, v53, vcc
	v_lshl_add_u64 v[60:61], v[2:3], 0, v[12:13]
	v_lshl_add_u64 v[12:13], v[2:3], 0, v[14:15]
	v_lshl_add_u64 v[10:11], v[2:3], 0, v[16:17]
	global_load_ushort v14, v[44:45], off nt
	global_load_ushort v15, v[44:45], off offset:2048 nt
	global_load_ushort v16, v[54:55], off nt
	global_load_ushort v17, v[54:55], off offset:2048 nt
	s_nop 0
	global_load_ushort v44, v[58:59], off nt
	global_load_ushort v45, v[58:59], off offset:2048 nt
	global_load_ushort v54, v[48:49], off nt
	s_nop 0
	global_load_ushort v48, v[48:49], off offset:2048 nt
	s_nop 0
	global_load_dword v49, v[52:53], off nt
	s_nop 0
	global_load_dword v52, v[50:51], off offset:-4096 nt
	s_nop 0
	global_load_dword v50, v[50:51], off nt
	s_nop 0
	global_load_dword v42, v[42:43], off nt
	s_nop 0
	global_load_dword v34, v[34:35], off nt
	s_nop 0
	global_load_dword v35, v[40:41], off nt
	s_nop 0
	global_load_dword v32, v[32:33], off nt
	s_nop 0
	global_load_dword v33, v[36:37], off nt
	s_nop 0
	global_load_dword v36, v[56:57], off nt
	global_load_dword v37, v[38:39], off nt
	s_nop 0
	global_load_dword v38, v[46:47], off nt
	v_cmp_eq_u32_e32 vcc, 0, v62
	v_add_u32_e32 v19, s75, v19
	v_cmp_lt_i32_e64 s[6:7], s79, v19
	s_or_b64 s[68:69], s[6:7], s[68:69]
	v_lshl_add_u64 v[30:31], v[2:3], 0, v[30:31]
	v_add_u32_e32 v8, s76, v8
	s_nop 1
	s_mov_b64 s[90:91], vcc
	s_mov_b32 s88, 0
.Lgn_loop:
	s_waitcnt vmcnt(0)
	s_mov_b64 s[92:93], s[90:91]
	v_mov_b32_e32 v71, v9
	v_mov_b32_e32 v72, v10
	v_mov_b32_e32 v73, v11
	v_mov_b32_e32 v74, v12
	v_mov_b32_e32 v75, v13
	v_mov_b32_e32 v76, v14
	v_mov_b32_e32 v77, v15
	v_mov_b32_e32 v78, v16
	v_mov_b32_e32 v79, v17
	v_mov_b32_e32 v92, v30
	v_mov_b32_e32 v93, v31
	v_mov_b32_e32 v94, v32
	v_mov_b32_e32 v95, v33
	v_mov_b32_e32 v96, v34
	v_mov_b32_e32 v97, v35
	v_mov_b32_e32 v98, v36
	v_mov_b32_e32 v99, v37
	v_mov_b32_e32 v100, v38
	v_mov_b32_e32 v104, v42
	v_mov_b32_e32 v106, v44
	v_mov_b32_e32 v107, v45
	v_mov_b32_e32 v110, v48
	v_mov_b32_e32 v111, v49
	v_mov_b32_e32 v112, v50
	v_mov_b32_e32 v114, v52
	v_mov_b32_e32 v116, v54
	v_mov_b32_e32 v122, v60
	v_mov_b32_e32 v123, v61
	v_mov_b32_e32 v125, v63
	v_mov_b32_e32 v126, v64
	v_mov_b32_e32 v127, v65
	v_mov_b32_e32 v128, v66
	v_mov_b32_e32 v129, v67
	v_mov_b32_e32 v130, v68
	v_mov_b32_e32 v131, v69
	v_add_u32_e32 v12, 1, v8
	v_mad_i64_i32 v[34:35], s[6:7], v12, s77, v[4:5]
	v_add_u32_e32 v14, 2, v8
	v_add_co_u32_e64 v46, s[8:9], s3, v34
	v_mad_i64_i32 v[36:37], s[6:7], v14, s77, v[4:5]
	s_nop 0
	v_addc_co_u32_e64 v47, s[8:9], 0, v35, s[8:9]
	v_mad_i64_i32 v[10:11], s[6:7], v8, s77, v[4:5]
	v_add_u32_e32 v16, 3, v8
	v_add_co_u32_e64 v48, s[8:9], s3, v36
	v_add_co_u32_e32 v32, vcc, 0x1000, v10
	v_mad_i64_i32 v[38:39], s[6:7], v16, s77, v[4:5]
	v_addc_co_u32_e64 v49, s[8:9], 0, v37, s[8:9]
	v_ashrrev_i32_e32 v9, 31, v8
	v_and_b32_e32 v62, 0x1ff, v19
	v_addc_co_u32_e32 v33, vcc, 0, v11, vcc
	v_add_co_u32_e64 v50, s[8:9], s3, v38
	v_lshlrev_b64 v[30:31], 12, v[8:9]
	global_load_dword v9, v[10:11], off nt
	global_load_dword v63, v[32:33], off nt
	v_cmp_ne_u32_e64 s[6:7], 0, v62
	v_addc_co_u32_e64 v51, s[8:9], 0, v39, s[8:9]
	global_load_dword v64, v[46:47], off offset:-4096 nt
	global_load_dword v65, v[46:47], off nt
	global_load_dword v66, v[48:49], off offset:-4096 nt
	global_load_dword v67, v[48:49], off nt
	global_load_dword v68, v[50:51], off offset:-4096 nt
	global_load_dword v69, v[50:51], off nt
	v_ashrrev_i32_e32 v13, 31, v12
	v_ashrrev_i32_e32 v17, 31, v16
	v_subbrev_co_u32_e64 v41, s[6:7], 0, v8, s[6:7]
	v_add_co_u32_e32 v40, vcc, 0x2000, v10
	v_ashrrev_i32_e32 v15, 31, v14
	v_lshlrev_b64 v[12:13], 12, v[12:13]
	v_lshlrev_b64 v[16:17], 12, v[16:17]
	v_mad_i64_i32 v[52:53], s[8:9], v41, s77, v[4:5]
	v_addc_co_u32_e32 v41, vcc, 0, v11, vcc
	v_lshl_add_u64 v[42:43], v[0:1], 0, v[30:31]
	v_lshl_add_u64 v[44:45], v[6:7], 0, v[30:31]
	v_lshlrev_b64 v[14:15], 12, v[14:15]
	v_lshl_add_u64 v[32:33], v[0:1], 0, v[12:13]
	v_lshl_add_u64 v[54:55], v[6:7], 0, v[12:13]
	v_lshl_add_u64 v[48:49], v[6:7], 0, v[16:17]
	v_add_co_u32_e32 v50, vcc, s3, v52
	v_lshl_add_u64 v[56:57], v[0:1], 0, v[14:15]
	v_lshl_add_u64 v[58:59], v[6:7], 0, v[14:15]
	v_lshl_add_u64 v[46:47], v[0:1], 0, v[16:17]
	v_addc_co_u32_e32 v51, vcc, 0, v53, vcc
	v_lshl_add_u64 v[60:61], v[2:3], 0, v[12:13]
	v_lshl_add_u64 v[12:13], v[2:3], 0, v[14:15]
	v_lshl_add_u64 v[10:11], v[2:3], 0, v[16:17]
	global_load_ushort v14, v[44:45], off nt
	global_load_ushort v15, v[44:45], off offset:2048 nt
	global_load_ushort v16, v[54:55], off nt
	global_load_ushort v17, v[54:55], off offset:2048 nt
	s_nop 0
	global_load_ushort v44, v[58:59], off nt
	global_load_ushort v45, v[58:59], off offset:2048 nt
	global_load_ushort v54, v[48:49], off nt
	s_nop 0
	global_load_ushort v48, v[48:49], off offset:2048 nt
	s_nop 0
	global_load_dword v49, v[52:53], off nt
	s_nop 0
	global_load_dword v52, v[50:51], off offset:-4096 nt
	s_nop 0
	global_load_dword v50, v[50:51], off nt
	s_nop 0
	global_load_dword v42, v[42:43], off nt
	s_nop 0
	global_load_dword v34, v[34:35], off nt
	s_nop 0
	global_load_dword v35, v[40:41], off nt
	s_nop 0
	global_load_dword v32, v[32:33], off nt
	s_nop 0
	global_load_dword v33, v[36:37], off nt
	s_nop 0
	global_load_dword v36, v[56:57], off nt
	global_load_dword v37, v[38:39], off nt
	s_nop 0
	global_load_dword v38, v[46:47], off nt
	v_cmp_eq_u32_e32 vcc, 0, v62
	v_add_u32_e32 v19, s75, v19
	v_cmp_lt_i32_e64 s[6:7], s79, v19
	s_or_b64 s[68:69], s[6:7], s[68:69]
	v_lshl_add_u64 v[30:31], v[2:3], 0, v[30:31]
	v_add_u32_e32 v8, s76, v8
	s_nop 1
	s_mov_b64 s[90:91], vcc
	v_cndmask_b32_e64 v111, v111, 0, s[92:93]
	v_cndmask_b32_e64 v114, v114, 0, s[92:93]
	v_cndmask_b32_e64 v112, v112, 0, s[92:93]
	v_sub_f32_e32 v168, v111, v71
	v_fma_f32 v140, v25, v168, v71
	v_sub_f32_e32 v169, v114, v125
	v_fma_f32 v144, v26, v169, v125
	v_sub_f32_e32 v170, v112, v97
	v_fma_f32 v148, v27, v170, v97
	v_lshlrev_b32_e32 v76, 16, v76
	v_lshlrev_b32_e32 v77, 16, v77
	v_add_f32_e32 v171, -1.0, v76
	v_fma_f32 v171, v20, v171, 1.0
	v_mul_f32_e32 v171, v144, v171
	v_mul_f32_e32 v156, v140, v171
	v_mul_f32_e32 v156, v21, v156
	v_mov_b32_e32 v152, v104
	v_sub_f32_e32 v168, v71, v96
	v_fma_f32 v141, v25, v168, v96
	v_sub_f32_e32 v169, v125, v126
	v_fma_f32 v145, v26, v169, v126
	v_sub_f32_e32 v170, v97, v127
	v_fma_f32 v149, v27, v170, v127
	v_lshlrev_b32_e32 v78, 16, v78
	v_lshlrev_b32_e32 v79, 16, v79
	v_add_f32_e32 v171, -1.0, v78
	v_fma_f32 v171, v20, v171, 1.0
	v_mul_f32_e32 v171, v145, v171
	v_mul_f32_e32 v157, v141, v171
	v_mul_f32_e32 v157, v21, v157
	v_mov_b32_e32 v153, v94
	v_sub_f32_e32 v168, v96, v95
	v_fma_f32 v142, v25, v168, v95
	v_sub_f32_e32 v169, v126, v128
	v_fma_f32 v146, v26, v169, v128
	v_sub_f32_e32 v170, v127, v129
	v_fma_f32 v150, v27, v170, v129
	v_lshlrev_b32_e32 v106, 16, v106
	v_lshlrev_b32_e32 v107, 16, v107
	v_add_f32_e32 v171, -1.0, v106
	v_fma_f32 v171, v20, v171, 1.0
	v_mul_f32_e32 v171, v146, v171
	v_mul_f32_e32 v158, v142, v171
	v_mul_f32_e32 v158, v21, v158
	v_mov_b32_e32 v154, v98
	v_sub_f32_e32 v168, v95, v99
	v_fma_f32 v143, v25, v168, v99
	v_sub_f32_e32 v169, v128, v130
	v_fma_f32 v147, v26, v169, v130
	v_sub_f32_e32 v170, v129, v131
	v_fma_f32 v151, v27, v170, v131
	v_lshlrev_b32_e32 v116, 16, v116
	v_lshlrev_b32_e32 v110, 16, v110
	v_add_f32_e32 v171, -1.0, v116
	v_fma_f32 v171, v20, v171, 1.0
	v_mul_f32_e32 v171, v147, v171
	v_mul_f32_e32 v159, v143, v171
	v_mul_f32_e32 v159, v21, v159
	v_mov_b32_e32 v155, v100
	v_add_f32_dpp v152, v152, v152 quad_perm:[1,0,3,2] row_mask:0xf bank_mask:0xf bound_ctrl:1
	v_add_f32_dpp v153, v153, v153 quad_perm:[1,0,3,2] row_mask:0xf bank_mask:0xf bound_ctrl:1
	v_add_f32_dpp v154, v154, v154 quad_perm:[1,0,3,2] row_mask:0xf bank_mask:0xf bound_ctrl:1
	v_add_f32_dpp v155, v155, v155 quad_perm:[1,0,3,2] row_mask:0xf bank_mask:0xf bound_ctrl:1
	v_add_f32_dpp v156, v156, v156 quad_perm:[1,0,3,2] row_mask:0xf bank_mask:0xf bound_ctrl:1
	v_add_f32_dpp v157, v157, v157 quad_perm:[1,0,3,2] row_mask:0xf bank_mask:0xf bound_ctrl:1
	v_add_f32_dpp v158, v158, v158 quad_perm:[1,0,3,2] row_mask:0xf bank_mask:0xf bound_ctrl:1
	v_add_f32_dpp v159, v159, v159 quad_perm:[1,0,3,2] row_mask:0xf bank_mask:0xf bound_ctrl:1
	v_add_f32_dpp v152, v152, v152 quad_perm:[2,3,0,1] row_mask:0xf bank_mask:0xf bound_ctrl:1
	v_add_f32_dpp v153, v153, v153 quad_perm:[2,3,0,1] row_mask:0xf bank_mask:0xf bound_ctrl:1
	v_add_f32_dpp v154, v154, v154 quad_perm:[2,3,0,1] row_mask:0xf bank_mask:0xf bound_ctrl:1
	v_add_f32_dpp v155, v155, v155 quad_perm:[2,3,0,1] row_mask:0xf bank_mask:0xf bound_ctrl:1
	v_add_f32_dpp v156, v156, v156 quad_perm:[2,3,0,1] row_mask:0xf bank_mask:0xf bound_ctrl:1
	v_add_f32_dpp v157, v157, v157 quad_perm:[2,3,0,1] row_mask:0xf bank_mask:0xf bound_ctrl:1
	v_add_f32_dpp v158, v158, v158 quad_perm:[2,3,0,1] row_mask:0xf bank_mask:0xf bound_ctrl:1
	v_add_f32_dpp v159, v159, v159 quad_perm:[2,3,0,1] row_mask:0xf bank_mask:0xf bound_ctrl:1
	v_add_f32_dpp v152, v152, v152 row_half_mirror row_mask:0xf bank_mask:0xf bound_ctrl:1
	v_add_f32_dpp v153, v153, v153 row_half_mirror row_mask:0xf bank_mask:0xf bound_ctrl:1
	v_add_f32_dpp v154, v154, v154 row_half_mirror row_mask:0xf bank_mask:0xf bound_ctrl:1
	v_add_f32_dpp v155, v155, v155 row_half_mirror row_mask:0xf bank_mask:0xf bound_ctrl:1
	v_add_f32_dpp v156, v156, v156 row_half_mirror row_mask:0xf bank_mask:0xf bound_ctrl:1
	v_add_f32_dpp v157, v157, v157 row_half_mirror row_mask:0xf bank_mask:0xf bound_ctrl:1
	v_add_f32_dpp v158, v158, v158 row_half_mirror row_mask:0xf bank_mask:0xf bound_ctrl:1
	v_add_f32_dpp v159, v159, v159 row_half_mirror row_mask:0xf bank_mask:0xf bound_ctrl:1
	v_add_f32_dpp v152, v152, v152 row_mirror row_mask:0xf bank_mask:0xf bound_ctrl:1
	v_add_f32_dpp v153, v153, v153 row_mirror row_mask:0xf bank_mask:0xf bound_ctrl:1
	v_add_f32_dpp v154, v154, v154 row_mirror row_mask:0xf bank_mask:0xf bound_ctrl:1
	v_add_f32_dpp v155, v155, v155 row_mirror row_mask:0xf bank_mask:0xf bound_ctrl:1
	v_add_f32_dpp v156, v156, v156 row_mirror row_mask:0xf bank_mask:0xf bound_ctrl:1
	v_add_f32_dpp v157, v157, v157 row_mirror row_mask:0xf bank_mask:0xf bound_ctrl:1
	v_add_f32_dpp v158, v158, v158 row_mirror row_mask:0xf bank_mask:0xf bound_ctrl:1
	v_add_f32_dpp v159, v159, v159 row_mirror row_mask:0xf bank_mask:0xf bound_ctrl:1
	v_mov_b32_e32 v168, v152
	v_mov_b32_e32 v169, v153
	v_mov_b32_e32 v170, v154
	v_mov_b32_e32 v171, v155
	v_mov_b32_e32 v172, v156
	v_mov_b32_e32 v173, v157
	v_mov_b32_e32 v174, v158
	v_mov_b32_e32 v175, v159
	v_permlane16_swap_b32 v152, v168
	v_permlane16_swap_b32 v153, v169
	v_permlane16_swap_b32 v154, v170
	v_permlane16_swap_b32 v155, v171
	v_permlane16_swap_b32 v156, v172
	v_permlane16_swap_b32 v157, v173
	v_permlane16_swap_b32 v158, v174
	v_permlane16_swap_b32 v159, v175
	v_add_f32_e32 v152, v152, v168
	v_add_f32_e32 v153, v153, v169
	v_add_f32_e32 v154, v154, v170
	v_add_f32_e32 v155, v155, v171
	v_add_f32_e32 v156, v156, v172
	v_add_f32_e32 v157, v157, v173
	v_add_f32_e32 v158, v158, v174
	v_add_f32_e32 v159, v159, v175
	v_mov_b32_e32 v168, v152
	v_mov_b32_e32 v169, v153
	v_mov_b32_e32 v170, v154
	v_mov_b32_e32 v171, v155
	v_mov_b32_e32 v172, v156
	v_mov_b32_e32 v173, v157
	v_mov_b32_e32 v174, v158
	v_mov_b32_e32 v175, v159
	v_permlane32_swap_b32 v152, v168
	v_permlane32_swap_b32 v153, v169
	v_permlane32_swap_b32 v154, v170
	v_permlane32_swap_b32 v155, v171
	v_permlane32_swap_b32 v156, v172
	v_permlane32_swap_b32 v157, v173
	v_permlane32_swap_b32 v158, v174
	v_permlane32_swap_b32 v159, v175
	v_add_f32_e32 v152, v152, v168
	v_add_f32_e32 v153, v153, v169
	v_add_f32_e32 v154, v154, v170
	v_add_f32_e32 v155, v155, v171
	v_add_f32_e32 v156, v156, v172
	v_add_f32_e32 v157, v157, v173
	v_add_f32_e32 v158, v158, v174
	v_add_f32_e32 v159, v159, v175
	v_fmamk_f32 v160, v152, 0xbc800000, v104
	v_fmamk_f32 v161, v153, 0xbc800000, v94
	v_fmamk_f32 v162, v154, 0xbc800000, v98
	v_fmamk_f32 v163, v155, 0xbc800000, v100
	v_mul_f32_e32 v164, v160, v160
	v_mul_f32_e32 v165, v161, v161
	v_mul_f32_e32 v166, v162, v162
	v_mul_f32_e32 v167, v163, v163
	v_add_f32_dpp v164, v164, v164 quad_perm:[1,0,3,2] row_mask:0xf bank_mask:0xf bound_ctrl:1
	v_add_f32_dpp v165, v165, v165 quad_perm:[1,0,3,2] row_mask:0xf bank_mask:0xf bound_ctrl:1
	v_add_f32_dpp v166, v166, v166 quad_perm:[1,0,3,2] row_mask:0xf bank_mask:0xf bound_ctrl:1
	v_add_f32_dpp v167, v167, v167 quad_perm:[1,0,3,2] row_mask:0xf bank_mask:0xf bound_ctrl:1
	v_add_f32_dpp v164, v164, v164 quad_perm:[2,3,0,1] row_mask:0xf bank_mask:0xf bound_ctrl:1
	v_add_f32_dpp v165, v165, v165 quad_perm:[2,3,0,1] row_mask:0xf bank_mask:0xf bound_ctrl:1
	v_add_f32_dpp v166, v166, v166 quad_perm:[2,3,0,1] row_mask:0xf bank_mask:0xf bound_ctrl:1
	v_add_f32_dpp v167, v167, v167 quad_perm:[2,3,0,1] row_mask:0xf bank_mask:0xf bound_ctrl:1
	v_add_f32_dpp v164, v164, v164 row_half_mirror row_mask:0xf bank_mask:0xf bound_ctrl:1
	v_add_f32_dpp v165, v165, v165 row_half_mirror row_mask:0xf bank_mask:0xf bound_ctrl:1
	v_add_f32_dpp v166, v166, v166 row_half_mirror row_mask:0xf bank_mask:0xf bound_ctrl:1
	v_add_f32_dpp v167, v167, v167 row_half_mirror row_mask:0xf bank_mask:0xf bound_ctrl:1
	v_add_f32_dpp v164, v164, v164 row_mirror row_mask:0xf bank_mask:0xf bound_ctrl:1
	v_add_f32_dpp v165, v165, v165 row_mirror row_mask:0xf bank_mask:0xf bound_ctrl:1
	v_add_f32_dpp v166, v166, v166 row_mirror row_mask:0xf bank_mask:0xf bound_ctrl:1
	v_add_f32_dpp v167, v167, v167 row_mirror row_mask:0xf bank_mask:0xf bound_ctrl:1
	v_mov_b32_e32 v168, v164
	v_mov_b32_e32 v169, v165
	v_mov_b32_e32 v170, v166
	v_mov_b32_e32 v171, v167
	v_permlane16_swap_b32 v164, v168
	v_permlane16_swap_b32 v165, v169
	v_permlane16_swap_b32 v166, v170
	v_permlane16_swap_b32 v167, v171
	v_add_f32_e32 v164, v164, v168
	v_add_f32_e32 v165, v165, v169
	v_add_f32_e32 v166, v166, v170
	v_add_f32_e32 v167, v167, v171
	v_mov_b32_e32 v168, v164
	v_mov_b32_e32 v169, v165
	v_mov_b32_e32 v170, v166
	v_mov_b32_e32 v171, v167
	v_permlane32_swap_b32 v164, v168
	v_permlane32_swap_b32 v165, v169
	v_permlane32_swap_b32 v166, v170
	v_permlane32_swap_b32 v167, v171
	v_add_f32_e32 v164, v164, v168
	v_add_f32_e32 v165, v165, v169
	v_add_f32_e32 v166, v166, v170
	v_add_f32_e32 v167, v167, v171
	v_mul_f32_e32 v164, 0x3c800000, v164
	v_mul_f32_e32 v165, 0x3c800000, v165
	v_mul_f32_e32 v166, 0x3c800000, v166
	v_mul_f32_e32 v167, 0x3c800000, v167
	v_add_f32_e32 v164, 0x3a27c5ac, v164
	v_add_f32_e32 v165, 0x3a27c5ac, v165
	v_add_f32_e32 v166, 0x3a27c5ac, v166
	v_add_f32_e32 v167, 0x3a27c5ac, v167
	v_rsq_f32_e32 v164, v164
	v_rsq_f32_e32 v165, v165
	v_rsq_f32_e32 v166, v166
	v_rsq_f32_e32 v167, v167
	v_mul_f32_e32 v160, v160, v164
	v_mul_f32_e32 v161, v161, v165
	v_mul_f32_e32 v162, v162, v166
	v_mul_f32_e32 v163, v163, v167
	v_fma_f32 v160, v160, v22, v23
	v_fma_f32 v161, v161, v22, v23
	v_fma_f32 v162, v162, v22, v23
	v_fma_f32 v163, v163, v22, v23
	v_fma_f32 v160, v156, v148, v160
	v_fma_f32 v161, v157, v149, v161
	v_fma_f32 v162, v158, v150, v162
	v_fma_f32 v163, v159, v151, v163
	v_mul_f32_e32 v160, v160, v77
	v_mul_f32_e32 v161, v161, v79
	v_mul_f32_e32 v162, v162, v107
	v_mul_f32_e32 v163, v163, v110
	v_mul_f32_e32 v160, v24, v160
	v_mul_f32_e32 v161, v24, v161
	v_mul_f32_e32 v162, v24, v162
	v_mul_f32_e32 v163, v24, v163
	v_cvt_pk_bf16_f32 v160, v160, v160
	v_cvt_pk_bf16_f32 v161, v161, v161
	v_cvt_pk_bf16_f32 v162, v162, v162
	v_cvt_pk_bf16_f32 v163, v163, v163
	global_store_short v[92:93], v160, off
	global_store_short v[122:123], v161, off
	global_store_short v[74:75], v162, off
	global_store_short v[72:73], v163, off
	s_add_u32 s88, s88, 1
	s_cmp_lt_u32 s88, 16
	s_cbranch_scc1 .Lgn_loop
	s_waitcnt vmcnt(0)

.LBB0_1726:
	s_cmp_lt_i32 s30, 11
	s_cselect_b64 s[8:9], -1, 0
	s_and_b64 s[10:11], s[8:9], s[6:7]
	s_andn2_b64 vcc, exec, s[10:11]
	s_cbranch_vccnz .LBB0_1738
	s_load_dwordx4 s[12:15], s[0:1], 0x100
	v_lshl_add_u32 v32, s2, 3, v230
	s_movk_i32 s3, 0x2000
	v_cmp_gt_i32_e32 vcc, s3, v32
	s_and_saveexec_b64 s[16:17], vcc
	s_cbranch_execz .LBB0_1732
	s_load_dwordx4 s[60:63], s[0:1], 0x100
	v_lshl_add_u32 v2, s2, 3, v230
	v_lshlrev_b32_e32 v137, 4, v136
	v_lshlrev_b32_e32 v1, 3, v136
	v_lshl_add_u32 v1, v2, 12, v1
	v_add_u32_e32 v4, 0x1000, v137
	s_add_u32 s88, s28, 0xe600000
	s_addc_u32 s89, s29, 0
	s_add_u32 s90, s28, 0xc500000
	s_addc_u32 s91, s29, 0
	global_load_dwordx2 v[204:205], v1, s[88:89] offset:0 nt
	global_load_dwordx2 v[206:207], v1, s[88:89] offset:512 nt
	global_load_dwordx2 v[208:209], v1, s[88:89] offset:1024 nt
	global_load_dwordx2 v[210:211], v1, s[88:89] offset:1536 nt
	global_load_dwordx2 v[212:213], v1, s[88:89] offset:2048 nt
	global_load_dwordx2 v[214:215], v1, s[88:89] offset:2560 nt
	global_load_dwordx2 v[216:217], v1, s[88:89] offset:3072 nt
	global_load_dwordx2 v[218:219], v1, s[88:89] offset:3584 nt
	s_add_u32 s88, s88, 0x800000
	s_addc_u32 s89, s89, 0
	s_waitcnt lgkmcnt(0)
	global_load_dwordx4 v[140:143], v137, s[60:61] offset:0
	global_load_dwordx4 v[144:147], v137, s[60:61] offset:1024
	global_load_dwordx4 v[148:151], v137, s[60:61] offset:2048
	global_load_dwordx4 v[152:155], v137, s[60:61] offset:3072
	global_load_dwordx4 v[156:159], v4, s[60:61] offset:0
	global_load_dwordx4 v[160:163], v4, s[60:61] offset:1024
	global_load_dwordx4 v[164:167], v4, s[60:61] offset:2048
	global_load_dwordx4 v[168:171], v4, s[60:61] offset:3072
	global_load_dwordx4 v[172:175], v137, s[62:63] offset:0
	global_load_dwordx4 v[176:179], v137, s[62:63] offset:1024
	global_load_dwordx4 v[180:183], v137, s[62:63] offset:2048
	global_load_dwordx4 v[184:187], v137, s[62:63] offset:3072
	global_load_dwordx4 v[188:191], v4, s[62:63] offset:0
	global_load_dwordx4 v[192:195], v4, s[62:63] offset:1024
	global_load_dwordx4 v[196:199], v4, s[62:63] offset:2048
	global_load_dwordx4 v[200:203], v4, s[62:63] offset:3072
	global_load_dwordx2 v[110:111], v1, s[88:89] offset:0 nt
	global_load_dwordx2 v[112:113], v1, s[88:89] offset:512 nt
	global_load_dwordx2 v[114:115], v1, s[88:89] offset:1024 nt
	global_load_dwordx2 v[116:117], v1, s[88:89] offset:1536 nt
	global_load_dwordx2 v[118:119], v1, s[88:89] offset:2048 nt
	global_load_dwordx2 v[120:121], v1, s[88:89] offset:2560 nt
	global_load_dwordx2 v[122:123], v1, s[88:89] offset:3072 nt
	global_load_dwordx2 v[124:125], v1, s[88:89] offset:3584 nt
	s_add_u32 s88, s88, 0x800000
	s_addc_u32 s89, s89, 0
	global_load_dwordx2 v[24:25], v1, s[88:89] offset:0 nt
	global_load_dwordx2 v[26:27], v1, s[88:89] offset:512 nt
	global_load_dwordx2 v[8:9], v1, s[88:89] offset:1024 nt
	global_load_dwordx2 v[10:11], v1, s[88:89] offset:1536 nt
	global_load_dwordx2 v[220:221], v1, s[88:89] offset:2048 nt
	global_load_dwordx2 v[222:223], v1, s[88:89] offset:2560 nt
	global_load_dwordx2 v[224:225], v1, s[88:89] offset:3072 nt
	global_load_dwordx2 v[226:227], v1, s[88:89] offset:3584 nt
	s_add_u32 s88, s88, 0x800000
	s_addc_u32 s89, s89, 0
	s_waitcnt vmcnt(32)
	v_lshlrev_b32_e32 v126, 16, v204
	v_and_b32_e32 v127, 0xffff0000, v204
	v_lshlrev_b32_e32 v128, 16, v205
	v_and_b32_e32 v129, 0xffff0000, v205
	v_lshlrev_b32_e32 v130, 16, v206
	v_and_b32_e32 v131, 0xffff0000, v206
	v_lshlrev_b32_e32 v132, 16, v207
	v_and_b32_e32 v133, 0xffff0000, v207
	v_lshlrev_b32_e32 v240, 16, v208
	v_and_b32_e32 v241, 0xffff0000, v208
	v_lshlrev_b32_e32 v242, 16, v209
	v_and_b32_e32 v243, 0xffff0000, v209
	v_lshlrev_b32_e32 v244, 16, v210
	v_and_b32_e32 v245, 0xffff0000, v210
	v_lshlrev_b32_e32 v246, 16, v211
	v_and_b32_e32 v247, 0xffff0000, v211
	v_lshlrev_b32_e32 v248, 16, v212
	v_and_b32_e32 v249, 0xffff0000, v212
	v_lshlrev_b32_e32 v250, 16, v213
	v_and_b32_e32 v251, 0xffff0000, v213
	v_lshlrev_b32_e32 v32, 16, v214
	v_and_b32_e32 v33, 0xffff0000, v214
	v_lshlrev_b32_e32 v34, 16, v215
	v_and_b32_e32 v35, 0xffff0000, v215
	v_lshlrev_b32_e32 v36, 16, v216
	v_and_b32_e32 v37, 0xffff0000, v216
	v_lshlrev_b32_e32 v38, 16, v217
	v_and_b32_e32 v39, 0xffff0000, v217
	v_lshlrev_b32_e32 v20, 16, v218
	v_and_b32_e32 v21, 0xffff0000, v218
	v_lshlrev_b32_e32 v22, 16, v219
	v_and_b32_e32 v23, 0xffff0000, v219
	v_pk_add_f32 v[228:229], v[126:127], v[128:129]
	v_pk_add_f32 v[228:229], v[228:229], v[130:131]
	v_pk_add_f32 v[228:229], v[228:229], v[132:133]
	v_pk_add_f32 v[228:229], v[228:229], v[240:241]
	v_pk_add_f32 v[228:229], v[228:229], v[242:243]
	v_pk_add_f32 v[228:229], v[228:229], v[244:245]
	v_pk_add_f32 v[228:229], v[228:229], v[246:247]
	v_pk_add_f32 v[228:229], v[228:229], v[248:249]
	v_pk_add_f32 v[228:229], v[228:229], v[250:251]
	v_pk_add_f32 v[228:229], v[228:229], v[32:33]
	v_pk_add_f32 v[228:229], v[228:229], v[34:35]
	v_pk_add_f32 v[228:229], v[228:229], v[36:37]
	v_pk_add_f32 v[228:229], v[228:229], v[38:39]
	v_pk_add_f32 v[228:229], v[228:229], v[20:21]
	v_pk_add_f32 v[228:229], v[228:229], v[22:23]
	v_add_f32_e32 v228, v228, v229
	s_nop 1
	v_add_f32_dpp v228, v228, v228 quad_perm:[1,0,3,2] row_mask:0xf bank_mask:0xf bound_ctrl:1
	s_nop 1
	v_add_f32_dpp v228, v228, v228 quad_perm:[2,3,0,1] row_mask:0xf bank_mask:0xf bound_ctrl:1
	s_nop 1
	v_add_f32_dpp v228, v228, v228 row_half_mirror row_mask:0xf bank_mask:0xf bound_ctrl:1
	s_nop 1
	v_add_f32_dpp v228, v228, v228 row_mirror row_mask:0xf bank_mask:0xf bound_ctrl:1
	v_mov_b32_e32 v2, v228
	s_nop 1
	v_permlane16_swap_b32 v228, v2
	s_nop 0
	v_add_f32_e32 v228, v228, v2
	v_mov_b32_e32 v2, v228
	s_nop 1
	v_permlane32_swap_b32 v228, v2
	s_nop 0
	v_add_f32_e32 v228, v228, v2
	v_mul_f32_e32 v134, 0x3a000000, v228
	v_pk_add_f32 v[126:127], v[126:127], v[134:135] op_sel_hi:[1,0] neg_lo:[0,1] neg_hi:[0,1]
	v_pk_add_f32 v[128:129], v[128:129], v[134:135] op_sel_hi:[1,0] neg_lo:[0,1] neg_hi:[0,1]
	v_pk_add_f32 v[130:131], v[130:131], v[134:135] op_sel_hi:[1,0] neg_lo:[0,1] neg_hi:[0,1]
	v_pk_add_f32 v[132:133], v[132:133], v[134:135] op_sel_hi:[1,0] neg_lo:[0,1] neg_hi:[0,1]
	v_pk_add_f32 v[240:241], v[240:241], v[134:135] op_sel_hi:[1,0] neg_lo:[0,1] neg_hi:[0,1]
	v_pk_add_f32 v[242:243], v[242:243], v[134:135] op_sel_hi:[1,0] neg_lo:[0,1] neg_hi:[0,1]
	v_pk_add_f32 v[244:245], v[244:245], v[134:135] op_sel_hi:[1,0] neg_lo:[0,1] neg_hi:[0,1]
	v_pk_add_f32 v[246:247], v[246:247], v[134:135] op_sel_hi:[1,0] neg_lo:[0,1] neg_hi:[0,1]
	v_pk_add_f32 v[248:249], v[248:249], v[134:135] op_sel_hi:[1,0] neg_lo:[0,1] neg_hi:[0,1]
	v_pk_add_f32 v[250:251], v[250:251], v[134:135] op_sel_hi:[1,0] neg_lo:[0,1] neg_hi:[0,1]
	v_pk_add_f32 v[32:33], v[32:33], v[134:135] op_sel_hi:[1,0] neg_lo:[0,1] neg_hi:[0,1]
	v_pk_add_f32 v[34:35], v[34:35], v[134:135] op_sel_hi:[1,0] neg_lo:[0,1] neg_hi:[0,1]
	v_pk_add_f32 v[36:37], v[36:37], v[134:135] op_sel_hi:[1,0] neg_lo:[0,1] neg_hi:[0,1]
	v_pk_add_f32 v[38:39], v[38:39], v[134:135] op_sel_hi:[1,0] neg_lo:[0,1] neg_hi:[0,1]
	v_pk_add_f32 v[20:21], v[20:21], v[134:135] op_sel_hi:[1,0] neg_lo:[0,1] neg_hi:[0,1]
	v_pk_add_f32 v[22:23], v[22:23], v[134:135] op_sel_hi:[1,0] neg_lo:[0,1] neg_hi:[0,1]
	v_pk_mul_f32 v[228:229], v[126:127], v[126:127]
	v_pk_fma_f32 v[228:229], v[128:129], v[128:129], v[228:229]
	v_pk_fma_f32 v[228:229], v[130:131], v[130:131], v[228:229]
	v_pk_fma_f32 v[228:229], v[132:133], v[132:133], v[228:229]
	v_pk_fma_f32 v[228:229], v[240:241], v[240:241], v[228:229]
	v_pk_fma_f32 v[228:229], v[242:243], v[242:243], v[228:229]
	v_pk_fma_f32 v[228:229], v[244:245], v[244:245], v[228:229]
	v_pk_fma_f32 v[228:229], v[246:247], v[246:247], v[228:229]
	v_pk_fma_f32 v[228:229], v[248:249], v[248:249], v[228:229]
	v_pk_fma_f32 v[228:229], v[250:251], v[250:251], v[228:229]
	v_pk_fma_f32 v[228:229], v[32:33], v[32:33], v[228:229]
	v_pk_fma_f32 v[228:229], v[34:35], v[34:35], v[228:229]
	v_pk_fma_f32 v[228:229], v[36:37], v[36:37], v[228:229]
	v_pk_fma_f32 v[228:229], v[38:39], v[38:39], v[228:229]
	v_pk_fma_f32 v[228:229], v[20:21], v[20:21], v[228:229]
	v_pk_fma_f32 v[228:229], v[22:23], v[22:23], v[228:229]
	v_add_f32_e32 v228, v228, v229
	s_nop 1
	v_add_f32_dpp v228, v228, v228 quad_perm:[1,0,3,2] row_mask:0xf bank_mask:0xf bound_ctrl:1
	s_nop 1
	v_add_f32_dpp v228, v228, v228 quad_perm:[2,3,0,1] row_mask:0xf bank_mask:0xf bound_ctrl:1
	s_nop 1
	v_add_f32_dpp v228, v228, v228 row_half_mirror row_mask:0xf bank_mask:0xf bound_ctrl:1
	s_nop 1
	v_add_f32_dpp v228, v228, v228 row_mirror row_mask:0xf bank_mask:0xf bound_ctrl:1
	v_mov_b32_e32 v2, v228
	s_nop 1
	v_permlane16_swap_b32 v228, v2
	s_nop 0
	v_add_f32_e32 v228, v228, v2
	v_mov_b32_e32 v2, v228
	s_nop 1
	v_permlane32_swap_b32 v228, v2
	s_nop 0
	v_add_f32_e32 v228, v228, v2
	v_mul_f32_e32 v0, 0x3a000000, v228
	v_add_f32_e32 v0, 0x3727c5ac, v0
	v_rsq_f32_e32 v0, v0
	s_waitcnt vmcnt(16)
	v_pk_mul_f32 v[228:229], v[140:141], v[0:1] op_sel_hi:[1,0]
	v_pk_fma_f32 v[126:127], v[126:127], v[228:229], v[172:173]
	v_pk_mul_f32 v[228:229], v[142:143], v[0:1] op_sel_hi:[1,0]
	v_pk_fma_f32 v[128:129], v[128:129], v[228:229], v[174:175]
	v_pk_mul_f32 v[228:229], v[144:145], v[0:1] op_sel_hi:[1,0]
	v_pk_fma_f32 v[130:131], v[130:131], v[228:229], v[176:177]
	v_pk_mul_f32 v[228:229], v[146:147], v[0:1] op_sel_hi:[1,0]
	v_pk_fma_f32 v[132:133], v[132:133], v[228:229], v[178:179]
	v_pk_mul_f32 v[228:229], v[148:149], v[0:1] op_sel_hi:[1,0]
	v_pk_fma_f32 v[240:241], v[240:241], v[228:229], v[180:181]
	v_pk_mul_f32 v[228:229], v[150:151], v[0:1] op_sel_hi:[1,0]
	v_pk_fma_f32 v[242:243], v[242:243], v[228:229], v[182:183]
	v_pk_mul_f32 v[228:229], v[152:153], v[0:1] op_sel_hi:[1,0]
	v_pk_fma_f32 v[244:245], v[244:245], v[228:229], v[184:185]
	v_pk_mul_f32 v[228:229], v[154:155], v[0:1] op_sel_hi:[1,0]
	v_pk_fma_f32 v[246:247], v[246:247], v[228:229], v[186:187]
	v_pk_mul_f32 v[228:229], v[156:157], v[0:1] op_sel_hi:[1,0]
	v_pk_fma_f32 v[248:249], v[248:249], v[228:229], v[188:189]
	v_pk_mul_f32 v[228:229], v[158:159], v[0:1] op_sel_hi:[1,0]
	v_pk_fma_f32 v[250:251], v[250:251], v[228:229], v[190:191]
	v_pk_mul_f32 v[228:229], v[160:161], v[0:1] op_sel_hi:[1,0]
	v_pk_fma_f32 v[32:33], v[32:33], v[228:229], v[192:193]
	v_pk_mul_f32 v[228:229], v[162:163], v[0:1] op_sel_hi:[1,0]
	v_pk_fma_f32 v[34:35], v[34:35], v[228:229], v[194:195]
	v_pk_mul_f32 v[228:229], v[164:165], v[0:1] op_sel_hi:[1,0]
	v_pk_fma_f32 v[36:37], v[36:37], v[228:229], v[196:197]
	v_pk_mul_f32 v[228:229], v[166:167], v[0:1] op_sel_hi:[1,0]
	v_pk_fma_f32 v[38:39], v[38:39], v[228:229], v[198:199]
	v_pk_mul_f32 v[228:229], v[168:169], v[0:1] op_sel_hi:[1,0]
	v_pk_fma_f32 v[20:21], v[20:21], v[228:229], v[200:201]
	v_pk_mul_f32 v[228:229], v[170:171], v[0:1] op_sel_hi:[1,0]
	v_pk_fma_f32 v[22:23], v[22:23], v[228:229], v[202:203]
	v_cvt_pk_bf16_f32 v204, v126, v127
	v_cvt_pk_bf16_f32 v205, v128, v129
	v_cvt_pk_bf16_f32 v206, v130, v131
	v_cvt_pk_bf16_f32 v207, v132, v133
	v_cvt_pk_bf16_f32 v208, v240, v241
	v_cvt_pk_bf16_f32 v209, v242, v243
	v_cvt_pk_bf16_f32 v210, v244, v245
	v_cvt_pk_bf16_f32 v211, v246, v247
	v_cvt_pk_bf16_f32 v212, v248, v249
	v_cvt_pk_bf16_f32 v213, v250, v251
	v_cvt_pk_bf16_f32 v214, v32, v33
	v_cvt_pk_bf16_f32 v215, v34, v35
	v_cvt_pk_bf16_f32 v216, v36, v37
	v_cvt_pk_bf16_f32 v217, v38, v39
	v_cvt_pk_bf16_f32 v218, v20, v21
	v_cvt_pk_bf16_f32 v219, v22, v23
	global_store_dwordx2 v1, v[204:205], s[90:91] offset:0
	global_store_dwordx2 v1, v[206:207], s[90:91] offset:512
	global_store_dwordx2 v1, v[208:209], s[90:91] offset:1024
	global_store_dwordx2 v1, v[210:211], s[90:91] offset:1536
	global_store_dwordx2 v1, v[212:213], s[90:91] offset:2048
	global_store_dwordx2 v1, v[214:215], s[90:91] offset:2560
	global_store_dwordx2 v1, v[216:217], s[90:91] offset:3072
	global_store_dwordx2 v1, v[218:219], s[90:91] offset:3584
	s_add_u32 s90, s90, 0x800000
	s_addc_u32 s91, s91, 0
	global_load_dwordx2 v[204:205], v1, s[88:89] offset:0 nt
	global_load_dwordx2 v[206:207], v1, s[88:89] offset:512 nt
	global_load_dwordx2 v[208:209], v1, s[88:89] offset:1024 nt
	global_load_dwordx2 v[210:211], v1, s[88:89] offset:1536 nt
	global_load_dwordx2 v[212:213], v1, s[88:89] offset:2048 nt
	global_load_dwordx2 v[214:215], v1, s[88:89] offset:2560 nt
	global_load_dwordx2 v[216:217], v1, s[88:89] offset:3072 nt
	global_load_dwordx2 v[218:219], v1, s[88:89] offset:3584 nt
	s_add_u32 s88, s88, 0x800000
	s_addc_u32 s89, s89, 0
	s_waitcnt vmcnt(24)
	v_lshlrev_b32_e32 v126, 16, v110
	v_and_b32_e32 v127, 0xffff0000, v110
	v_lshlrev_b32_e32 v128, 16, v111
	v_and_b32_e32 v129, 0xffff0000, v111
	v_lshlrev_b32_e32 v130, 16, v112
	v_and_b32_e32 v131, 0xffff0000, v112
	v_lshlrev_b32_e32 v132, 16, v113
	v_and_b32_e32 v133, 0xffff0000, v113
	v_lshlrev_b32_e32 v240, 16, v114
	v_and_b32_e32 v241, 0xffff0000, v114
	v_lshlrev_b32_e32 v242, 16, v115
	v_and_b32_e32 v243, 0xffff0000, v115
	v_lshlrev_b32_e32 v244, 16, v116
	v_and_b32_e32 v245, 0xffff0000, v116
	v_lshlrev_b32_e32 v246, 16, v117
	v_and_b32_e32 v247, 0xffff0000, v117
	v_lshlrev_b32_e32 v248, 16, v118
	v_and_b32_e32 v249, 0xffff0000, v118
	v_lshlrev_b32_e32 v250, 16, v119
	v_and_b32_e32 v251, 0xffff0000, v119
	v_lshlrev_b32_e32 v32, 16, v120
	v_and_b32_e32 v33, 0xffff0000, v120
	v_lshlrev_b32_e32 v34, 16, v121
	v_and_b32_e32 v35, 0xffff0000, v121
	v_lshlrev_b32_e32 v36, 16, v122
	v_and_b32_e32 v37, 0xffff0000, v122
	v_lshlrev_b32_e32 v38, 16, v123
	v_and_b32_e32 v39, 0xffff0000, v123
	v_lshlrev_b32_e32 v20, 16, v124
	v_and_b32_e32 v21, 0xffff0000, v124
	v_lshlrev_b32_e32 v22, 16, v125
	v_and_b32_e32 v23, 0xffff0000, v125
	v_pk_add_f32 v[228:229], v[126:127], v[128:129]
	v_pk_add_f32 v[228:229], v[228:229], v[130:131]
	v_pk_add_f32 v[228:229], v[228:229], v[132:133]
	v_pk_add_f32 v[228:229], v[228:229], v[240:241]
	v_pk_add_f32 v[228:229], v[228:229], v[242:243]
	v_pk_add_f32 v[228:229], v[228:229], v[244:245]
	v_pk_add_f32 v[228:229], v[228:229], v[246:247]
	v_pk_add_f32 v[228:229], v[228:229], v[248:249]
	v_pk_add_f32 v[228:229], v[228:229], v[250:251]
	v_pk_add_f32 v[228:229], v[228:229], v[32:33]
	v_pk_add_f32 v[228:229], v[228:229], v[34:35]
	v_pk_add_f32 v[228:229], v[228:229], v[36:37]
	v_pk_add_f32 v[228:229], v[228:229], v[38:39]
	v_pk_add_f32 v[228:229], v[228:229], v[20:21]
	v_pk_add_f32 v[228:229], v[228:229], v[22:23]
	v_add_f32_e32 v228, v228, v229
	s_nop 1
	v_add_f32_dpp v228, v228, v228 quad_perm:[1,0,3,2] row_mask:0xf bank_mask:0xf bound_ctrl:1
	s_nop 1
	v_add_f32_dpp v228, v228, v228 quad_perm:[2,3,0,1] row_mask:0xf bank_mask:0xf bound_ctrl:1
	s_nop 1
	v_add_f32_dpp v228, v228, v228 row_half_mirror row_mask:0xf bank_mask:0xf bound_ctrl:1
	s_nop 1
	v_add_f32_dpp v228, v228, v228 row_mirror row_mask:0xf bank_mask:0xf bound_ctrl:1
	v_mov_b32_e32 v2, v228
	s_nop 1
	v_permlane16_swap_b32 v228, v2
	s_nop 0
	v_add_f32_e32 v228, v228, v2
	v_mov_b32_e32 v2, v228
	s_nop 1
	v_permlane32_swap_b32 v228, v2
	s_nop 0
	v_add_f32_e32 v228, v228, v2
	v_mul_f32_e32 v134, 0x3a000000, v228
	v_pk_add_f32 v[126:127], v[126:127], v[134:135] op_sel_hi:[1,0] neg_lo:[0,1] neg_hi:[0,1]
	v_pk_add_f32 v[128:129], v[128:129], v[134:135] op_sel_hi:[1,0] neg_lo:[0,1] neg_hi:[0,1]
	v_pk_add_f32 v[130:131], v[130:131], v[134:135] op_sel_hi:[1,0] neg_lo:[0,1] neg_hi:[0,1]
	v_pk_add_f32 v[132:133], v[132:133], v[134:135] op_sel_hi:[1,0] neg_lo:[0,1] neg_hi:[0,1]
	v_pk_add_f32 v[240:241], v[240:241], v[134:135] op_sel_hi:[1,0] neg_lo:[0,1] neg_hi:[0,1]
	v_pk_add_f32 v[242:243], v[242:243], v[134:135] op_sel_hi:[1,0] neg_lo:[0,1] neg_hi:[0,1]
	v_pk_add_f32 v[244:245], v[244:245], v[134:135] op_sel_hi:[1,0] neg_lo:[0,1] neg_hi:[0,1]
	v_pk_add_f32 v[246:247], v[246:247], v[134:135] op_sel_hi:[1,0] neg_lo:[0,1] neg_hi:[0,1]
	v_pk_add_f32 v[248:249], v[248:249], v[134:135] op_sel_hi:[1,0] neg_lo:[0,1] neg_hi:[0,1]
	v_pk_add_f32 v[250:251], v[250:251], v[134:135] op_sel_hi:[1,0] neg_lo:[0,1] neg_hi:[0,1]
	v_pk_add_f32 v[32:33], v[32:33], v[134:135] op_sel_hi:[1,0] neg_lo:[0,1] neg_hi:[0,1]
	v_pk_add_f32 v[34:35], v[34:35], v[134:135] op_sel_hi:[1,0] neg_lo:[0,1] neg_hi:[0,1]
	v_pk_add_f32 v[36:37], v[36:37], v[134:135] op_sel_hi:[1,0] neg_lo:[0,1] neg_hi:[0,1]
	v_pk_add_f32 v[38:39], v[38:39], v[134:135] op_sel_hi:[1,0] neg_lo:[0,1] neg_hi:[0,1]
	v_pk_add_f32 v[20:21], v[20:21], v[134:135] op_sel_hi:[1,0] neg_lo:[0,1] neg_hi:[0,1]
	v_pk_add_f32 v[22:23], v[22:23], v[134:135] op_sel_hi:[1,0] neg_lo:[0,1] neg_hi:[0,1]
	v_pk_mul_f32 v[228:229], v[126:127], v[126:127]
	v_pk_fma_f32 v[228:229], v[128:129], v[128:129], v[228:229]
	v_pk_fma_f32 v[228:229], v[130:131], v[130:131], v[228:229]
	v_pk_fma_f32 v[228:229], v[132:133], v[132:133], v[228:229]
	v_pk_fma_f32 v[228:229], v[240:241], v[240:241], v[228:229]
	v_pk_fma_f32 v[228:229], v[242:243], v[242:243], v[228:229]
	v_pk_fma_f32 v[228:229], v[244:245], v[244:245], v[228:229]
	v_pk_fma_f32 v[228:229], v[246:247], v[246:247], v[228:229]
	v_pk_fma_f32 v[228:229], v[248:249], v[248:249], v[228:229]
	v_pk_fma_f32 v[228:229], v[250:251], v[250:251], v[228:229]
	v_pk_fma_f32 v[228:229], v[32:33], v[32:33], v[228:229]
	v_pk_fma_f32 v[228:229], v[34:35], v[34:35], v[228:229]
	v_pk_fma_f32 v[228:229], v[36:37], v[36:37], v[228:229]
	v_pk_fma_f32 v[228:229], v[38:39], v[38:39], v[228:229]
	v_pk_fma_f32 v[228:229], v[20:21], v[20:21], v[228:229]
	v_pk_fma_f32 v[228:229], v[22:23], v[22:23], v[228:229]
	v_add_f32_e32 v228, v228, v229
	s_nop 1
	v_add_f32_dpp v228, v228, v228 quad_perm:[1,0,3,2] row_mask:0xf bank_mask:0xf bound_ctrl:1
	s_nop 1
	v_add_f32_dpp v228, v228, v228 quad_perm:[2,3,0,1] row_mask:0xf bank_mask:0xf bound_ctrl:1
	s_nop 1
	v_add_f32_dpp v228, v228, v228 row_half_mirror row_mask:0xf bank_mask:0xf bound_ctrl:1
	s_nop 1
	v_add_f32_dpp v228, v228, v228 row_mirror row_mask:0xf bank_mask:0xf bound_ctrl:1
	v_mov_b32_e32 v2, v228
	s_nop 1
	v_permlane16_swap_b32 v228, v2
	s_nop 0
	v_add_f32_e32 v228, v228, v2
	v_mov_b32_e32 v2, v228
	s_nop 1
	v_permlane32_swap_b32 v228, v2
	s_nop 0
	v_add_f32_e32 v228, v228, v2
	v_mul_f32_e32 v0, 0x3a000000, v228
	v_add_f32_e32 v0, 0x3727c5ac, v0
	v_rsq_f32_e32 v0, v0
	s_nop 0
	v_pk_mul_f32 v[228:229], v[140:141], v[0:1] op_sel_hi:[1,0]
	v_pk_fma_f32 v[126:127], v[126:127], v[228:229], v[172:173]
	v_pk_mul_f32 v[228:229], v[142:143], v[0:1] op_sel_hi:[1,0]
	v_pk_fma_f32 v[128:129], v[128:129], v[228:229], v[174:175]
	v_pk_mul_f32 v[228:229], v[144:145], v[0:1] op_sel_hi:[1,0]
	v_pk_fma_f32 v[130:131], v[130:131], v[228:229], v[176:177]
	v_pk_mul_f32 v[228:229], v[146:147], v[0:1] op_sel_hi:[1,0]
	v_pk_fma_f32 v[132:133], v[132:133], v[228:229], v[178:179]
	v_pk_mul_f32 v[228:229], v[148:149], v[0:1] op_sel_hi:[1,0]
	v_pk_fma_f32 v[240:241], v[240:241], v[228:229], v[180:181]
	v_pk_mul_f32 v[228:229], v[150:151], v[0:1] op_sel_hi:[1,0]
	v_pk_fma_f32 v[242:243], v[242:243], v[228:229], v[182:183]
	v_pk_mul_f32 v[228:229], v[152:153], v[0:1] op_sel_hi:[1,0]
	v_pk_fma_f32 v[244:245], v[244:245], v[228:229], v[184:185]
	v_pk_mul_f32 v[228:229], v[154:155], v[0:1] op_sel_hi:[1,0]
	v_pk_fma_f32 v[246:247], v[246:247], v[228:229], v[186:187]
	v_pk_mul_f32 v[228:229], v[156:157], v[0:1] op_sel_hi:[1,0]
	v_pk_fma_f32 v[248:249], v[248:249], v[228:229], v[188:189]
	v_pk_mul_f32 v[228:229], v[158:159], v[0:1] op_sel_hi:[1,0]
	v_pk_fma_f32 v[250:251], v[250:251], v[228:229], v[190:191]
	v_pk_mul_f32 v[228:229], v[160:161], v[0:1] op_sel_hi:[1,0]
	v_pk_fma_f32 v[32:33], v[32:33], v[228:229], v[192:193]
	v_pk_mul_f32 v[228:229], v[162:163], v[0:1] op_sel_hi:[1,0]
	v_pk_fma_f32 v[34:35], v[34:35], v[228:229], v[194:195]
	v_pk_mul_f32 v[228:229], v[164:165], v[0:1] op_sel_hi:[1,0]
	v_pk_fma_f32 v[36:37], v[36:37], v[228:229], v[196:197]
	v_pk_mul_f32 v[228:229], v[166:167], v[0:1] op_sel_hi:[1,0]
	v_pk_fma_f32 v[38:39], v[38:39], v[228:229], v[198:199]
	v_pk_mul_f32 v[228:229], v[168:169], v[0:1] op_sel_hi:[1,0]
	v_pk_fma_f32 v[20:21], v[20:21], v[228:229], v[200:201]
	v_pk_mul_f32 v[228:229], v[170:171], v[0:1] op_sel_hi:[1,0]
	v_pk_fma_f32 v[22:23], v[22:23], v[228:229], v[202:203]
	v_cvt_pk_bf16_f32 v110, v126, v127
	v_cvt_pk_bf16_f32 v111, v128, v129
	v_cvt_pk_bf16_f32 v112, v130, v131
	v_cvt_pk_bf16_f32 v113, v132, v133
	v_cvt_pk_bf16_f32 v114, v240, v241
	v_cvt_pk_bf16_f32 v115, v242, v243
	v_cvt_pk_bf16_f32 v116, v244, v245
	v_cvt_pk_bf16_f32 v117, v246, v247
	v_cvt_pk_bf16_f32 v118, v248, v249
	v_cvt_pk_bf16_f32 v119, v250, v251
	v_cvt_pk_bf16_f32 v120, v32, v33
	v_cvt_pk_bf16_f32 v121, v34, v35
	v_cvt_pk_bf16_f32 v122, v36, v37
	v_cvt_pk_bf16_f32 v123, v38, v39
	v_cvt_pk_bf16_f32 v124, v20, v21
	v_cvt_pk_bf16_f32 v125, v22, v23
	global_store_dwordx2 v1, v[110:111], s[90:91] offset:0
	global_store_dwordx2 v1, v[112:113], s[90:91] offset:512
	global_store_dwordx2 v1, v[114:115], s[90:91] offset:1024
	global_store_dwordx2 v1, v[116:117], s[90:91] offset:1536
	global_store_dwordx2 v1, v[118:119], s[90:91] offset:2048
	global_store_dwordx2 v1, v[120:121], s[90:91] offset:2560
	global_store_dwordx2 v1, v[122:123], s[90:91] offset:3072
	global_store_dwordx2 v1, v[124:125], s[90:91] offset:3584
	s_add_u32 s90, s90, 0x800000
	s_addc_u32 s91, s91, 0
	s_waitcnt vmcnt(24)
	v_lshlrev_b32_e32 v126, 16, v24
	v_and_b32_e32 v127, 0xffff0000, v24
	v_lshlrev_b32_e32 v128, 16, v25
	v_and_b32_e32 v129, 0xffff0000, v25
	v_lshlrev_b32_e32 v130, 16, v26
	v_and_b32_e32 v131, 0xffff0000, v26
	v_lshlrev_b32_e32 v132, 16, v27
	v_and_b32_e32 v133, 0xffff0000, v27
	v_lshlrev_b32_e32 v240, 16, v8
	v_and_b32_e32 v241, 0xffff0000, v8
	v_lshlrev_b32_e32 v242, 16, v9
	v_and_b32_e32 v243, 0xffff0000, v9
	v_lshlrev_b32_e32 v244, 16, v10
	v_and_b32_e32 v245, 0xffff0000, v10
	v_lshlrev_b32_e32 v246, 16, v11
	v_and_b32_e32 v247, 0xffff0000, v11
	v_lshlrev_b32_e32 v248, 16, v220
	v_and_b32_e32 v249, 0xffff0000, v220
	v_lshlrev_b32_e32 v250, 16, v221
	v_and_b32_e32 v251, 0xffff0000, v221
	v_lshlrev_b32_e32 v32, 16, v222
	v_and_b32_e32 v33, 0xffff0000, v222
	v_lshlrev_b32_e32 v34, 16, v223
	v_and_b32_e32 v35, 0xffff0000, v223
	v_lshlrev_b32_e32 v36, 16, v224
	v_and_b32_e32 v37, 0xffff0000, v224
	v_lshlrev_b32_e32 v38, 16, v225
	v_and_b32_e32 v39, 0xffff0000, v225
	v_lshlrev_b32_e32 v20, 16, v226
	v_and_b32_e32 v21, 0xffff0000, v226
	v_lshlrev_b32_e32 v22, 16, v227
	v_and_b32_e32 v23, 0xffff0000, v227
	v_pk_add_f32 v[228:229], v[126:127], v[128:129]
	v_pk_add_f32 v[228:229], v[228:229], v[130:131]
	v_pk_add_f32 v[228:229], v[228:229], v[132:133]
	v_pk_add_f32 v[228:229], v[228:229], v[240:241]
	v_pk_add_f32 v[228:229], v[228:229], v[242:243]
	v_pk_add_f32 v[228:229], v[228:229], v[244:245]
	v_pk_add_f32 v[228:229], v[228:229], v[246:247]
	v_pk_add_f32 v[228:229], v[228:229], v[248:249]
	v_pk_add_f32 v[228:229], v[228:229], v[250:251]
	v_pk_add_f32 v[228:229], v[228:229], v[32:33]
	v_pk_add_f32 v[228:229], v[228:229], v[34:35]
	v_pk_add_f32 v[228:229], v[228:229], v[36:37]
	v_pk_add_f32 v[228:229], v[228:229], v[38:39]
	v_pk_add_f32 v[228:229], v[228:229], v[20:21]
	v_pk_add_f32 v[228:229], v[228:229], v[22:23]
	v_add_f32_e32 v228, v228, v229
	s_nop 1
	v_add_f32_dpp v228, v228, v228 quad_perm:[1,0,3,2] row_mask:0xf bank_mask:0xf bound_ctrl:1
	s_nop 1
	v_add_f32_dpp v228, v228, v228 quad_perm:[2,3,0,1] row_mask:0xf bank_mask:0xf bound_ctrl:1
	s_nop 1
	v_add_f32_dpp v228, v228, v228 row_half_mirror row_mask:0xf bank_mask:0xf bound_ctrl:1
	s_nop 1
	v_add_f32_dpp v228, v228, v228 row_mirror row_mask:0xf bank_mask:0xf bound_ctrl:1
	v_mov_b32_e32 v2, v228
	s_nop 1
	v_permlane16_swap_b32 v228, v2
	s_nop 0
	v_add_f32_e32 v228, v228, v2
	v_mov_b32_e32 v2, v228
	s_nop 1
	v_permlane32_swap_b32 v228, v2
	s_nop 0
	v_add_f32_e32 v228, v228, v2
	v_mul_f32_e32 v134, 0x3a000000, v228
	v_pk_add_f32 v[126:127], v[126:127], v[134:135] op_sel_hi:[1,0] neg_lo:[0,1] neg_hi:[0,1]
	v_pk_add_f32 v[128:129], v[128:129], v[134:135] op_sel_hi:[1,0] neg_lo:[0,1] neg_hi:[0,1]
	v_pk_add_f32 v[130:131], v[130:131], v[134:135] op_sel_hi:[1,0] neg_lo:[0,1] neg_hi:[0,1]
	v_pk_add_f32 v[132:133], v[132:133], v[134:135] op_sel_hi:[1,0] neg_lo:[0,1] neg_hi:[0,1]
	v_pk_add_f32 v[240:241], v[240:241], v[134:135] op_sel_hi:[1,0] neg_lo:[0,1] neg_hi:[0,1]
	v_pk_add_f32 v[242:243], v[242:243], v[134:135] op_sel_hi:[1,0] neg_lo:[0,1] neg_hi:[0,1]
	v_pk_add_f32 v[244:245], v[244:245], v[134:135] op_sel_hi:[1,0] neg_lo:[0,1] neg_hi:[0,1]
	v_pk_add_f32 v[246:247], v[246:247], v[134:135] op_sel_hi:[1,0] neg_lo:[0,1] neg_hi:[0,1]
	v_pk_add_f32 v[248:249], v[248:249], v[134:135] op_sel_hi:[1,0] neg_lo:[0,1] neg_hi:[0,1]
	v_pk_add_f32 v[250:251], v[250:251], v[134:135] op_sel_hi:[1,0] neg_lo:[0,1] neg_hi:[0,1]
	v_pk_add_f32 v[32:33], v[32:33], v[134:135] op_sel_hi:[1,0] neg_lo:[0,1] neg_hi:[0,1]
	v_pk_add_f32 v[34:35], v[34:35], v[134:135] op_sel_hi:[1,0] neg_lo:[0,1] neg_hi:[0,1]
	v_pk_add_f32 v[36:37], v[36:37], v[134:135] op_sel_hi:[1,0] neg_lo:[0,1] neg_hi:[0,1]
	v_pk_add_f32 v[38:39], v[38:39], v[134:135] op_sel_hi:[1,0] neg_lo:[0,1] neg_hi:[0,1]
	v_pk_add_f32 v[20:21], v[20:21], v[134:135] op_sel_hi:[1,0] neg_lo:[0,1] neg_hi:[0,1]
	v_pk_add_f32 v[22:23], v[22:23], v[134:135] op_sel_hi:[1,0] neg_lo:[0,1] neg_hi:[0,1]
	v_pk_mul_f32 v[228:229], v[126:127], v[126:127]
	v_pk_fma_f32 v[228:229], v[128:129], v[128:129], v[228:229]
	v_pk_fma_f32 v[228:229], v[130:131], v[130:131], v[228:229]
	v_pk_fma_f32 v[228:229], v[132:133], v[132:133], v[228:229]
	v_pk_fma_f32 v[228:229], v[240:241], v[240:241], v[228:229]
	v_pk_fma_f32 v[228:229], v[242:243], v[242:243], v[228:229]
	v_pk_fma_f32 v[228:229], v[244:245], v[244:245], v[228:229]
	v_pk_fma_f32 v[228:229], v[246:247], v[246:247], v[228:229]
	v_pk_fma_f32 v[228:229], v[248:249], v[248:249], v[228:229]
	v_pk_fma_f32 v[228:229], v[250:251], v[250:251], v[228:229]
	v_pk_fma_f32 v[228:229], v[32:33], v[32:33], v[228:229]
	v_pk_fma_f32 v[228:229], v[34:35], v[34:35], v[228:229]
	v_pk_fma_f32 v[228:229], v[36:37], v[36:37], v[228:229]
	v_pk_fma_f32 v[228:229], v[38:39], v[38:39], v[228:229]
	v_pk_fma_f32 v[228:229], v[20:21], v[20:21], v[228:229]
	v_pk_fma_f32 v[228:229], v[22:23], v[22:23], v[228:229]
	v_add_f32_e32 v228, v228, v229
	s_nop 1
	v_add_f32_dpp v228, v228, v228 quad_perm:[1,0,3,2] row_mask:0xf bank_mask:0xf bound_ctrl:1
	s_nop 1
	v_add_f32_dpp v228, v228, v228 quad_perm:[2,3,0,1] row_mask:0xf bank_mask:0xf bound_ctrl:1
	s_nop 1
	v_add_f32_dpp v228, v228, v228 row_half_mirror row_mask:0xf bank_mask:0xf bound_ctrl:1
	s_nop 1
	v_add_f32_dpp v228, v228, v228 row_mirror row_mask:0xf bank_mask:0xf bound_ctrl:1
	v_mov_b32_e32 v2, v228
	s_nop 1
	v_permlane16_swap_b32 v228, v2
	s_nop 0
	v_add_f32_e32 v228, v228, v2
	v_mov_b32_e32 v2, v228
	s_nop 1
	v_permlane32_swap_b32 v228, v2
	s_nop 0
	v_add_f32_e32 v228, v228, v2
	v_mul_f32_e32 v0, 0x3a000000, v228
	v_add_f32_e32 v0, 0x3727c5ac, v0
	v_rsq_f32_e32 v0, v0
	s_nop 0
	v_pk_mul_f32 v[228:229], v[140:141], v[0:1] op_sel_hi:[1,0]
	v_pk_fma_f32 v[126:127], v[126:127], v[228:229], v[172:173]
	v_pk_mul_f32 v[228:229], v[142:143], v[0:1] op_sel_hi:[1,0]
	v_pk_fma_f32 v[128:129], v[128:129], v[228:229], v[174:175]
	v_pk_mul_f32 v[228:229], v[144:145], v[0:1] op_sel_hi:[1,0]
	v_pk_fma_f32 v[130:131], v[130:131], v[228:229], v[176:177]
	v_pk_mul_f32 v[228:229], v[146:147], v[0:1] op_sel_hi:[1,0]
	v_pk_fma_f32 v[132:133], v[132:133], v[228:229], v[178:179]
	v_pk_mul_f32 v[228:229], v[148:149], v[0:1] op_sel_hi:[1,0]
	v_pk_fma_f32 v[240:241], v[240:241], v[228:229], v[180:181]
	v_pk_mul_f32 v[228:229], v[150:151], v[0:1] op_sel_hi:[1,0]
	v_pk_fma_f32 v[242:243], v[242:243], v[228:229], v[182:183]
	v_pk_mul_f32 v[228:229], v[152:153], v[0:1] op_sel_hi:[1,0]
	v_pk_fma_f32 v[244:245], v[244:245], v[228:229], v[184:185]
	v_pk_mul_f32 v[228:229], v[154:155], v[0:1] op_sel_hi:[1,0]
	v_pk_fma_f32 v[246:247], v[246:247], v[228:229], v[186:187]
	v_pk_mul_f32 v[228:229], v[156:157], v[0:1] op_sel_hi:[1,0]
	v_pk_fma_f32 v[248:249], v[248:249], v[228:229], v[188:189]
	v_pk_mul_f32 v[228:229], v[158:159], v[0:1] op_sel_hi:[1,0]
	v_pk_fma_f32 v[250:251], v[250:251], v[228:229], v[190:191]
	v_pk_mul_f32 v[228:229], v[160:161], v[0:1] op_sel_hi:[1,0]
	v_pk_fma_f32 v[32:33], v[32:33], v[228:229], v[192:193]
	v_pk_mul_f32 v[228:229], v[162:163], v[0:1] op_sel_hi:[1,0]
	v_pk_fma_f32 v[34:35], v[34:35], v[228:229], v[194:195]
	v_pk_mul_f32 v[228:229], v[164:165], v[0:1] op_sel_hi:[1,0]
	v_pk_fma_f32 v[36:37], v[36:37], v[228:229], v[196:197]
	v_pk_mul_f32 v[228:229], v[166:167], v[0:1] op_sel_hi:[1,0]
	v_pk_fma_f32 v[38:39], v[38:39], v[228:229], v[198:199]
	v_pk_mul_f32 v[228:229], v[168:169], v[0:1] op_sel_hi:[1,0]
	v_pk_fma_f32 v[20:21], v[20:21], v[228:229], v[200:201]
	v_pk_mul_f32 v[228:229], v[170:171], v[0:1] op_sel_hi:[1,0]
	v_pk_fma_f32 v[22:23], v[22:23], v[228:229], v[202:203]
	v_cvt_pk_bf16_f32 v24, v126, v127
	v_cvt_pk_bf16_f32 v25, v128, v129
	v_cvt_pk_bf16_f32 v26, v130, v131
	v_cvt_pk_bf16_f32 v27, v132, v133
	v_cvt_pk_bf16_f32 v8, v240, v241
	v_cvt_pk_bf16_f32 v9, v242, v243
	v_cvt_pk_bf16_f32 v10, v244, v245
	v_cvt_pk_bf16_f32 v11, v246, v247
	v_cvt_pk_bf16_f32 v220, v248, v249
	v_cvt_pk_bf16_f32 v221, v250, v251
	v_cvt_pk_bf16_f32 v222, v32, v33
	v_cvt_pk_bf16_f32 v223, v34, v35
	v_cvt_pk_bf16_f32 v224, v36, v37
	v_cvt_pk_bf16_f32 v225, v38, v39
	v_cvt_pk_bf16_f32 v226, v20, v21
	v_cvt_pk_bf16_f32 v227, v22, v23
	global_store_dwordx2 v1, v[24:25], s[90:91] offset:0
	global_store_dwordx2 v1, v[26:27], s[90:91] offset:512
	global_store_dwordx2 v1, v[8:9], s[90:91] offset:1024
	global_store_dwordx2 v1, v[10:11], s[90:91] offset:1536
	global_store_dwordx2 v1, v[220:221], s[90:91] offset:2048
	global_store_dwordx2 v1, v[222:223], s[90:91] offset:2560
	global_store_dwordx2 v1, v[224:225], s[90:91] offset:3072
	global_store_dwordx2 v1, v[226:227], s[90:91] offset:3584
	s_add_u32 s90, s90, 0x800000
	s_addc_u32 s91, s91, 0
	s_waitcnt vmcnt(16)
	v_lshlrev_b32_e32 v126, 16, v204
	v_and_b32_e32 v127, 0xffff0000, v204
	v_lshlrev_b32_e32 v128, 16, v205
	v_and_b32_e32 v129, 0xffff0000, v205
	v_lshlrev_b32_e32 v130, 16, v206
	v_and_b32_e32 v131, 0xffff0000, v206
	v_lshlrev_b32_e32 v132, 16, v207
	v_and_b32_e32 v133, 0xffff0000, v207
	v_lshlrev_b32_e32 v240, 16, v208
	v_and_b32_e32 v241, 0xffff0000, v208
	v_lshlrev_b32_e32 v242, 16, v209
	v_and_b32_e32 v243, 0xffff0000, v209
	v_lshlrev_b32_e32 v244, 16, v210
	v_and_b32_e32 v245, 0xffff0000, v210
	v_lshlrev_b32_e32 v246, 16, v211
	v_and_b32_e32 v247, 0xffff0000, v211
	v_lshlrev_b32_e32 v248, 16, v212
	v_and_b32_e32 v249, 0xffff0000, v212
	v_lshlrev_b32_e32 v250, 16, v213
	v_and_b32_e32 v251, 0xffff0000, v213
	v_lshlrev_b32_e32 v32, 16, v214
	v_and_b32_e32 v33, 0xffff0000, v214
	v_lshlrev_b32_e32 v34, 16, v215
	v_and_b32_e32 v35, 0xffff0000, v215
	v_lshlrev_b32_e32 v36, 16, v216
	v_and_b32_e32 v37, 0xffff0000, v216
	v_lshlrev_b32_e32 v38, 16, v217
	v_and_b32_e32 v39, 0xffff0000, v217
	v_lshlrev_b32_e32 v20, 16, v218
	v_and_b32_e32 v21, 0xffff0000, v218
	v_lshlrev_b32_e32 v22, 16, v219
	v_and_b32_e32 v23, 0xffff0000, v219
	v_pk_add_f32 v[228:229], v[126:127], v[128:129]
	v_pk_add_f32 v[228:229], v[228:229], v[130:131]
	v_pk_add_f32 v[228:229], v[228:229], v[132:133]
	v_pk_add_f32 v[228:229], v[228:229], v[240:241]
	v_pk_add_f32 v[228:229], v[228:229], v[242:243]
	v_pk_add_f32 v[228:229], v[228:229], v[244:245]
	v_pk_add_f32 v[228:229], v[228:229], v[246:247]
	v_pk_add_f32 v[228:229], v[228:229], v[248:249]
	v_pk_add_f32 v[228:229], v[228:229], v[250:251]
	v_pk_add_f32 v[228:229], v[228:229], v[32:33]
	v_pk_add_f32 v[228:229], v[228:229], v[34:35]
	v_pk_add_f32 v[228:229], v[228:229], v[36:37]
	v_pk_add_f32 v[228:229], v[228:229], v[38:39]
	v_pk_add_f32 v[228:229], v[228:229], v[20:21]
	v_pk_add_f32 v[228:229], v[228:229], v[22:23]
	v_add_f32_e32 v228, v228, v229
	s_nop 1
	v_add_f32_dpp v228, v228, v228 quad_perm:[1,0,3,2] row_mask:0xf bank_mask:0xf bound_ctrl:1
	s_nop 1
	v_add_f32_dpp v228, v228, v228 quad_perm:[2,3,0,1] row_mask:0xf bank_mask:0xf bound_ctrl:1
	s_nop 1
	v_add_f32_dpp v228, v228, v228 row_half_mirror row_mask:0xf bank_mask:0xf bound_ctrl:1
	s_nop 1
	v_add_f32_dpp v228, v228, v228 row_mirror row_mask:0xf bank_mask:0xf bound_ctrl:1
	v_mov_b32_e32 v2, v228
	s_nop 1
	v_permlane16_swap_b32 v228, v2
	s_nop 0
	v_add_f32_e32 v228, v228, v2
	v_mov_b32_e32 v2, v228
	s_nop 1
	v_permlane32_swap_b32 v228, v2
	s_nop 0
	v_add_f32_e32 v228, v228, v2
	v_mul_f32_e32 v134, 0x3a000000, v228
	v_pk_add_f32 v[126:127], v[126:127], v[134:135] op_sel_hi:[1,0] neg_lo:[0,1] neg_hi:[0,1]
	v_pk_add_f32 v[128:129], v[128:129], v[134:135] op_sel_hi:[1,0] neg_lo:[0,1] neg_hi:[0,1]
	v_pk_add_f32 v[130:131], v[130:131], v[134:135] op_sel_hi:[1,0] neg_lo:[0,1] neg_hi:[0,1]
	v_pk_add_f32 v[132:133], v[132:133], v[134:135] op_sel_hi:[1,0] neg_lo:[0,1] neg_hi:[0,1]
	v_pk_add_f32 v[240:241], v[240:241], v[134:135] op_sel_hi:[1,0] neg_lo:[0,1] neg_hi:[0,1]
	v_pk_add_f32 v[242:243], v[242:243], v[134:135] op_sel_hi:[1,0] neg_lo:[0,1] neg_hi:[0,1]
	v_pk_add_f32 v[244:245], v[244:245], v[134:135] op_sel_hi:[1,0] neg_lo:[0,1] neg_hi:[0,1]
	v_pk_add_f32 v[246:247], v[246:247], v[134:135] op_sel_hi:[1,0] neg_lo:[0,1] neg_hi:[0,1]
	v_pk_add_f32 v[248:249], v[248:249], v[134:135] op_sel_hi:[1,0] neg_lo:[0,1] neg_hi:[0,1]
	v_pk_add_f32 v[250:251], v[250:251], v[134:135] op_sel_hi:[1,0] neg_lo:[0,1] neg_hi:[0,1]
	v_pk_add_f32 v[32:33], v[32:33], v[134:135] op_sel_hi:[1,0] neg_lo:[0,1] neg_hi:[0,1]
	v_pk_add_f32 v[34:35], v[34:35], v[134:135] op_sel_hi:[1,0] neg_lo:[0,1] neg_hi:[0,1]
	v_pk_add_f32 v[36:37], v[36:37], v[134:135] op_sel_hi:[1,0] neg_lo:[0,1] neg_hi:[0,1]
	v_pk_add_f32 v[38:39], v[38:39], v[134:135] op_sel_hi:[1,0] neg_lo:[0,1] neg_hi:[0,1]
	v_pk_add_f32 v[20:21], v[20:21], v[134:135] op_sel_hi:[1,0] neg_lo:[0,1] neg_hi:[0,1]
	v_pk_add_f32 v[22:23], v[22:23], v[134:135] op_sel_hi:[1,0] neg_lo:[0,1] neg_hi:[0,1]
	v_pk_mul_f32 v[228:229], v[126:127], v[126:127]
	v_pk_fma_f32 v[228:229], v[128:129], v[128:129], v[228:229]
	v_pk_fma_f32 v[228:229], v[130:131], v[130:131], v[228:229]
	v_pk_fma_f32 v[228:229], v[132:133], v[132:133], v[228:229]
	v_pk_fma_f32 v[228:229], v[240:241], v[240:241], v[228:229]
	v_pk_fma_f32 v[228:229], v[242:243], v[242:243], v[228:229]
	v_pk_fma_f32 v[228:229], v[244:245], v[244:245], v[228:229]
	v_pk_fma_f32 v[228:229], v[246:247], v[246:247], v[228:229]
	v_pk_fma_f32 v[228:229], v[248:249], v[248:249], v[228:229]
	v_pk_fma_f32 v[228:229], v[250:251], v[250:251], v[228:229]
	v_pk_fma_f32 v[228:229], v[32:33], v[32:33], v[228:229]
	v_pk_fma_f32 v[228:229], v[34:35], v[34:35], v[228:229]
	v_pk_fma_f32 v[228:229], v[36:37], v[36:37], v[228:229]
	v_pk_fma_f32 v[228:229], v[38:39], v[38:39], v[228:229]
	v_pk_fma_f32 v[228:229], v[20:21], v[20:21], v[228:229]
	v_pk_fma_f32 v[228:229], v[22:23], v[22:23], v[228:229]
	v_add_f32_e32 v228, v228, v229
	s_nop 1
	v_add_f32_dpp v228, v228, v228 quad_perm:[1,0,3,2] row_mask:0xf bank_mask:0xf bound_ctrl:1
	s_nop 1
	v_add_f32_dpp v228, v228, v228 quad_perm:[2,3,0,1] row_mask:0xf bank_mask:0xf bound_ctrl:1
	s_nop 1
	v_add_f32_dpp v228, v228, v228 row_half_mirror row_mask:0xf bank_mask:0xf bound_ctrl:1
	s_nop 1
	v_add_f32_dpp v228, v228, v228 row_mirror row_mask:0xf bank_mask:0xf bound_ctrl:1
	v_mov_b32_e32 v2, v228
	s_nop 1
	v_permlane16_swap_b32 v228, v2
	s_nop 0
	v_add_f32_e32 v228, v228, v2
	v_mov_b32_e32 v2, v228
	s_nop 1
	v_permlane32_swap_b32 v228, v2
	s_nop 0
	v_add_f32_e32 v228, v228, v2
	v_mul_f32_e32 v0, 0x3a000000, v228
	v_add_f32_e32 v0, 0x3727c5ac, v0
	v_rsq_f32_e32 v0, v0
	s_nop 0
	v_pk_mul_f32 v[228:229], v[140:141], v[0:1] op_sel_hi:[1,0]
	v_pk_fma_f32 v[126:127], v[126:127], v[228:229], v[172:173]
	v_pk_mul_f32 v[228:229], v[142:143], v[0:1] op_sel_hi:[1,0]
	v_pk_fma_f32 v[128:129], v[128:129], v[228:229], v[174:175]
	v_pk_mul_f32 v[228:229], v[144:145], v[0:1] op_sel_hi:[1,0]
	v_pk_fma_f32 v[130:131], v[130:131], v[228:229], v[176:177]
	v_pk_mul_f32 v[228:229], v[146:147], v[0:1] op_sel_hi:[1,0]
	v_pk_fma_f32 v[132:133], v[132:133], v[228:229], v[178:179]
	v_pk_mul_f32 v[228:229], v[148:149], v[0:1] op_sel_hi:[1,0]
	v_pk_fma_f32 v[240:241], v[240:241], v[228:229], v[180:181]
	v_pk_mul_f32 v[228:229], v[150:151], v[0:1] op_sel_hi:[1,0]
	v_pk_fma_f32 v[242:243], v[242:243], v[228:229], v[182:183]
	v_pk_mul_f32 v[228:229], v[152:153], v[0:1] op_sel_hi:[1,0]
	v_pk_fma_f32 v[244:245], v[244:245], v[228:229], v[184:185]
	v_pk_mul_f32 v[228:229], v[154:155], v[0:1] op_sel_hi:[1,0]
	v_pk_fma_f32 v[246:247], v[246:247], v[228:229], v[186:187]
	v_pk_mul_f32 v[228:229], v[156:157], v[0:1] op_sel_hi:[1,0]
	v_pk_fma_f32 v[248:249], v[248:249], v[228:229], v[188:189]
	v_pk_mul_f32 v[228:229], v[158:159], v[0:1] op_sel_hi:[1,0]
	v_pk_fma_f32 v[250:251], v[250:251], v[228:229], v[190:191]
	v_pk_mul_f32 v[228:229], v[160:161], v[0:1] op_sel_hi:[1,0]
	v_pk_fma_f32 v[32:33], v[32:33], v[228:229], v[192:193]
	v_pk_mul_f32 v[228:229], v[162:163], v[0:1] op_sel_hi:[1,0]
	v_pk_fma_f32 v[34:35], v[34:35], v[228:229], v[194:195]
	v_pk_mul_f32 v[228:229], v[164:165], v[0:1] op_sel_hi:[1,0]
	v_pk_fma_f32 v[36:37], v[36:37], v[228:229], v[196:197]
	v_pk_mul_f32 v[228:229], v[166:167], v[0:1] op_sel_hi:[1,0]
	v_pk_fma_f32 v[38:39], v[38:39], v[228:229], v[198:199]
	v_pk_mul_f32 v[228:229], v[168:169], v[0:1] op_sel_hi:[1,0]
	v_pk_fma_f32 v[20:21], v[20:21], v[228:229], v[200:201]
	v_pk_mul_f32 v[228:229], v[170:171], v[0:1] op_sel_hi:[1,0]
	v_pk_fma_f32 v[22:23], v[22:23], v[228:229], v[202:203]
	v_cvt_pk_bf16_f32 v204, v126, v127
	v_cvt_pk_bf16_f32 v205, v128, v129
	v_cvt_pk_bf16_f32 v206, v130, v131
	v_cvt_pk_bf16_f32 v207, v132, v133
	v_cvt_pk_bf16_f32 v208, v240, v241
	v_cvt_pk_bf16_f32 v209, v242, v243
	v_cvt_pk_bf16_f32 v210, v244, v245
	v_cvt_pk_bf16_f32 v211, v246, v247
	v_cvt_pk_bf16_f32 v212, v248, v249
	v_cvt_pk_bf16_f32 v213, v250, v251
	v_cvt_pk_bf16_f32 v214, v32, v33
	v_cvt_pk_bf16_f32 v215, v34, v35
	v_cvt_pk_bf16_f32 v216, v36, v37
	v_cvt_pk_bf16_f32 v217, v38, v39
	v_cvt_pk_bf16_f32 v218, v20, v21
	v_cvt_pk_bf16_f32 v219, v22, v23
	global_store_dwordx2 v1, v[204:205], s[90:91] offset:0
	global_store_dwordx2 v1, v[206:207], s[90:91] offset:512
	global_store_dwordx2 v1, v[208:209], s[90:91] offset:1024
	global_store_dwordx2 v1, v[210:211], s[90:91] offset:1536
	global_store_dwordx2 v1, v[212:213], s[90:91] offset:2048
	global_store_dwordx2 v1, v[214:215], s[90:91] offset:2560
	global_store_dwordx2 v1, v[216:217], s[90:91] offset:3072
	global_store_dwordx2 v1, v[218:219], s[90:91] offset:3584
	s_add_u32 s90, s90, 0x800000
	s_addc_u32 s91, s91, 0

.LBB0_2203:
	s_cmp_lt_i32 s30, 16
	s_cselect_b64 s[8:9], -1, 0
	s_and_b64 s[10:11], s[8:9], s[6:7]
	s_andn2_b64 vcc, exec, s[10:11]
	s_cbranch_vccnz .LBB0_2215
	s_load_dwordx4 s[12:15], s[0:1], 0x130
	v_lshl_add_u32 v32, s2, 3, v230
	s_movk_i32 s3, 0x2000
	v_cmp_gt_i32_e32 vcc, s3, v32
	s_and_saveexec_b64 s[16:17], vcc
	s_cbranch_execz .LBB0_2209
	s_load_dwordx4 s[60:63], s[0:1], 0x130
	v_lshl_add_u32 v2, s2, 3, v230
	v_lshlrev_b32_e32 v137, 4, v136
	v_lshlrev_b32_e32 v1, 3, v136
	v_lshl_add_u32 v1, v2, 12, v1
	v_add_u32_e32 v4, 0x1000, v137
	s_add_u32 s88, s28, 0xe600000
	s_addc_u32 s89, s29, 0
	s_add_u32 s90, s28, 0xc500000
	s_addc_u32 s91, s29, 0
	global_load_dwordx2 v[204:205], v1, s[88:89] offset:0 nt
	global_load_dwordx2 v[206:207], v1, s[88:89] offset:512 nt
	global_load_dwordx2 v[208:209], v1, s[88:89] offset:1024 nt
	global_load_dwordx2 v[210:211], v1, s[88:89] offset:1536 nt
	global_load_dwordx2 v[212:213], v1, s[88:89] offset:2048 nt
	global_load_dwordx2 v[214:215], v1, s[88:89] offset:2560 nt
	global_load_dwordx2 v[216:217], v1, s[88:89] offset:3072 nt
	global_load_dwordx2 v[218:219], v1, s[88:89] offset:3584 nt
	s_add_u32 s88, s88, 0x800000
	s_addc_u32 s89, s89, 0
	s_waitcnt lgkmcnt(0)
	global_load_dwordx4 v[140:143], v137, s[60:61] offset:0
	global_load_dwordx4 v[144:147], v137, s[60:61] offset:1024
	global_load_dwordx4 v[148:151], v137, s[60:61] offset:2048
	global_load_dwordx4 v[152:155], v137, s[60:61] offset:3072
	global_load_dwordx4 v[156:159], v4, s[60:61] offset:0
	global_load_dwordx4 v[160:163], v4, s[60:61] offset:1024
	global_load_dwordx4 v[164:167], v4, s[60:61] offset:2048
	global_load_dwordx4 v[168:171], v4, s[60:61] offset:3072
	global_load_dwordx4 v[172:175], v137, s[62:63] offset:0
	global_load_dwordx4 v[176:179], v137, s[62:63] offset:1024
	global_load_dwordx4 v[180:183], v137, s[62:63] offset:2048
	global_load_dwordx4 v[184:187], v137, s[62:63] offset:3072
	global_load_dwordx4 v[188:191], v4, s[62:63] offset:0
	global_load_dwordx4 v[192:195], v4, s[62:63] offset:1024
	global_load_dwordx4 v[196:199], v4, s[62:63] offset:2048
	global_load_dwordx4 v[200:203], v4, s[62:63] offset:3072
	global_load_dwordx2 v[110:111], v1, s[88:89] offset:0 nt
	global_load_dwordx2 v[112:113], v1, s[88:89] offset:512 nt
	global_load_dwordx2 v[114:115], v1, s[88:89] offset:1024 nt
	global_load_dwordx2 v[116:117], v1, s[88:89] offset:1536 nt
	global_load_dwordx2 v[118:119], v1, s[88:89] offset:2048 nt
	global_load_dwordx2 v[120:121], v1, s[88:89] offset:2560 nt
	global_load_dwordx2 v[122:123], v1, s[88:89] offset:3072 nt
	global_load_dwordx2 v[124:125], v1, s[88:89] offset:3584 nt
	s_add_u32 s88, s88, 0x800000
	s_addc_u32 s89, s89, 0
	global_load_dwordx2 v[24:25], v1, s[88:89] offset:0 nt
	global_load_dwordx2 v[26:27], v1, s[88:89] offset:512 nt
	global_load_dwordx2 v[8:9], v1, s[88:89] offset:1024 nt
	global_load_dwordx2 v[10:11], v1, s[88:89] offset:1536 nt
	global_load_dwordx2 v[220:221], v1, s[88:89] offset:2048 nt
	global_load_dwordx2 v[222:223], v1, s[88:89] offset:2560 nt
	global_load_dwordx2 v[224:225], v1, s[88:89] offset:3072 nt
	global_load_dwordx2 v[226:227], v1, s[88:89] offset:3584 nt
	s_add_u32 s88, s88, 0x800000
	s_addc_u32 s89, s89, 0
	s_waitcnt vmcnt(32)
	v_lshlrev_b32_e32 v126, 16, v204
	v_and_b32_e32 v127, 0xffff0000, v204
	v_lshlrev_b32_e32 v128, 16, v205
	v_and_b32_e32 v129, 0xffff0000, v205
	v_lshlrev_b32_e32 v130, 16, v206
	v_and_b32_e32 v131, 0xffff0000, v206
	v_lshlrev_b32_e32 v132, 16, v207
	v_and_b32_e32 v133, 0xffff0000, v207
	v_lshlrev_b32_e32 v240, 16, v208
	v_and_b32_e32 v241, 0xffff0000, v208
	v_lshlrev_b32_e32 v242, 16, v209
	v_and_b32_e32 v243, 0xffff0000, v209
	v_lshlrev_b32_e32 v244, 16, v210
	v_and_b32_e32 v245, 0xffff0000, v210
	v_lshlrev_b32_e32 v246, 16, v211
	v_and_b32_e32 v247, 0xffff0000, v211
	v_lshlrev_b32_e32 v248, 16, v212
	v_and_b32_e32 v249, 0xffff0000, v212
	v_lshlrev_b32_e32 v250, 16, v213
	v_and_b32_e32 v251, 0xffff0000, v213
	v_lshlrev_b32_e32 v32, 16, v214
	v_and_b32_e32 v33, 0xffff0000, v214
	v_lshlrev_b32_e32 v34, 16, v215
	v_and_b32_e32 v35, 0xffff0000, v215
	v_lshlrev_b32_e32 v36, 16, v216
	v_and_b32_e32 v37, 0xffff0000, v216
	v_lshlrev_b32_e32 v38, 16, v217
	v_and_b32_e32 v39, 0xffff0000, v217
	v_lshlrev_b32_e32 v20, 16, v218
	v_and_b32_e32 v21, 0xffff0000, v218
	v_lshlrev_b32_e32 v22, 16, v219
	v_and_b32_e32 v23, 0xffff0000, v219
	v_pk_add_f32 v[228:229], v[126:127], v[128:129]
	v_pk_add_f32 v[228:229], v[228:229], v[130:131]
	v_pk_add_f32 v[228:229], v[228:229], v[132:133]
	v_pk_add_f32 v[228:229], v[228:229], v[240:241]
	v_pk_add_f32 v[228:229], v[228:229], v[242:243]
	v_pk_add_f32 v[228:229], v[228:229], v[244:245]
	v_pk_add_f32 v[228:229], v[228:229], v[246:247]
	v_pk_add_f32 v[228:229], v[228:229], v[248:249]
	v_pk_add_f32 v[228:229], v[228:229], v[250:251]
	v_pk_add_f32 v[228:229], v[228:229], v[32:33]
	v_pk_add_f32 v[228:229], v[228:229], v[34:35]
	v_pk_add_f32 v[228:229], v[228:229], v[36:37]
	v_pk_add_f32 v[228:229], v[228:229], v[38:39]
	v_pk_add_f32 v[228:229], v[228:229], v[20:21]
	v_pk_add_f32 v[228:229], v[228:229], v[22:23]
	v_add_f32_e32 v228, v228, v229
	s_nop 1
	v_add_f32_dpp v228, v228, v228 quad_perm:[1,0,3,2] row_mask:0xf bank_mask:0xf bound_ctrl:1
	s_nop 1
	v_add_f32_dpp v228, v228, v228 quad_perm:[2,3,0,1] row_mask:0xf bank_mask:0xf bound_ctrl:1
	s_nop 1
	v_add_f32_dpp v228, v228, v228 row_half_mirror row_mask:0xf bank_mask:0xf bound_ctrl:1
	s_nop 1
	v_add_f32_dpp v228, v228, v228 row_mirror row_mask:0xf bank_mask:0xf bound_ctrl:1
	v_mov_b32_e32 v2, v228
	s_nop 1
	v_permlane16_swap_b32 v228, v2
	s_nop 0
	v_add_f32_e32 v228, v228, v2
	v_mov_b32_e32 v2, v228
	s_nop 1
	v_permlane32_swap_b32 v228, v2
	s_nop 0
	v_add_f32_e32 v228, v228, v2
	v_mul_f32_e32 v134, 0x3a000000, v228
	v_pk_add_f32 v[126:127], v[126:127], v[134:135] op_sel_hi:[1,0] neg_lo:[0,1] neg_hi:[0,1]
	v_pk_add_f32 v[128:129], v[128:129], v[134:135] op_sel_hi:[1,0] neg_lo:[0,1] neg_hi:[0,1]
	v_pk_add_f32 v[130:131], v[130:131], v[134:135] op_sel_hi:[1,0] neg_lo:[0,1] neg_hi:[0,1]
	v_pk_add_f32 v[132:133], v[132:133], v[134:135] op_sel_hi:[1,0] neg_lo:[0,1] neg_hi:[0,1]
	v_pk_add_f32 v[240:241], v[240:241], v[134:135] op_sel_hi:[1,0] neg_lo:[0,1] neg_hi:[0,1]
	v_pk_add_f32 v[242:243], v[242:243], v[134:135] op_sel_hi:[1,0] neg_lo:[0,1] neg_hi:[0,1]
	v_pk_add_f32 v[244:245], v[244:245], v[134:135] op_sel_hi:[1,0] neg_lo:[0,1] neg_hi:[0,1]
	v_pk_add_f32 v[246:247], v[246:247], v[134:135] op_sel_hi:[1,0] neg_lo:[0,1] neg_hi:[0,1]
	v_pk_add_f32 v[248:249], v[248:249], v[134:135] op_sel_hi:[1,0] neg_lo:[0,1] neg_hi:[0,1]
	v_pk_add_f32 v[250:251], v[250:251], v[134:135] op_sel_hi:[1,0] neg_lo:[0,1] neg_hi:[0,1]
	v_pk_add_f32 v[32:33], v[32:33], v[134:135] op_sel_hi:[1,0] neg_lo:[0,1] neg_hi:[0,1]
	v_pk_add_f32 v[34:35], v[34:35], v[134:135] op_sel_hi:[1,0] neg_lo:[0,1] neg_hi:[0,1]
	v_pk_add_f32 v[36:37], v[36:37], v[134:135] op_sel_hi:[1,0] neg_lo:[0,1] neg_hi:[0,1]
	v_pk_add_f32 v[38:39], v[38:39], v[134:135] op_sel_hi:[1,0] neg_lo:[0,1] neg_hi:[0,1]
	v_pk_add_f32 v[20:21], v[20:21], v[134:135] op_sel_hi:[1,0] neg_lo:[0,1] neg_hi:[0,1]
	v_pk_add_f32 v[22:23], v[22:23], v[134:135] op_sel_hi:[1,0] neg_lo:[0,1] neg_hi:[0,1]
	v_pk_mul_f32 v[228:229], v[126:127], v[126:127]
	v_pk_fma_f32 v[228:229], v[128:129], v[128:129], v[228:229]
	v_pk_fma_f32 v[228:229], v[130:131], v[130:131], v[228:229]
	v_pk_fma_f32 v[228:229], v[132:133], v[132:133], v[228:229]
	v_pk_fma_f32 v[228:229], v[240:241], v[240:241], v[228:229]
	v_pk_fma_f32 v[228:229], v[242:243], v[242:243], v[228:229]
	v_pk_fma_f32 v[228:229], v[244:245], v[244:245], v[228:229]
	v_pk_fma_f32 v[228:229], v[246:247], v[246:247], v[228:229]
	v_pk_fma_f32 v[228:229], v[248:249], v[248:249], v[228:229]
	v_pk_fma_f32 v[228:229], v[250:251], v[250:251], v[228:229]
	v_pk_fma_f32 v[228:229], v[32:33], v[32:33], v[228:229]
	v_pk_fma_f32 v[228:229], v[34:35], v[34:35], v[228:229]
	v_pk_fma_f32 v[228:229], v[36:37], v[36:37], v[228:229]
	v_pk_fma_f32 v[228:229], v[38:39], v[38:39], v[228:229]
	v_pk_fma_f32 v[228:229], v[20:21], v[20:21], v[228:229]
	v_pk_fma_f32 v[228:229], v[22:23], v[22:23], v[228:229]
	v_add_f32_e32 v228, v228, v229
	s_nop 1
	v_add_f32_dpp v228, v228, v228 quad_perm:[1,0,3,2] row_mask:0xf bank_mask:0xf bound_ctrl:1
	s_nop 1
	v_add_f32_dpp v228, v228, v228 quad_perm:[2,3,0,1] row_mask:0xf bank_mask:0xf bound_ctrl:1
	s_nop 1
	v_add_f32_dpp v228, v228, v228 row_half_mirror row_mask:0xf bank_mask:0xf bound_ctrl:1
	s_nop 1
	v_add_f32_dpp v228, v228, v228 row_mirror row_mask:0xf bank_mask:0xf bound_ctrl:1
	v_mov_b32_e32 v2, v228
	s_nop 1
	v_permlane16_swap_b32 v228, v2
	s_nop 0
	v_add_f32_e32 v228, v228, v2
	v_mov_b32_e32 v2, v228
	s_nop 1
	v_permlane32_swap_b32 v228, v2
	s_nop 0
	v_add_f32_e32 v228, v228, v2
	v_mul_f32_e32 v0, 0x3a000000, v228
	v_add_f32_e32 v0, 0x3727c5ac, v0
	v_rsq_f32_e32 v0, v0
	s_waitcnt vmcnt(16)
	v_pk_mul_f32 v[228:229], v[140:141], v[0:1] op_sel_hi:[1,0]
	v_pk_fma_f32 v[126:127], v[126:127], v[228:229], v[172:173]
	v_pk_mul_f32 v[228:229], v[142:143], v[0:1] op_sel_hi:[1,0]
	v_pk_fma_f32 v[128:129], v[128:129], v[228:229], v[174:175]
	v_pk_mul_f32 v[228:229], v[144:145], v[0:1] op_sel_hi:[1,0]
	v_pk_fma_f32 v[130:131], v[130:131], v[228:229], v[176:177]
	v_pk_mul_f32 v[228:229], v[146:147], v[0:1] op_sel_hi:[1,0]
	v_pk_fma_f32 v[132:133], v[132:133], v[228:229], v[178:179]
	v_pk_mul_f32 v[228:229], v[148:149], v[0:1] op_sel_hi:[1,0]
	v_pk_fma_f32 v[240:241], v[240:241], v[228:229], v[180:181]
	v_pk_mul_f32 v[228:229], v[150:151], v[0:1] op_sel_hi:[1,0]
	v_pk_fma_f32 v[242:243], v[242:243], v[228:229], v[182:183]
	v_pk_mul_f32 v[228:229], v[152:153], v[0:1] op_sel_hi:[1,0]
	v_pk_fma_f32 v[244:245], v[244:245], v[228:229], v[184:185]
	v_pk_mul_f32 v[228:229], v[154:155], v[0:1] op_sel_hi:[1,0]
	v_pk_fma_f32 v[246:247], v[246:247], v[228:229], v[186:187]
	v_pk_mul_f32 v[228:229], v[156:157], v[0:1] op_sel_hi:[1,0]
	v_pk_fma_f32 v[248:249], v[248:249], v[228:229], v[188:189]
	v_pk_mul_f32 v[228:229], v[158:159], v[0:1] op_sel_hi:[1,0]
	v_pk_fma_f32 v[250:251], v[250:251], v[228:229], v[190:191]
	v_pk_mul_f32 v[228:229], v[160:161], v[0:1] op_sel_hi:[1,0]
	v_pk_fma_f32 v[32:33], v[32:33], v[228:229], v[192:193]
	v_pk_mul_f32 v[228:229], v[162:163], v[0:1] op_sel_hi:[1,0]
	v_pk_fma_f32 v[34:35], v[34:35], v[228:229], v[194:195]
	v_pk_mul_f32 v[228:229], v[164:165], v[0:1] op_sel_hi:[1,0]
	v_pk_fma_f32 v[36:37], v[36:37], v[228:229], v[196:197]
	v_pk_mul_f32 v[228:229], v[166:167], v[0:1] op_sel_hi:[1,0]
	v_pk_fma_f32 v[38:39], v[38:39], v[228:229], v[198:199]
	v_pk_mul_f32 v[228:229], v[168:169], v[0:1] op_sel_hi:[1,0]
	v_pk_fma_f32 v[20:21], v[20:21], v[228:229], v[200:201]
	v_pk_mul_f32 v[228:229], v[170:171], v[0:1] op_sel_hi:[1,0]
	v_pk_fma_f32 v[22:23], v[22:23], v[228:229], v[202:203]
	v_cvt_pk_bf16_f32 v204, v126, v127
	v_cvt_pk_bf16_f32 v205, v128, v129
	v_cvt_pk_bf16_f32 v206, v130, v131
	v_cvt_pk_bf16_f32 v207, v132, v133
	v_cvt_pk_bf16_f32 v208, v240, v241
	v_cvt_pk_bf16_f32 v209, v242, v243
	v_cvt_pk_bf16_f32 v210, v244, v245
	v_cvt_pk_bf16_f32 v211, v246, v247
	v_cvt_pk_bf16_f32 v212, v248, v249
	v_cvt_pk_bf16_f32 v213, v250, v251
	v_cvt_pk_bf16_f32 v214, v32, v33
	v_cvt_pk_bf16_f32 v215, v34, v35
	v_cvt_pk_bf16_f32 v216, v36, v37
	v_cvt_pk_bf16_f32 v217, v38, v39
	v_cvt_pk_bf16_f32 v218, v20, v21
	v_cvt_pk_bf16_f32 v219, v22, v23
	global_store_dwordx2 v1, v[204:205], s[90:91] offset:0
	global_store_dwordx2 v1, v[206:207], s[90:91] offset:512
	global_store_dwordx2 v1, v[208:209], s[90:91] offset:1024
	global_store_dwordx2 v1, v[210:211], s[90:91] offset:1536
	global_store_dwordx2 v1, v[212:213], s[90:91] offset:2048
	global_store_dwordx2 v1, v[214:215], s[90:91] offset:2560
	global_store_dwordx2 v1, v[216:217], s[90:91] offset:3072
	global_store_dwordx2 v1, v[218:219], s[90:91] offset:3584
	s_add_u32 s90, s90, 0x800000
	s_addc_u32 s91, s91, 0
	global_load_dwordx2 v[204:205], v1, s[88:89] offset:0 nt
	global_load_dwordx2 v[206:207], v1, s[88:89] offset:512 nt
	global_load_dwordx2 v[208:209], v1, s[88:89] offset:1024 nt
	global_load_dwordx2 v[210:211], v1, s[88:89] offset:1536 nt
	global_load_dwordx2 v[212:213], v1, s[88:89] offset:2048 nt
	global_load_dwordx2 v[214:215], v1, s[88:89] offset:2560 nt
	global_load_dwordx2 v[216:217], v1, s[88:89] offset:3072 nt
	global_load_dwordx2 v[218:219], v1, s[88:89] offset:3584 nt
	s_add_u32 s88, s88, 0x800000
	s_addc_u32 s89, s89, 0
	s_waitcnt vmcnt(24)
	v_lshlrev_b32_e32 v126, 16, v110
	v_and_b32_e32 v127, 0xffff0000, v110
	v_lshlrev_b32_e32 v128, 16, v111
	v_and_b32_e32 v129, 0xffff0000, v111
	v_lshlrev_b32_e32 v130, 16, v112
	v_and_b32_e32 v131, 0xffff0000, v112
	v_lshlrev_b32_e32 v132, 16, v113
	v_and_b32_e32 v133, 0xffff0000, v113
	v_lshlrev_b32_e32 v240, 16, v114
	v_and_b32_e32 v241, 0xffff0000, v114
	v_lshlrev_b32_e32 v242, 16, v115
	v_and_b32_e32 v243, 0xffff0000, v115
	v_lshlrev_b32_e32 v244, 16, v116
	v_and_b32_e32 v245, 0xffff0000, v116
	v_lshlrev_b32_e32 v246, 16, v117
	v_and_b32_e32 v247, 0xffff0000, v117
	v_lshlrev_b32_e32 v248, 16, v118
	v_and_b32_e32 v249, 0xffff0000, v118
	v_lshlrev_b32_e32 v250, 16, v119
	v_and_b32_e32 v251, 0xffff0000, v119
	v_lshlrev_b32_e32 v32, 16, v120
	v_and_b32_e32 v33, 0xffff0000, v120
	v_lshlrev_b32_e32 v34, 16, v121
	v_and_b32_e32 v35, 0xffff0000, v121
	v_lshlrev_b32_e32 v36, 16, v122
	v_and_b32_e32 v37, 0xffff0000, v122
	v_lshlrev_b32_e32 v38, 16, v123
	v_and_b32_e32 v39, 0xffff0000, v123
	v_lshlrev_b32_e32 v20, 16, v124
	v_and_b32_e32 v21, 0xffff0000, v124
	v_lshlrev_b32_e32 v22, 16, v125
	v_and_b32_e32 v23, 0xffff0000, v125
	v_pk_add_f32 v[228:229], v[126:127], v[128:129]
	v_pk_add_f32 v[228:229], v[228:229], v[130:131]
	v_pk_add_f32 v[228:229], v[228:229], v[132:133]
	v_pk_add_f32 v[228:229], v[228:229], v[240:241]
	v_pk_add_f32 v[228:229], v[228:229], v[242:243]
	v_pk_add_f32 v[228:229], v[228:229], v[244:245]
	v_pk_add_f32 v[228:229], v[228:229], v[246:247]
	v_pk_add_f32 v[228:229], v[228:229], v[248:249]
	v_pk_add_f32 v[228:229], v[228:229], v[250:251]
	v_pk_add_f32 v[228:229], v[228:229], v[32:33]
	v_pk_add_f32 v[228:229], v[228:229], v[34:35]
	v_pk_add_f32 v[228:229], v[228:229], v[36:37]
	v_pk_add_f32 v[228:229], v[228:229], v[38:39]
	v_pk_add_f32 v[228:229], v[228:229], v[20:21]
	v_pk_add_f32 v[228:229], v[228:229], v[22:23]
	v_add_f32_e32 v228, v228, v229
	s_nop 1
	v_add_f32_dpp v228, v228, v228 quad_perm:[1,0,3,2] row_mask:0xf bank_mask:0xf bound_ctrl:1
	s_nop 1
	v_add_f32_dpp v228, v228, v228 quad_perm:[2,3,0,1] row_mask:0xf bank_mask:0xf bound_ctrl:1
	s_nop 1
	v_add_f32_dpp v228, v228, v228 row_half_mirror row_mask:0xf bank_mask:0xf bound_ctrl:1
	s_nop 1
	v_add_f32_dpp v228, v228, v228 row_mirror row_mask:0xf bank_mask:0xf bound_ctrl:1
	v_mov_b32_e32 v2, v228
	s_nop 1
	v_permlane16_swap_b32 v228, v2
	s_nop 0
	v_add_f32_e32 v228, v228, v2
	v_mov_b32_e32 v2, v228
	s_nop 1
	v_permlane32_swap_b32 v228, v2
	s_nop 0
	v_add_f32_e32 v228, v228, v2
	v_mul_f32_e32 v134, 0x3a000000, v228
	v_pk_add_f32 v[126:127], v[126:127], v[134:135] op_sel_hi:[1,0] neg_lo:[0,1] neg_hi:[0,1]
	v_pk_add_f32 v[128:129], v[128:129], v[134:135] op_sel_hi:[1,0] neg_lo:[0,1] neg_hi:[0,1]
	v_pk_add_f32 v[130:131], v[130:131], v[134:135] op_sel_hi:[1,0] neg_lo:[0,1] neg_hi:[0,1]
	v_pk_add_f32 v[132:133], v[132:133], v[134:135] op_sel_hi:[1,0] neg_lo:[0,1] neg_hi:[0,1]
	v_pk_add_f32 v[240:241], v[240:241], v[134:135] op_sel_hi:[1,0] neg_lo:[0,1] neg_hi:[0,1]
	v_pk_add_f32 v[242:243], v[242:243], v[134:135] op_sel_hi:[1,0] neg_lo:[0,1] neg_hi:[0,1]
	v_pk_add_f32 v[244:245], v[244:245], v[134:135] op_sel_hi:[1,0] neg_lo:[0,1] neg_hi:[0,1]
	v_pk_add_f32 v[246:247], v[246:247], v[134:135] op_sel_hi:[1,0] neg_lo:[0,1] neg_hi:[0,1]
	v_pk_add_f32 v[248:249], v[248:249], v[134:135] op_sel_hi:[1,0] neg_lo:[0,1] neg_hi:[0,1]
	v_pk_add_f32 v[250:251], v[250:251], v[134:135] op_sel_hi:[1,0] neg_lo:[0,1] neg_hi:[0,1]
	v_pk_add_f32 v[32:33], v[32:33], v[134:135] op_sel_hi:[1,0] neg_lo:[0,1] neg_hi:[0,1]
	v_pk_add_f32 v[34:35], v[34:35], v[134:135] op_sel_hi:[1,0] neg_lo:[0,1] neg_hi:[0,1]
	v_pk_add_f32 v[36:37], v[36:37], v[134:135] op_sel_hi:[1,0] neg_lo:[0,1] neg_hi:[0,1]
	v_pk_add_f32 v[38:39], v[38:39], v[134:135] op_sel_hi:[1,0] neg_lo:[0,1] neg_hi:[0,1]
	v_pk_add_f32 v[20:21], v[20:21], v[134:135] op_sel_hi:[1,0] neg_lo:[0,1] neg_hi:[0,1]
	v_pk_add_f32 v[22:23], v[22:23], v[134:135] op_sel_hi:[1,0] neg_lo:[0,1] neg_hi:[0,1]
	v_pk_mul_f32 v[228:229], v[126:127], v[126:127]
	v_pk_fma_f32 v[228:229], v[128:129], v[128:129], v[228:229]
	v_pk_fma_f32 v[228:229], v[130:131], v[130:131], v[228:229]
	v_pk_fma_f32 v[228:229], v[132:133], v[132:133], v[228:229]
	v_pk_fma_f32 v[228:229], v[240:241], v[240:241], v[228:229]
	v_pk_fma_f32 v[228:229], v[242:243], v[242:243], v[228:229]
	v_pk_fma_f32 v[228:229], v[244:245], v[244:245], v[228:229]
	v_pk_fma_f32 v[228:229], v[246:247], v[246:247], v[228:229]
	v_pk_fma_f32 v[228:229], v[248:249], v[248:249], v[228:229]
	v_pk_fma_f32 v[228:229], v[250:251], v[250:251], v[228:229]
	v_pk_fma_f32 v[228:229], v[32:33], v[32:33], v[228:229]
	v_pk_fma_f32 v[228:229], v[34:35], v[34:35], v[228:229]
	v_pk_fma_f32 v[228:229], v[36:37], v[36:37], v[228:229]
	v_pk_fma_f32 v[228:229], v[38:39], v[38:39], v[228:229]
	v_pk_fma_f32 v[228:229], v[20:21], v[20:21], v[228:229]
	v_pk_fma_f32 v[228:229], v[22:23], v[22:23], v[228:229]
	v_add_f32_e32 v228, v228, v229
	s_nop 1
	v_add_f32_dpp v228, v228, v228 quad_perm:[1,0,3,2] row_mask:0xf bank_mask:0xf bound_ctrl:1
	s_nop 1
	v_add_f32_dpp v228, v228, v228 quad_perm:[2,3,0,1] row_mask:0xf bank_mask:0xf bound_ctrl:1
	s_nop 1
	v_add_f32_dpp v228, v228, v228 row_half_mirror row_mask:0xf bank_mask:0xf bound_ctrl:1
	s_nop 1
	v_add_f32_dpp v228, v228, v228 row_mirror row_mask:0xf bank_mask:0xf bound_ctrl:1
	v_mov_b32_e32 v2, v228
	s_nop 1
	v_permlane16_swap_b32 v228, v2
	s_nop 0
	v_add_f32_e32 v228, v228, v2
	v_mov_b32_e32 v2, v228
	s_nop 1
	v_permlane32_swap_b32 v228, v2
	s_nop 0
	v_add_f32_e32 v228, v228, v2
	v_mul_f32_e32 v0, 0x3a000000, v228
	v_add_f32_e32 v0, 0x3727c5ac, v0
	v_rsq_f32_e32 v0, v0
	s_nop 0
	v_pk_mul_f32 v[228:229], v[140:141], v[0:1] op_sel_hi:[1,0]
	v_pk_fma_f32 v[126:127], v[126:127], v[228:229], v[172:173]
	v_pk_mul_f32 v[228:229], v[142:143], v[0:1] op_sel_hi:[1,0]
	v_pk_fma_f32 v[128:129], v[128:129], v[228:229], v[174:175]
	v_pk_mul_f32 v[228:229], v[144:145], v[0:1] op_sel_hi:[1,0]
	v_pk_fma_f32 v[130:131], v[130:131], v[228:229], v[176:177]
	v_pk_mul_f32 v[228:229], v[146:147], v[0:1] op_sel_hi:[1,0]
	v_pk_fma_f32 v[132:133], v[132:133], v[228:229], v[178:179]
	v_pk_mul_f32 v[228:229], v[148:149], v[0:1] op_sel_hi:[1,0]
	v_pk_fma_f32 v[240:241], v[240:241], v[228:229], v[180:181]
	v_pk_mul_f32 v[228:229], v[150:151], v[0:1] op_sel_hi:[1,0]
	v_pk_fma_f32 v[242:243], v[242:243], v[228:229], v[182:183]
	v_pk_mul_f32 v[228:229], v[152:153], v[0:1] op_sel_hi:[1,0]
	v_pk_fma_f32 v[244:245], v[244:245], v[228:229], v[184:185]
	v_pk_mul_f32 v[228:229], v[154:155], v[0:1] op_sel_hi:[1,0]
	v_pk_fma_f32 v[246:247], v[246:247], v[228:229], v[186:187]
	v_pk_mul_f32 v[228:229], v[156:157], v[0:1] op_sel_hi:[1,0]
	v_pk_fma_f32 v[248:249], v[248:249], v[228:229], v[188:189]
	v_pk_mul_f32 v[228:229], v[158:159], v[0:1] op_sel_hi:[1,0]
	v_pk_fma_f32 v[250:251], v[250:251], v[228:229], v[190:191]
	v_pk_mul_f32 v[228:229], v[160:161], v[0:1] op_sel_hi:[1,0]
	v_pk_fma_f32 v[32:33], v[32:33], v[228:229], v[192:193]
	v_pk_mul_f32 v[228:229], v[162:163], v[0:1] op_sel_hi:[1,0]
	v_pk_fma_f32 v[34:35], v[34:35], v[228:229], v[194:195]
	v_pk_mul_f32 v[228:229], v[164:165], v[0:1] op_sel_hi:[1,0]
	v_pk_fma_f32 v[36:37], v[36:37], v[228:229], v[196:197]
	v_pk_mul_f32 v[228:229], v[166:167], v[0:1] op_sel_hi:[1,0]
	v_pk_fma_f32 v[38:39], v[38:39], v[228:229], v[198:199]
	v_pk_mul_f32 v[228:229], v[168:169], v[0:1] op_sel_hi:[1,0]
	v_pk_fma_f32 v[20:21], v[20:21], v[228:229], v[200:201]
	v_pk_mul_f32 v[228:229], v[170:171], v[0:1] op_sel_hi:[1,0]
	v_pk_fma_f32 v[22:23], v[22:23], v[228:229], v[202:203]
	v_cvt_pk_bf16_f32 v110, v126, v127
	v_cvt_pk_bf16_f32 v111, v128, v129
	v_cvt_pk_bf16_f32 v112, v130, v131
	v_cvt_pk_bf16_f32 v113, v132, v133
	v_cvt_pk_bf16_f32 v114, v240, v241
	v_cvt_pk_bf16_f32 v115, v242, v243
	v_cvt_pk_bf16_f32 v116, v244, v245
	v_cvt_pk_bf16_f32 v117, v246, v247
	v_cvt_pk_bf16_f32 v118, v248, v249
	v_cvt_pk_bf16_f32 v119, v250, v251
	v_cvt_pk_bf16_f32 v120, v32, v33
	v_cvt_pk_bf16_f32 v121, v34, v35
	v_cvt_pk_bf16_f32 v122, v36, v37
	v_cvt_pk_bf16_f32 v123, v38, v39
	v_cvt_pk_bf16_f32 v124, v20, v21
	v_cvt_pk_bf16_f32 v125, v22, v23
	global_store_dwordx2 v1, v[110:111], s[90:91] offset:0
	global_store_dwordx2 v1, v[112:113], s[90:91] offset:512
	global_store_dwordx2 v1, v[114:115], s[90:91] offset:1024
	global_store_dwordx2 v1, v[116:117], s[90:91] offset:1536
	global_store_dwordx2 v1, v[118:119], s[90:91] offset:2048
	global_store_dwordx2 v1, v[120:121], s[90:91] offset:2560
	global_store_dwordx2 v1, v[122:123], s[90:91] offset:3072
	global_store_dwordx2 v1, v[124:125], s[90:91] offset:3584
	s_add_u32 s90, s90, 0x800000
	s_addc_u32 s91, s91, 0
	s_waitcnt vmcnt(24)
	v_lshlrev_b32_e32 v126, 16, v24
	v_and_b32_e32 v127, 0xffff0000, v24
	v_lshlrev_b32_e32 v128, 16, v25
	v_and_b32_e32 v129, 0xffff0000, v25
	v_lshlrev_b32_e32 v130, 16, v26
	v_and_b32_e32 v131, 0xffff0000, v26
	v_lshlrev_b32_e32 v132, 16, v27
	v_and_b32_e32 v133, 0xffff0000, v27
	v_lshlrev_b32_e32 v240, 16, v8
	v_and_b32_e32 v241, 0xffff0000, v8
	v_lshlrev_b32_e32 v242, 16, v9
	v_and_b32_e32 v243, 0xffff0000, v9
	v_lshlrev_b32_e32 v244, 16, v10
	v_and_b32_e32 v245, 0xffff0000, v10
	v_lshlrev_b32_e32 v246, 16, v11
	v_and_b32_e32 v247, 0xffff0000, v11
	v_lshlrev_b32_e32 v248, 16, v220
	v_and_b32_e32 v249, 0xffff0000, v220
	v_lshlrev_b32_e32 v250, 16, v221
	v_and_b32_e32 v251, 0xffff0000, v221
	v_lshlrev_b32_e32 v32, 16, v222
	v_and_b32_e32 v33, 0xffff0000, v222
	v_lshlrev_b32_e32 v34, 16, v223
	v_and_b32_e32 v35, 0xffff0000, v223
	v_lshlrev_b32_e32 v36, 16, v224
	v_and_b32_e32 v37, 0xffff0000, v224
	v_lshlrev_b32_e32 v38, 16, v225
	v_and_b32_e32 v39, 0xffff0000, v225
	v_lshlrev_b32_e32 v20, 16, v226
	v_and_b32_e32 v21, 0xffff0000, v226
	v_lshlrev_b32_e32 v22, 16, v227
	v_and_b32_e32 v23, 0xffff0000, v227
	v_pk_add_f32 v[228:229], v[126:127], v[128:129]
	v_pk_add_f32 v[228:229], v[228:229], v[130:131]
	v_pk_add_f32 v[228:229], v[228:229], v[132:133]
	v_pk_add_f32 v[228:229], v[228:229], v[240:241]
	v_pk_add_f32 v[228:229], v[228:229], v[242:243]
	v_pk_add_f32 v[228:229], v[228:229], v[244:245]
	v_pk_add_f32 v[228:229], v[228:229], v[246:247]
	v_pk_add_f32 v[228:229], v[228:229], v[248:249]
	v_pk_add_f32 v[228:229], v[228:229], v[250:251]
	v_pk_add_f32 v[228:229], v[228:229], v[32:33]
	v_pk_add_f32 v[228:229], v[228:229], v[34:35]
	v_pk_add_f32 v[228:229], v[228:229], v[36:37]
	v_pk_add_f32 v[228:229], v[228:229], v[38:39]
	v_pk_add_f32 v[228:229], v[228:229], v[20:21]
	v_pk_add_f32 v[228:229], v[228:229], v[22:23]
	v_add_f32_e32 v228, v228, v229
	s_nop 1
	v_add_f32_dpp v228, v228, v228 quad_perm:[1,0,3,2] row_mask:0xf bank_mask:0xf bound_ctrl:1
	s_nop 1
	v_add_f32_dpp v228, v228, v228 quad_perm:[2,3,0,1] row_mask:0xf bank_mask:0xf bound_ctrl:1
	s_nop 1
	v_add_f32_dpp v228, v228, v228 row_half_mirror row_mask:0xf bank_mask:0xf bound_ctrl:1
	s_nop 1
	v_add_f32_dpp v228, v228, v228 row_mirror row_mask:0xf bank_mask:0xf bound_ctrl:1
	v_mov_b32_e32 v2, v228
	s_nop 1
	v_permlane16_swap_b32 v228, v2
	s_nop 0
	v_add_f32_e32 v228, v228, v2
	v_mov_b32_e32 v2, v228
	s_nop 1
	v_permlane32_swap_b32 v228, v2
	s_nop 0
	v_add_f32_e32 v228, v228, v2
	v_mul_f32_e32 v134, 0x3a000000, v228
	v_pk_add_f32 v[126:127], v[126:127], v[134:135] op_sel_hi:[1,0] neg_lo:[0,1] neg_hi:[0,1]
	v_pk_add_f32 v[128:129], v[128:129], v[134:135] op_sel_hi:[1,0] neg_lo:[0,1] neg_hi:[0,1]
	v_pk_add_f32 v[130:131], v[130:131], v[134:135] op_sel_hi:[1,0] neg_lo:[0,1] neg_hi:[0,1]
	v_pk_add_f32 v[132:133], v[132:133], v[134:135] op_sel_hi:[1,0] neg_lo:[0,1] neg_hi:[0,1]
	v_pk_add_f32 v[240:241], v[240:241], v[134:135] op_sel_hi:[1,0] neg_lo:[0,1] neg_hi:[0,1]
	v_pk_add_f32 v[242:243], v[242:243], v[134:135] op_sel_hi:[1,0] neg_lo:[0,1] neg_hi:[0,1]
	v_pk_add_f32 v[244:245], v[244:245], v[134:135] op_sel_hi:[1,0] neg_lo:[0,1] neg_hi:[0,1]
	v_pk_add_f32 v[246:247], v[246:247], v[134:135] op_sel_hi:[1,0] neg_lo:[0,1] neg_hi:[0,1]
	v_pk_add_f32 v[248:249], v[248:249], v[134:135] op_sel_hi:[1,0] neg_lo:[0,1] neg_hi:[0,1]
	v_pk_add_f32 v[250:251], v[250:251], v[134:135] op_sel_hi:[1,0] neg_lo:[0,1] neg_hi:[0,1]
	v_pk_add_f32 v[32:33], v[32:33], v[134:135] op_sel_hi:[1,0] neg_lo:[0,1] neg_hi:[0,1]
	v_pk_add_f32 v[34:35], v[34:35], v[134:135] op_sel_hi:[1,0] neg_lo:[0,1] neg_hi:[0,1]
	v_pk_add_f32 v[36:37], v[36:37], v[134:135] op_sel_hi:[1,0] neg_lo:[0,1] neg_hi:[0,1]
	v_pk_add_f32 v[38:39], v[38:39], v[134:135] op_sel_hi:[1,0] neg_lo:[0,1] neg_hi:[0,1]
	v_pk_add_f32 v[20:21], v[20:21], v[134:135] op_sel_hi:[1,0] neg_lo:[0,1] neg_hi:[0,1]
	v_pk_add_f32 v[22:23], v[22:23], v[134:135] op_sel_hi:[1,0] neg_lo:[0,1] neg_hi:[0,1]
	v_pk_mul_f32 v[228:229], v[126:127], v[126:127]
	v_pk_fma_f32 v[228:229], v[128:129], v[128:129], v[228:229]
	v_pk_fma_f32 v[228:229], v[130:131], v[130:131], v[228:229]
	v_pk_fma_f32 v[228:229], v[132:133], v[132:133], v[228:229]
	v_pk_fma_f32 v[228:229], v[240:241], v[240:241], v[228:229]
	v_pk_fma_f32 v[228:229], v[242:243], v[242:243], v[228:229]
	v_pk_fma_f32 v[228:229], v[244:245], v[244:245], v[228:229]
	v_pk_fma_f32 v[228:229], v[246:247], v[246:247], v[228:229]
	v_pk_fma_f32 v[228:229], v[248:249], v[248:249], v[228:229]
	v_pk_fma_f32 v[228:229], v[250:251], v[250:251], v[228:229]
	v_pk_fma_f32 v[228:229], v[32:33], v[32:33], v[228:229]
	v_pk_fma_f32 v[228:229], v[34:35], v[34:35], v[228:229]
	v_pk_fma_f32 v[228:229], v[36:37], v[36:37], v[228:229]
	v_pk_fma_f32 v[228:229], v[38:39], v[38:39], v[228:229]
	v_pk_fma_f32 v[228:229], v[20:21], v[20:21], v[228:229]
	v_pk_fma_f32 v[228:229], v[22:23], v[22:23], v[228:229]
	v_add_f32_e32 v228, v228, v229
	s_nop 1
	v_add_f32_dpp v228, v228, v228 quad_perm:[1,0,3,2] row_mask:0xf bank_mask:0xf bound_ctrl:1
	s_nop 1
	v_add_f32_dpp v228, v228, v228 quad_perm:[2,3,0,1] row_mask:0xf bank_mask:0xf bound_ctrl:1
	s_nop 1
	v_add_f32_dpp v228, v228, v228 row_half_mirror row_mask:0xf bank_mask:0xf bound_ctrl:1
	s_nop 1
	v_add_f32_dpp v228, v228, v228 row_mirror row_mask:0xf bank_mask:0xf bound_ctrl:1
	v_mov_b32_e32 v2, v228
	s_nop 1
	v_permlane16_swap_b32 v228, v2
	s_nop 0
	v_add_f32_e32 v228, v228, v2
	v_mov_b32_e32 v2, v228
	s_nop 1
	v_permlane32_swap_b32 v228, v2
	s_nop 0
	v_add_f32_e32 v228, v228, v2
	v_mul_f32_e32 v0, 0x3a000000, v228
	v_add_f32_e32 v0, 0x3727c5ac, v0
	v_rsq_f32_e32 v0, v0
	s_nop 0
	v_pk_mul_f32 v[228:229], v[140:141], v[0:1] op_sel_hi:[1,0]
	v_pk_fma_f32 v[126:127], v[126:127], v[228:229], v[172:173]
	v_pk_mul_f32 v[228:229], v[142:143], v[0:1] op_sel_hi:[1,0]
	v_pk_fma_f32 v[128:129], v[128:129], v[228:229], v[174:175]
	v_pk_mul_f32 v[228:229], v[144:145], v[0:1] op_sel_hi:[1,0]
	v_pk_fma_f32 v[130:131], v[130:131], v[228:229], v[176:177]
	v_pk_mul_f32 v[228:229], v[146:147], v[0:1] op_sel_hi:[1,0]
	v_pk_fma_f32 v[132:133], v[132:133], v[228:229], v[178:179]
	v_pk_mul_f32 v[228:229], v[148:149], v[0:1] op_sel_hi:[1,0]
	v_pk_fma_f32 v[240:241], v[240:241], v[228:229], v[180:181]
	v_pk_mul_f32 v[228:229], v[150:151], v[0:1] op_sel_hi:[1,0]
	v_pk_fma_f32 v[242:243], v[242:243], v[228:229], v[182:183]
	v_pk_mul_f32 v[228:229], v[152:153], v[0:1] op_sel_hi:[1,0]
	v_pk_fma_f32 v[244:245], v[244:245], v[228:229], v[184:185]
	v_pk_mul_f32 v[228:229], v[154:155], v[0:1] op_sel_hi:[1,0]
	v_pk_fma_f32 v[246:247], v[246:247], v[228:229], v[186:187]
	v_pk_mul_f32 v[228:229], v[156:157], v[0:1] op_sel_hi:[1,0]
	v_pk_fma_f32 v[248:249], v[248:249], v[228:229], v[188:189]
	v_pk_mul_f32 v[228:229], v[158:159], v[0:1] op_sel_hi:[1,0]
	v_pk_fma_f32 v[250:251], v[250:251], v[228:229], v[190:191]
	v_pk_mul_f32 v[228:229], v[160:161], v[0:1] op_sel_hi:[1,0]
	v_pk_fma_f32 v[32:33], v[32:33], v[228:229], v[192:193]
	v_pk_mul_f32 v[228:229], v[162:163], v[0:1] op_sel_hi:[1,0]
	v_pk_fma_f32 v[34:35], v[34:35], v[228:229], v[194:195]
	v_pk_mul_f32 v[228:229], v[164:165], v[0:1] op_sel_hi:[1,0]
	v_pk_fma_f32 v[36:37], v[36:37], v[228:229], v[196:197]
	v_pk_mul_f32 v[228:229], v[166:167], v[0:1] op_sel_hi:[1,0]
	v_pk_fma_f32 v[38:39], v[38:39], v[228:229], v[198:199]
	v_pk_mul_f32 v[228:229], v[168:169], v[0:1] op_sel_hi:[1,0]
	v_pk_fma_f32 v[20:21], v[20:21], v[228:229], v[200:201]
	v_pk_mul_f32 v[228:229], v[170:171], v[0:1] op_sel_hi:[1,0]
	v_pk_fma_f32 v[22:23], v[22:23], v[228:229], v[202:203]
	v_cvt_pk_bf16_f32 v24, v126, v127
	v_cvt_pk_bf16_f32 v25, v128, v129
	v_cvt_pk_bf16_f32 v26, v130, v131
	v_cvt_pk_bf16_f32 v27, v132, v133
	v_cvt_pk_bf16_f32 v8, v240, v241
	v_cvt_pk_bf16_f32 v9, v242, v243
	v_cvt_pk_bf16_f32 v10, v244, v245
	v_cvt_pk_bf16_f32 v11, v246, v247
	v_cvt_pk_bf16_f32 v220, v248, v249
	v_cvt_pk_bf16_f32 v221, v250, v251
	v_cvt_pk_bf16_f32 v222, v32, v33
	v_cvt_pk_bf16_f32 v223, v34, v35
	v_cvt_pk_bf16_f32 v224, v36, v37
	v_cvt_pk_bf16_f32 v225, v38, v39
	v_cvt_pk_bf16_f32 v226, v20, v21
	v_cvt_pk_bf16_f32 v227, v22, v23
	global_store_dwordx2 v1, v[24:25], s[90:91] offset:0
	global_store_dwordx2 v1, v[26:27], s[90:91] offset:512
	global_store_dwordx2 v1, v[8:9], s[90:91] offset:1024
	global_store_dwordx2 v1, v[10:11], s[90:91] offset:1536
	global_store_dwordx2 v1, v[220:221], s[90:91] offset:2048
	global_store_dwordx2 v1, v[222:223], s[90:91] offset:2560
	global_store_dwordx2 v1, v[224:225], s[90:91] offset:3072
	global_store_dwordx2 v1, v[226:227], s[90:91] offset:3584
	s_add_u32 s90, s90, 0x800000
	s_addc_u32 s91, s91, 0
	s_waitcnt vmcnt(16)
	v_lshlrev_b32_e32 v126, 16, v204
	v_and_b32_e32 v127, 0xffff0000, v204
	v_lshlrev_b32_e32 v128, 16, v205
	v_and_b32_e32 v129, 0xffff0000, v205
	v_lshlrev_b32_e32 v130, 16, v206
	v_and_b32_e32 v131, 0xffff0000, v206
	v_lshlrev_b32_e32 v132, 16, v207
	v_and_b32_e32 v133, 0xffff0000, v207
	v_lshlrev_b32_e32 v240, 16, v208
	v_and_b32_e32 v241, 0xffff0000, v208
	v_lshlrev_b32_e32 v242, 16, v209
	v_and_b32_e32 v243, 0xffff0000, v209
	v_lshlrev_b32_e32 v244, 16, v210
	v_and_b32_e32 v245, 0xffff0000, v210
	v_lshlrev_b32_e32 v246, 16, v211
	v_and_b32_e32 v247, 0xffff0000, v211
	v_lshlrev_b32_e32 v248, 16, v212
	v_and_b32_e32 v249, 0xffff0000, v212
	v_lshlrev_b32_e32 v250, 16, v213
	v_and_b32_e32 v251, 0xffff0000, v213
	v_lshlrev_b32_e32 v32, 16, v214
	v_and_b32_e32 v33, 0xffff0000, v214
	v_lshlrev_b32_e32 v34, 16, v215
	v_and_b32_e32 v35, 0xffff0000, v215
	v_lshlrev_b32_e32 v36, 16, v216
	v_and_b32_e32 v37, 0xffff0000, v216
	v_lshlrev_b32_e32 v38, 16, v217
	v_and_b32_e32 v39, 0xffff0000, v217
	v_lshlrev_b32_e32 v20, 16, v218
	v_and_b32_e32 v21, 0xffff0000, v218
	v_lshlrev_b32_e32 v22, 16, v219
	v_and_b32_e32 v23, 0xffff0000, v219
	v_pk_add_f32 v[228:229], v[126:127], v[128:129]
	v_pk_add_f32 v[228:229], v[228:229], v[130:131]
	v_pk_add_f32 v[228:229], v[228:229], v[132:133]
	v_pk_add_f32 v[228:229], v[228:229], v[240:241]
	v_pk_add_f32 v[228:229], v[228:229], v[242:243]
	v_pk_add_f32 v[228:229], v[228:229], v[244:245]
	v_pk_add_f32 v[228:229], v[228:229], v[246:247]
	v_pk_add_f32 v[228:229], v[228:229], v[248:249]
	v_pk_add_f32 v[228:229], v[228:229], v[250:251]
	v_pk_add_f32 v[228:229], v[228:229], v[32:33]
	v_pk_add_f32 v[228:229], v[228:229], v[34:35]
	v_pk_add_f32 v[228:229], v[228:229], v[36:37]
	v_pk_add_f32 v[228:229], v[228:229], v[38:39]
	v_pk_add_f32 v[228:229], v[228:229], v[20:21]
	v_pk_add_f32 v[228:229], v[228:229], v[22:23]
	v_add_f32_e32 v228, v228, v229
	s_nop 1
	v_add_f32_dpp v228, v228, v228 quad_perm:[1,0,3,2] row_mask:0xf bank_mask:0xf bound_ctrl:1
	s_nop 1
	v_add_f32_dpp v228, v228, v228 quad_perm:[2,3,0,1] row_mask:0xf bank_mask:0xf bound_ctrl:1
	s_nop 1
	v_add_f32_dpp v228, v228, v228 row_half_mirror row_mask:0xf bank_mask:0xf bound_ctrl:1
	s_nop 1
	v_add_f32_dpp v228, v228, v228 row_mirror row_mask:0xf bank_mask:0xf bound_ctrl:1
	v_mov_b32_e32 v2, v228
	s_nop 1
	v_permlane16_swap_b32 v228, v2
	s_nop 0
	v_add_f32_e32 v228, v228, v2
	v_mov_b32_e32 v2, v228
	s_nop 1
	v_permlane32_swap_b32 v228, v2
	s_nop 0
	v_add_f32_e32 v228, v228, v2
	v_mul_f32_e32 v134, 0x3a000000, v228
	v_pk_add_f32 v[126:127], v[126:127], v[134:135] op_sel_hi:[1,0] neg_lo:[0,1] neg_hi:[0,1]
	v_pk_add_f32 v[128:129], v[128:129], v[134:135] op_sel_hi:[1,0] neg_lo:[0,1] neg_hi:[0,1]
	v_pk_add_f32 v[130:131], v[130:131], v[134:135] op_sel_hi:[1,0] neg_lo:[0,1] neg_hi:[0,1]
	v_pk_add_f32 v[132:133], v[132:133], v[134:135] op_sel_hi:[1,0] neg_lo:[0,1] neg_hi:[0,1]
	v_pk_add_f32 v[240:241], v[240:241], v[134:135] op_sel_hi:[1,0] neg_lo:[0,1] neg_hi:[0,1]
	v_pk_add_f32 v[242:243], v[242:243], v[134:135] op_sel_hi:[1,0] neg_lo:[0,1] neg_hi:[0,1]
	v_pk_add_f32 v[244:245], v[244:245], v[134:135] op_sel_hi:[1,0] neg_lo:[0,1] neg_hi:[0,1]
	v_pk_add_f32 v[246:247], v[246:247], v[134:135] op_sel_hi:[1,0] neg_lo:[0,1] neg_hi:[0,1]
	v_pk_add_f32 v[248:249], v[248:249], v[134:135] op_sel_hi:[1,0] neg_lo:[0,1] neg_hi:[0,1]
	v_pk_add_f32 v[250:251], v[250:251], v[134:135] op_sel_hi:[1,0] neg_lo:[0,1] neg_hi:[0,1]
	v_pk_add_f32 v[32:33], v[32:33], v[134:135] op_sel_hi:[1,0] neg_lo:[0,1] neg_hi:[0,1]
	v_pk_add_f32 v[34:35], v[34:35], v[134:135] op_sel_hi:[1,0] neg_lo:[0,1] neg_hi:[0,1]
	v_pk_add_f32 v[36:37], v[36:37], v[134:135] op_sel_hi:[1,0] neg_lo:[0,1] neg_hi:[0,1]
	v_pk_add_f32 v[38:39], v[38:39], v[134:135] op_sel_hi:[1,0] neg_lo:[0,1] neg_hi:[0,1]
	v_pk_add_f32 v[20:21], v[20:21], v[134:135] op_sel_hi:[1,0] neg_lo:[0,1] neg_hi:[0,1]
	v_pk_add_f32 v[22:23], v[22:23], v[134:135] op_sel_hi:[1,0] neg_lo:[0,1] neg_hi:[0,1]
	v_pk_mul_f32 v[228:229], v[126:127], v[126:127]
	v_pk_fma_f32 v[228:229], v[128:129], v[128:129], v[228:229]
	v_pk_fma_f32 v[228:229], v[130:131], v[130:131], v[228:229]
	v_pk_fma_f32 v[228:229], v[132:133], v[132:133], v[228:229]
	v_pk_fma_f32 v[228:229], v[240:241], v[240:241], v[228:229]
	v_pk_fma_f32 v[228:229], v[242:243], v[242:243], v[228:229]
	v_pk_fma_f32 v[228:229], v[244:245], v[244:245], v[228:229]
	v_pk_fma_f32 v[228:229], v[246:247], v[246:247], v[228:229]
	v_pk_fma_f32 v[228:229], v[248:249], v[248:249], v[228:229]
	v_pk_fma_f32 v[228:229], v[250:251], v[250:251], v[228:229]
	v_pk_fma_f32 v[228:229], v[32:33], v[32:33], v[228:229]
	v_pk_fma_f32 v[228:229], v[34:35], v[34:35], v[228:229]
	v_pk_fma_f32 v[228:229], v[36:37], v[36:37], v[228:229]
	v_pk_fma_f32 v[228:229], v[38:39], v[38:39], v[228:229]
	v_pk_fma_f32 v[228:229], v[20:21], v[20:21], v[228:229]
	v_pk_fma_f32 v[228:229], v[22:23], v[22:23], v[228:229]
	v_add_f32_e32 v228, v228, v229
	s_nop 1
	v_add_f32_dpp v228, v228, v228 quad_perm:[1,0,3,2] row_mask:0xf bank_mask:0xf bound_ctrl:1
	s_nop 1
	v_add_f32_dpp v228, v228, v228 quad_perm:[2,3,0,1] row_mask:0xf bank_mask:0xf bound_ctrl:1
	s_nop 1
	v_add_f32_dpp v228, v228, v228 row_half_mirror row_mask:0xf bank_mask:0xf bound_ctrl:1
	s_nop 1
	v_add_f32_dpp v228, v228, v228 row_mirror row_mask:0xf bank_mask:0xf bound_ctrl:1
	v_mov_b32_e32 v2, v228
	s_nop 1
	v_permlane16_swap_b32 v228, v2
	s_nop 0
	v_add_f32_e32 v228, v228, v2
	v_mov_b32_e32 v2, v228
	s_nop 1
	v_permlane32_swap_b32 v228, v2
	s_nop 0
	v_add_f32_e32 v228, v228, v2
	v_mul_f32_e32 v0, 0x3a000000, v228
	v_add_f32_e32 v0, 0x3727c5ac, v0
	v_rsq_f32_e32 v0, v0
	s_nop 0
	v_pk_mul_f32 v[228:229], v[140:141], v[0:1] op_sel_hi:[1,0]
	v_pk_fma_f32 v[126:127], v[126:127], v[228:229], v[172:173]
	v_pk_mul_f32 v[228:229], v[142:143], v[0:1] op_sel_hi:[1,0]
	v_pk_fma_f32 v[128:129], v[128:129], v[228:229], v[174:175]
	v_pk_mul_f32 v[228:229], v[144:145], v[0:1] op_sel_hi:[1,0]
	v_pk_fma_f32 v[130:131], v[130:131], v[228:229], v[176:177]
	v_pk_mul_f32 v[228:229], v[146:147], v[0:1] op_sel_hi:[1,0]
	v_pk_fma_f32 v[132:133], v[132:133], v[228:229], v[178:179]
	v_pk_mul_f32 v[228:229], v[148:149], v[0:1] op_sel_hi:[1,0]
	v_pk_fma_f32 v[240:241], v[240:241], v[228:229], v[180:181]
	v_pk_mul_f32 v[228:229], v[150:151], v[0:1] op_sel_hi:[1,0]
	v_pk_fma_f32 v[242:243], v[242:243], v[228:229], v[182:183]
	v_pk_mul_f32 v[228:229], v[152:153], v[0:1] op_sel_hi:[1,0]
	v_pk_fma_f32 v[244:245], v[244:245], v[228:229], v[184:185]
	v_pk_mul_f32 v[228:229], v[154:155], v[0:1] op_sel_hi:[1,0]
	v_pk_fma_f32 v[246:247], v[246:247], v[228:229], v[186:187]
	v_pk_mul_f32 v[228:229], v[156:157], v[0:1] op_sel_hi:[1,0]
	v_pk_fma_f32 v[248:249], v[248:249], v[228:229], v[188:189]
	v_pk_mul_f32 v[228:229], v[158:159], v[0:1] op_sel_hi:[1,0]
	v_pk_fma_f32 v[250:251], v[250:251], v[228:229], v[190:191]
	v_pk_mul_f32 v[228:229], v[160:161], v[0:1] op_sel_hi:[1,0]
	v_pk_fma_f32 v[32:33], v[32:33], v[228:229], v[192:193]
	v_pk_mul_f32 v[228:229], v[162:163], v[0:1] op_sel_hi:[1,0]
	v_pk_fma_f32 v[34:35], v[34:35], v[228:229], v[194:195]
	v_pk_mul_f32 v[228:229], v[164:165], v[0:1] op_sel_hi:[1,0]
	v_pk_fma_f32 v[36:37], v[36:37], v[228:229], v[196:197]
	v_pk_mul_f32 v[228:229], v[166:167], v[0:1] op_sel_hi:[1,0]
	v_pk_fma_f32 v[38:39], v[38:39], v[228:229], v[198:199]
	v_pk_mul_f32 v[228:229], v[168:169], v[0:1] op_sel_hi:[1,0]
	v_pk_fma_f32 v[20:21], v[20:21], v[228:229], v[200:201]
	v_pk_mul_f32 v[228:229], v[170:171], v[0:1] op_sel_hi:[1,0]
	v_pk_fma_f32 v[22:23], v[22:23], v[228:229], v[202:203]
	v_cvt_pk_bf16_f32 v204, v126, v127
	v_cvt_pk_bf16_f32 v205, v128, v129
	v_cvt_pk_bf16_f32 v206, v130, v131
	v_cvt_pk_bf16_f32 v207, v132, v133
	v_cvt_pk_bf16_f32 v208, v240, v241
	v_cvt_pk_bf16_f32 v209, v242, v243
	v_cvt_pk_bf16_f32 v210, v244, v245
	v_cvt_pk_bf16_f32 v211, v246, v247
	v_cvt_pk_bf16_f32 v212, v248, v249
	v_cvt_pk_bf16_f32 v213, v250, v251
	v_cvt_pk_bf16_f32 v214, v32, v33
	v_cvt_pk_bf16_f32 v215, v34, v35
	v_cvt_pk_bf16_f32 v216, v36, v37
	v_cvt_pk_bf16_f32 v217, v38, v39
	v_cvt_pk_bf16_f32 v218, v20, v21
	v_cvt_pk_bf16_f32 v219, v22, v23
	global_store_dwordx2 v1, v[204:205], s[90:91] offset:0
	global_store_dwordx2 v1, v[206:207], s[90:91] offset:512
	global_store_dwordx2 v1, v[208:209], s[90:91] offset:1024
	global_store_dwordx2 v1, v[210:211], s[90:91] offset:1536
	global_store_dwordx2 v1, v[212:213], s[90:91] offset:2048
	global_store_dwordx2 v1, v[214:215], s[90:91] offset:2560
	global_store_dwordx2 v1, v[216:217], s[90:91] offset:3072
	global_store_dwordx2 v1, v[218:219], s[90:91] offset:3584
	s_add_u32 s90, s90, 0x800000
	s_addc_u32 s91, s91, 0

.LBB0_2453:
	s_cmp_lt_i32 s30, 19
	s_cselect_b64 s[4:5], -1, 0
	s_and_b64 s[4:5], s[4:5], s[6:7]
	s_andn2_b64 vcc, exec, s[4:5]
	s_cbranch_vccnz .LBB0_2469
	s_load_dwordx4 s[8:11], s[0:1], 0x158
	s_load_dwordx2 s[6:7], s[0:1], 0x168
	v_lshl_add_u32 v32, s2, 3, v230
	s_movk_i32 s3, 0x2000
	v_cmp_gt_i32_e32 vcc, s3, v32
	s_waitcnt lgkmcnt(0)
	s_mov_b64 s[14:15], 0
	s_cmp_lg_u64 s[6:7], 0
	s_cselect_b64 s[12:13], -1, 0
	s_and_saveexec_b64 s[16:17], vcc
	s_cbranch_execz .LBB0_2461
	s_load_dwordx4 s[60:63], s[0:1], 0x158
	s_load_dwordx2 s[92:93], s[0:1], 0x168
	v_lshl_add_u32 v2, s2, 3, v230
	v_lshlrev_b32_e32 v137, 4, v136
	v_lshlrev_b32_e32 v1, 3, v136
	v_lshl_add_u32 v1, v2, 12, v1
	v_add_u32_e32 v4, 0x1000, v137
	v_lshl_add_u32 v75, v2, 13, v137
	v_add_u32_e32 v135, 0x1000, v75
	s_add_u32 s88, s28, 0xe600000
	s_addc_u32 s89, s29, 0
	global_load_dwordx2 v[204:205], v1, s[88:89] offset:0 nt
	global_load_dwordx2 v[206:207], v1, s[88:89] offset:512 nt
	global_load_dwordx2 v[208:209], v1, s[88:89] offset:1024 nt
	global_load_dwordx2 v[210:211], v1, s[88:89] offset:1536 nt
	global_load_dwordx2 v[212:213], v1, s[88:89] offset:2048 nt
	global_load_dwordx2 v[214:215], v1, s[88:89] offset:2560 nt
	global_load_dwordx2 v[216:217], v1, s[88:89] offset:3072 nt
	global_load_dwordx2 v[218:219], v1, s[88:89] offset:3584 nt
	s_add_u32 s88, s88, 0x800000
	s_addc_u32 s89, s89, 0
	s_waitcnt lgkmcnt(0)
	global_load_dwordx4 v[140:143], v137, s[60:61] offset:0
	global_load_dwordx4 v[144:147], v137, s[60:61] offset:1024
	global_load_dwordx4 v[148:151], v137, s[60:61] offset:2048
	global_load_dwordx4 v[152:155], v137, s[60:61] offset:3072
	global_load_dwordx4 v[156:159], v4, s[60:61] offset:0
	global_load_dwordx4 v[160:163], v4, s[60:61] offset:1024
	global_load_dwordx4 v[164:167], v4, s[60:61] offset:2048
	global_load_dwordx4 v[168:171], v4, s[60:61] offset:3072
	global_load_dwordx4 v[172:175], v137, s[62:63] offset:0
	global_load_dwordx4 v[176:179], v137, s[62:63] offset:1024
	global_load_dwordx4 v[180:183], v137, s[62:63] offset:2048
	global_load_dwordx4 v[184:187], v137, s[62:63] offset:3072
	global_load_dwordx4 v[188:191], v4, s[62:63] offset:0
	global_load_dwordx4 v[192:195], v4, s[62:63] offset:1024
	global_load_dwordx4 v[196:199], v4, s[62:63] offset:2048
	global_load_dwordx4 v[200:203], v4, s[62:63] offset:3072
	global_load_dwordx2 v[110:111], v1, s[88:89] offset:0 nt
	global_load_dwordx2 v[112:113], v1, s[88:89] offset:512 nt
	global_load_dwordx2 v[114:115], v1, s[88:89] offset:1024 nt
	global_load_dwordx2 v[116:117], v1, s[88:89] offset:1536 nt
	global_load_dwordx2 v[118:119], v1, s[88:89] offset:2048 nt
	global_load_dwordx2 v[120:121], v1, s[88:89] offset:2560 nt
	global_load_dwordx2 v[122:123], v1, s[88:89] offset:3072 nt
	global_load_dwordx2 v[124:125], v1, s[88:89] offset:3584 nt
	s_add_u32 s88, s88, 0x800000
	s_addc_u32 s89, s89, 0
	global_load_dwordx2 v[24:25], v1, s[88:89] offset:0 nt
	global_load_dwordx2 v[26:27], v1, s[88:89] offset:512 nt
	global_load_dwordx2 v[8:9], v1, s[88:89] offset:1024 nt
	global_load_dwordx2 v[10:11], v1, s[88:89] offset:1536 nt
	global_load_dwordx2 v[220:221], v1, s[88:89] offset:2048 nt
	global_load_dwordx2 v[222:223], v1, s[88:89] offset:2560 nt
	global_load_dwordx2 v[224:225], v1, s[88:89] offset:3072 nt
	global_load_dwordx2 v[226:227], v1, s[88:89] offset:3584 nt
	s_add_u32 s88, s88, 0x800000
	s_addc_u32 s89, s89, 0
	s_mov_b64 s[90:91], s[92:93]
	s_waitcnt vmcnt(32)
	v_lshlrev_b32_e32 v126, 16, v204
	v_and_b32_e32 v127, 0xffff0000, v204
	v_lshlrev_b32_e32 v128, 16, v205
	v_and_b32_e32 v129, 0xffff0000, v205
	v_lshlrev_b32_e32 v130, 16, v206
	v_and_b32_e32 v131, 0xffff0000, v206
	v_lshlrev_b32_e32 v132, 16, v207
	v_and_b32_e32 v133, 0xffff0000, v207
	v_lshlrev_b32_e32 v240, 16, v208
	v_and_b32_e32 v241, 0xffff0000, v208
	v_lshlrev_b32_e32 v242, 16, v209
	v_and_b32_e32 v243, 0xffff0000, v209
	v_lshlrev_b32_e32 v244, 16, v210
	v_and_b32_e32 v245, 0xffff0000, v210
	v_lshlrev_b32_e32 v246, 16, v211
	v_and_b32_e32 v247, 0xffff0000, v211
	v_lshlrev_b32_e32 v248, 16, v212
	v_and_b32_e32 v249, 0xffff0000, v212
	v_lshlrev_b32_e32 v250, 16, v213
	v_and_b32_e32 v251, 0xffff0000, v213
	v_lshlrev_b32_e32 v32, 16, v214
	v_and_b32_e32 v33, 0xffff0000, v214
	v_lshlrev_b32_e32 v34, 16, v215
	v_and_b32_e32 v35, 0xffff0000, v215
	v_lshlrev_b32_e32 v36, 16, v216
	v_and_b32_e32 v37, 0xffff0000, v216
	v_lshlrev_b32_e32 v38, 16, v217
	v_and_b32_e32 v39, 0xffff0000, v217
	v_lshlrev_b32_e32 v20, 16, v218
	v_and_b32_e32 v21, 0xffff0000, v218
	v_lshlrev_b32_e32 v22, 16, v219
	v_and_b32_e32 v23, 0xffff0000, v219
	v_pk_add_f32 v[228:229], v[126:127], v[128:129]
	v_pk_add_f32 v[228:229], v[228:229], v[130:131]
	v_pk_add_f32 v[228:229], v[228:229], v[132:133]
	v_pk_add_f32 v[228:229], v[228:229], v[240:241]
	v_pk_add_f32 v[228:229], v[228:229], v[242:243]
	v_pk_add_f32 v[228:229], v[228:229], v[244:245]
	v_pk_add_f32 v[228:229], v[228:229], v[246:247]
	v_pk_add_f32 v[228:229], v[228:229], v[248:249]
	v_pk_add_f32 v[228:229], v[228:229], v[250:251]
	v_pk_add_f32 v[228:229], v[228:229], v[32:33]
	v_pk_add_f32 v[228:229], v[228:229], v[34:35]
	v_pk_add_f32 v[228:229], v[228:229], v[36:37]
	v_pk_add_f32 v[228:229], v[228:229], v[38:39]
	v_pk_add_f32 v[228:229], v[228:229], v[20:21]
	v_pk_add_f32 v[228:229], v[228:229], v[22:23]
	v_add_f32_e32 v228, v228, v229
	s_nop 1
	v_add_f32_dpp v228, v228, v228 quad_perm:[1,0,3,2] row_mask:0xf bank_mask:0xf bound_ctrl:1
	s_nop 1
	v_add_f32_dpp v228, v228, v228 quad_perm:[2,3,0,1] row_mask:0xf bank_mask:0xf bound_ctrl:1
	s_nop 1
	v_add_f32_dpp v228, v228, v228 row_half_mirror row_mask:0xf bank_mask:0xf bound_ctrl:1
	s_nop 1
	v_add_f32_dpp v228, v228, v228 row_mirror row_mask:0xf bank_mask:0xf bound_ctrl:1
	v_mov_b32_e32 v2, v228
	s_nop 1
	v_permlane16_swap_b32 v228, v2
	s_nop 0
	v_add_f32_e32 v228, v228, v2
	v_mov_b32_e32 v2, v228
	s_nop 1
	v_permlane32_swap_b32 v228, v2
	s_nop 0
	v_add_f32_e32 v228, v228, v2
	v_mul_f32_e32 v134, 0x3a000000, v228
	v_pk_add_f32 v[126:127], v[126:127], v[134:135] op_sel_hi:[1,0] neg_lo:[0,1] neg_hi:[0,1]
	v_pk_add_f32 v[128:129], v[128:129], v[134:135] op_sel_hi:[1,0] neg_lo:[0,1] neg_hi:[0,1]
	v_pk_add_f32 v[130:131], v[130:131], v[134:135] op_sel_hi:[1,0] neg_lo:[0,1] neg_hi:[0,1]
	v_pk_add_f32 v[132:133], v[132:133], v[134:135] op_sel_hi:[1,0] neg_lo:[0,1] neg_hi:[0,1]
	v_pk_add_f32 v[240:241], v[240:241], v[134:135] op_sel_hi:[1,0] neg_lo:[0,1] neg_hi:[0,1]
	v_pk_add_f32 v[242:243], v[242:243], v[134:135] op_sel_hi:[1,0] neg_lo:[0,1] neg_hi:[0,1]
	v_pk_add_f32 v[244:245], v[244:245], v[134:135] op_sel_hi:[1,0] neg_lo:[0,1] neg_hi:[0,1]
	v_pk_add_f32 v[246:247], v[246:247], v[134:135] op_sel_hi:[1,0] neg_lo:[0,1] neg_hi:[0,1]
	v_pk_add_f32 v[248:249], v[248:249], v[134:135] op_sel_hi:[1,0] neg_lo:[0,1] neg_hi:[0,1]
	v_pk_add_f32 v[250:251], v[250:251], v[134:135] op_sel_hi:[1,0] neg_lo:[0,1] neg_hi:[0,1]
	v_pk_add_f32 v[32:33], v[32:33], v[134:135] op_sel_hi:[1,0] neg_lo:[0,1] neg_hi:[0,1]
	v_pk_add_f32 v[34:35], v[34:35], v[134:135] op_sel_hi:[1,0] neg_lo:[0,1] neg_hi:[0,1]
	v_pk_add_f32 v[36:37], v[36:37], v[134:135] op_sel_hi:[1,0] neg_lo:[0,1] neg_hi:[0,1]
	v_pk_add_f32 v[38:39], v[38:39], v[134:135] op_sel_hi:[1,0] neg_lo:[0,1] neg_hi:[0,1]
	v_pk_add_f32 v[20:21], v[20:21], v[134:135] op_sel_hi:[1,0] neg_lo:[0,1] neg_hi:[0,1]
	v_pk_add_f32 v[22:23], v[22:23], v[134:135] op_sel_hi:[1,0] neg_lo:[0,1] neg_hi:[0,1]
	v_pk_mul_f32 v[228:229], v[126:127], v[126:127]
	v_pk_fma_f32 v[228:229], v[128:129], v[128:129], v[228:229]
	v_pk_fma_f32 v[228:229], v[130:131], v[130:131], v[228:229]
	v_pk_fma_f32 v[228:229], v[132:133], v[132:133], v[228:229]
	v_pk_fma_f32 v[228:229], v[240:241], v[240:241], v[228:229]
	v_pk_fma_f32 v[228:229], v[242:243], v[242:243], v[228:229]
	v_pk_fma_f32 v[228:229], v[244:245], v[244:245], v[228:229]
	v_pk_fma_f32 v[228:229], v[246:247], v[246:247], v[228:229]
	v_pk_fma_f32 v[228:229], v[248:249], v[248:249], v[228:229]
	v_pk_fma_f32 v[228:229], v[250:251], v[250:251], v[228:229]
	v_pk_fma_f32 v[228:229], v[32:33], v[32:33], v[228:229]
	v_pk_fma_f32 v[228:229], v[34:35], v[34:35], v[228:229]
	v_pk_fma_f32 v[228:229], v[36:37], v[36:37], v[228:229]
	v_pk_fma_f32 v[228:229], v[38:39], v[38:39], v[228:229]
	v_pk_fma_f32 v[228:229], v[20:21], v[20:21], v[228:229]
	v_pk_fma_f32 v[228:229], v[22:23], v[22:23], v[228:229]
	v_add_f32_e32 v228, v228, v229
	s_nop 1
	v_add_f32_dpp v228, v228, v228 quad_perm:[1,0,3,2] row_mask:0xf bank_mask:0xf bound_ctrl:1
	s_nop 1
	v_add_f32_dpp v228, v228, v228 quad_perm:[2,3,0,1] row_mask:0xf bank_mask:0xf bound_ctrl:1
	s_nop 1
	v_add_f32_dpp v228, v228, v228 row_half_mirror row_mask:0xf bank_mask:0xf bound_ctrl:1
	s_nop 1
	v_add_f32_dpp v228, v228, v228 row_mirror row_mask:0xf bank_mask:0xf bound_ctrl:1
	v_mov_b32_e32 v2, v228
	s_nop 1
	v_permlane16_swap_b32 v228, v2
	s_nop 0
	v_add_f32_e32 v228, v228, v2
	v_mov_b32_e32 v2, v228
	s_nop 1
	v_permlane32_swap_b32 v228, v2
	s_nop 0
	v_add_f32_e32 v228, v228, v2
	v_mul_f32_e32 v0, 0x3a000000, v228
	v_add_f32_e32 v0, 0x3727c5ac, v0
	v_rsq_f32_e32 v0, v0
	s_waitcnt vmcnt(16)
	v_pk_mul_f32 v[228:229], v[140:141], v[0:1] op_sel_hi:[1,0]
	v_pk_fma_f32 v[126:127], v[126:127], v[228:229], v[172:173]
	v_pk_mul_f32 v[228:229], v[142:143], v[0:1] op_sel_hi:[1,0]
	v_pk_fma_f32 v[128:129], v[128:129], v[228:229], v[174:175]
	v_pk_mul_f32 v[228:229], v[144:145], v[0:1] op_sel_hi:[1,0]
	v_pk_fma_f32 v[130:131], v[130:131], v[228:229], v[176:177]
	v_pk_mul_f32 v[228:229], v[146:147], v[0:1] op_sel_hi:[1,0]
	v_pk_fma_f32 v[132:133], v[132:133], v[228:229], v[178:179]
	v_pk_mul_f32 v[228:229], v[148:149], v[0:1] op_sel_hi:[1,0]
	v_pk_fma_f32 v[240:241], v[240:241], v[228:229], v[180:181]
	v_pk_mul_f32 v[228:229], v[150:151], v[0:1] op_sel_hi:[1,0]
	v_pk_fma_f32 v[242:243], v[242:243], v[228:229], v[182:183]
	v_pk_mul_f32 v[228:229], v[152:153], v[0:1] op_sel_hi:[1,0]
	v_pk_fma_f32 v[244:245], v[244:245], v[228:229], v[184:185]
	v_pk_mul_f32 v[228:229], v[154:155], v[0:1] op_sel_hi:[1,0]
	v_pk_fma_f32 v[246:247], v[246:247], v[228:229], v[186:187]
	v_pk_mul_f32 v[228:229], v[156:157], v[0:1] op_sel_hi:[1,0]
	v_pk_fma_f32 v[248:249], v[248:249], v[228:229], v[188:189]
	v_pk_mul_f32 v[228:229], v[158:159], v[0:1] op_sel_hi:[1,0]
	v_pk_fma_f32 v[250:251], v[250:251], v[228:229], v[190:191]
	v_pk_mul_f32 v[228:229], v[160:161], v[0:1] op_sel_hi:[1,0]
	v_pk_fma_f32 v[32:33], v[32:33], v[228:229], v[192:193]
	v_pk_mul_f32 v[228:229], v[162:163], v[0:1] op_sel_hi:[1,0]
	v_pk_fma_f32 v[34:35], v[34:35], v[228:229], v[194:195]
	v_pk_mul_f32 v[228:229], v[164:165], v[0:1] op_sel_hi:[1,0]
	v_pk_fma_f32 v[36:37], v[36:37], v[228:229], v[196:197]
	v_pk_mul_f32 v[228:229], v[166:167], v[0:1] op_sel_hi:[1,0]
	v_pk_fma_f32 v[38:39], v[38:39], v[228:229], v[198:199]
	v_pk_mul_f32 v[228:229], v[168:169], v[0:1] op_sel_hi:[1,0]
	v_pk_fma_f32 v[20:21], v[20:21], v[228:229], v[200:201]
	v_pk_mul_f32 v[228:229], v[170:171], v[0:1] op_sel_hi:[1,0]
	v_pk_fma_f32 v[22:23], v[22:23], v[228:229], v[202:203]
	global_store_dwordx4 v75, v[126:129], s[90:91] offset:0
	global_store_dwordx4 v75, v[130:133], s[90:91] offset:1024
	global_store_dwordx4 v75, v[240:243], s[90:91] offset:2048
	global_store_dwordx4 v75, v[244:247], s[90:91] offset:3072
	global_store_dwordx4 v135, v[248:251], s[90:91] offset:0
	global_store_dwordx4 v135, v[32:35], s[90:91] offset:1024
	global_store_dwordx4 v135, v[36:39], s[90:91] offset:2048
	global_store_dwordx4 v135, v[20:23], s[90:91] offset:3072
	s_add_u32 s90, s90, 0x1000000
	s_addc_u32 s91, s91, 0
	global_load_dwordx2 v[204:205], v1, s[88:89] offset:0 nt
	global_load_dwordx2 v[206:207], v1, s[88:89] offset:512 nt
	global_load_dwordx2 v[208:209], v1, s[88:89] offset:1024 nt
	global_load_dwordx2 v[210:211], v1, s[88:89] offset:1536 nt
	global_load_dwordx2 v[212:213], v1, s[88:89] offset:2048 nt
	global_load_dwordx2 v[214:215], v1, s[88:89] offset:2560 nt
	global_load_dwordx2 v[216:217], v1, s[88:89] offset:3072 nt
	global_load_dwordx2 v[218:219], v1, s[88:89] offset:3584 nt
	s_add_u32 s88, s88, 0x800000
	s_addc_u32 s89, s89, 0
	s_waitcnt vmcnt(24)
	v_lshlrev_b32_e32 v126, 16, v110
	v_and_b32_e32 v127, 0xffff0000, v110
	v_lshlrev_b32_e32 v128, 16, v111
	v_and_b32_e32 v129, 0xffff0000, v111
	v_lshlrev_b32_e32 v130, 16, v112
	v_and_b32_e32 v131, 0xffff0000, v112
	v_lshlrev_b32_e32 v132, 16, v113
	v_and_b32_e32 v133, 0xffff0000, v113
	v_lshlrev_b32_e32 v240, 16, v114
	v_and_b32_e32 v241, 0xffff0000, v114
	v_lshlrev_b32_e32 v242, 16, v115
	v_and_b32_e32 v243, 0xffff0000, v115
	v_lshlrev_b32_e32 v244, 16, v116
	v_and_b32_e32 v245, 0xffff0000, v116
	v_lshlrev_b32_e32 v246, 16, v117
	v_and_b32_e32 v247, 0xffff0000, v117
	v_lshlrev_b32_e32 v248, 16, v118
	v_and_b32_e32 v249, 0xffff0000, v118
	v_lshlrev_b32_e32 v250, 16, v119
	v_and_b32_e32 v251, 0xffff0000, v119
	v_lshlrev_b32_e32 v32, 16, v120
	v_and_b32_e32 v33, 0xffff0000, v120
	v_lshlrev_b32_e32 v34, 16, v121
	v_and_b32_e32 v35, 0xffff0000, v121
	v_lshlrev_b32_e32 v36, 16, v122
	v_and_b32_e32 v37, 0xffff0000, v122
	v_lshlrev_b32_e32 v38, 16, v123
	v_and_b32_e32 v39, 0xffff0000, v123
	v_lshlrev_b32_e32 v20, 16, v124
	v_and_b32_e32 v21, 0xffff0000, v124
	v_lshlrev_b32_e32 v22, 16, v125
	v_and_b32_e32 v23, 0xffff0000, v125
	v_pk_add_f32 v[228:229], v[126:127], v[128:129]
	v_pk_add_f32 v[228:229], v[228:229], v[130:131]
	v_pk_add_f32 v[228:229], v[228:229], v[132:133]
	v_pk_add_f32 v[228:229], v[228:229], v[240:241]
	v_pk_add_f32 v[228:229], v[228:229], v[242:243]
	v_pk_add_f32 v[228:229], v[228:229], v[244:245]
	v_pk_add_f32 v[228:229], v[228:229], v[246:247]
	v_pk_add_f32 v[228:229], v[228:229], v[248:249]
	v_pk_add_f32 v[228:229], v[228:229], v[250:251]
	v_pk_add_f32 v[228:229], v[228:229], v[32:33]
	v_pk_add_f32 v[228:229], v[228:229], v[34:35]
	v_pk_add_f32 v[228:229], v[228:229], v[36:37]
	v_pk_add_f32 v[228:229], v[228:229], v[38:39]
	v_pk_add_f32 v[228:229], v[228:229], v[20:21]
	v_pk_add_f32 v[228:229], v[228:229], v[22:23]
	v_add_f32_e32 v228, v228, v229
	s_nop 1
	v_add_f32_dpp v228, v228, v228 quad_perm:[1,0,3,2] row_mask:0xf bank_mask:0xf bound_ctrl:1
	s_nop 1
	v_add_f32_dpp v228, v228, v228 quad_perm:[2,3,0,1] row_mask:0xf bank_mask:0xf bound_ctrl:1
	s_nop 1
	v_add_f32_dpp v228, v228, v228 row_half_mirror row_mask:0xf bank_mask:0xf bound_ctrl:1
	s_nop 1
	v_add_f32_dpp v228, v228, v228 row_mirror row_mask:0xf bank_mask:0xf bound_ctrl:1
	v_mov_b32_e32 v2, v228
	s_nop 1
	v_permlane16_swap_b32 v228, v2
	s_nop 0
	v_add_f32_e32 v228, v228, v2
	v_mov_b32_e32 v2, v228
	s_nop 1
	v_permlane32_swap_b32 v228, v2
	s_nop 0
	v_add_f32_e32 v228, v228, v2
	v_mul_f32_e32 v134, 0x3a000000, v228
	v_pk_add_f32 v[126:127], v[126:127], v[134:135] op_sel_hi:[1,0] neg_lo:[0,1] neg_hi:[0,1]
	v_pk_add_f32 v[128:129], v[128:129], v[134:135] op_sel_hi:[1,0] neg_lo:[0,1] neg_hi:[0,1]
	v_pk_add_f32 v[130:131], v[130:131], v[134:135] op_sel_hi:[1,0] neg_lo:[0,1] neg_hi:[0,1]
	v_pk_add_f32 v[132:133], v[132:133], v[134:135] op_sel_hi:[1,0] neg_lo:[0,1] neg_hi:[0,1]
	v_pk_add_f32 v[240:241], v[240:241], v[134:135] op_sel_hi:[1,0] neg_lo:[0,1] neg_hi:[0,1]
	v_pk_add_f32 v[242:243], v[242:243], v[134:135] op_sel_hi:[1,0] neg_lo:[0,1] neg_hi:[0,1]
	v_pk_add_f32 v[244:245], v[244:245], v[134:135] op_sel_hi:[1,0] neg_lo:[0,1] neg_hi:[0,1]
	v_pk_add_f32 v[246:247], v[246:247], v[134:135] op_sel_hi:[1,0] neg_lo:[0,1] neg_hi:[0,1]
	v_pk_add_f32 v[248:249], v[248:249], v[134:135] op_sel_hi:[1,0] neg_lo:[0,1] neg_hi:[0,1]
	v_pk_add_f32 v[250:251], v[250:251], v[134:135] op_sel_hi:[1,0] neg_lo:[0,1] neg_hi:[0,1]
	v_pk_add_f32 v[32:33], v[32:33], v[134:135] op_sel_hi:[1,0] neg_lo:[0,1] neg_hi:[0,1]
	v_pk_add_f32 v[34:35], v[34:35], v[134:135] op_sel_hi:[1,0] neg_lo:[0,1] neg_hi:[0,1]
	v_pk_add_f32 v[36:37], v[36:37], v[134:135] op_sel_hi:[1,0] neg_lo:[0,1] neg_hi:[0,1]
	v_pk_add_f32 v[38:39], v[38:39], v[134:135] op_sel_hi:[1,0] neg_lo:[0,1] neg_hi:[0,1]
	v_pk_add_f32 v[20:21], v[20:21], v[134:135] op_sel_hi:[1,0] neg_lo:[0,1] neg_hi:[0,1]
	v_pk_add_f32 v[22:23], v[22:23], v[134:135] op_sel_hi:[1,0] neg_lo:[0,1] neg_hi:[0,1]
	v_pk_mul_f32 v[228:229], v[126:127], v[126:127]
	v_pk_fma_f32 v[228:229], v[128:129], v[128:129], v[228:229]
	v_pk_fma_f32 v[228:229], v[130:131], v[130:131], v[228:229]
	v_pk_fma_f32 v[228:229], v[132:133], v[132:133], v[228:229]
	v_pk_fma_f32 v[228:229], v[240:241], v[240:241], v[228:229]
	v_pk_fma_f32 v[228:229], v[242:243], v[242:243], v[228:229]
	v_pk_fma_f32 v[228:229], v[244:245], v[244:245], v[228:229]
	v_pk_fma_f32 v[228:229], v[246:247], v[246:247], v[228:229]
	v_pk_fma_f32 v[228:229], v[248:249], v[248:249], v[228:229]
	v_pk_fma_f32 v[228:229], v[250:251], v[250:251], v[228:229]
	v_pk_fma_f32 v[228:229], v[32:33], v[32:33], v[228:229]
	v_pk_fma_f32 v[228:229], v[34:35], v[34:35], v[228:229]
	v_pk_fma_f32 v[228:229], v[36:37], v[36:37], v[228:229]
	v_pk_fma_f32 v[228:229], v[38:39], v[38:39], v[228:229]
	v_pk_fma_f32 v[228:229], v[20:21], v[20:21], v[228:229]
	v_pk_fma_f32 v[228:229], v[22:23], v[22:23], v[228:229]
	v_add_f32_e32 v228, v228, v229
	s_nop 1
	v_add_f32_dpp v228, v228, v228 quad_perm:[1,0,3,2] row_mask:0xf bank_mask:0xf bound_ctrl:1
	s_nop 1
	v_add_f32_dpp v228, v228, v228 quad_perm:[2,3,0,1] row_mask:0xf bank_mask:0xf bound_ctrl:1
	s_nop 1
	v_add_f32_dpp v228, v228, v228 row_half_mirror row_mask:0xf bank_mask:0xf bound_ctrl:1
	s_nop 1
	v_add_f32_dpp v228, v228, v228 row_mirror row_mask:0xf bank_mask:0xf bound_ctrl:1
	v_mov_b32_e32 v2, v228
	s_nop 1
	v_permlane16_swap_b32 v228, v2
	s_nop 0
	v_add_f32_e32 v228, v228, v2
	v_mov_b32_e32 v2, v228
	s_nop 1
	v_permlane32_swap_b32 v228, v2
	s_nop 0
	v_add_f32_e32 v228, v228, v2
	v_mul_f32_e32 v0, 0x3a000000, v228
	v_add_f32_e32 v0, 0x3727c5ac, v0
	v_rsq_f32_e32 v0, v0
	s_nop 0
	v_pk_mul_f32 v[228:229], v[140:141], v[0:1] op_sel_hi:[1,0]
	v_pk_fma_f32 v[126:127], v[126:127], v[228:229], v[172:173]
	v_pk_mul_f32 v[228:229], v[142:143], v[0:1] op_sel_hi:[1,0]
	v_pk_fma_f32 v[128:129], v[128:129], v[228:229], v[174:175]
	v_pk_mul_f32 v[228:229], v[144:145], v[0:1] op_sel_hi:[1,0]
	v_pk_fma_f32 v[130:131], v[130:131], v[228:229], v[176:177]
	v_pk_mul_f32 v[228:229], v[146:147], v[0:1] op_sel_hi:[1,0]
	v_pk_fma_f32 v[132:133], v[132:133], v[228:229], v[178:179]
	v_pk_mul_f32 v[228:229], v[148:149], v[0:1] op_sel_hi:[1,0]
	v_pk_fma_f32 v[240:241], v[240:241], v[228:229], v[180:181]
	v_pk_mul_f32 v[228:229], v[150:151], v[0:1] op_sel_hi:[1,0]
	v_pk_fma_f32 v[242:243], v[242:243], v[228:229], v[182:183]
	v_pk_mul_f32 v[228:229], v[152:153], v[0:1] op_sel_hi:[1,0]
	v_pk_fma_f32 v[244:245], v[244:245], v[228:229], v[184:185]
	v_pk_mul_f32 v[228:229], v[154:155], v[0:1] op_sel_hi:[1,0]
	v_pk_fma_f32 v[246:247], v[246:247], v[228:229], v[186:187]
	v_pk_mul_f32 v[228:229], v[156:157], v[0:1] op_sel_hi:[1,0]
	v_pk_fma_f32 v[248:249], v[248:249], v[228:229], v[188:189]
	v_pk_mul_f32 v[228:229], v[158:159], v[0:1] op_sel_hi:[1,0]
	v_pk_fma_f32 v[250:251], v[250:251], v[228:229], v[190:191]
	v_pk_mul_f32 v[228:229], v[160:161], v[0:1] op_sel_hi:[1,0]
	v_pk_fma_f32 v[32:33], v[32:33], v[228:229], v[192:193]
	v_pk_mul_f32 v[228:229], v[162:163], v[0:1] op_sel_hi:[1,0]
	v_pk_fma_f32 v[34:35], v[34:35], v[228:229], v[194:195]
	v_pk_mul_f32 v[228:229], v[164:165], v[0:1] op_sel_hi:[1,0]
	v_pk_fma_f32 v[36:37], v[36:37], v[228:229], v[196:197]
	v_pk_mul_f32 v[228:229], v[166:167], v[0:1] op_sel_hi:[1,0]
	v_pk_fma_f32 v[38:39], v[38:39], v[228:229], v[198:199]
	v_pk_mul_f32 v[228:229], v[168:169], v[0:1] op_sel_hi:[1,0]
	v_pk_fma_f32 v[20:21], v[20:21], v[228:229], v[200:201]
	v_pk_mul_f32 v[228:229], v[170:171], v[0:1] op_sel_hi:[1,0]
	v_pk_fma_f32 v[22:23], v[22:23], v[228:229], v[202:203]
	global_store_dwordx4 v75, v[126:129], s[90:91] offset:0
	global_store_dwordx4 v75, v[130:133], s[90:91] offset:1024
	global_store_dwordx4 v75, v[240:243], s[90:91] offset:2048
	global_store_dwordx4 v75, v[244:247], s[90:91] offset:3072
	global_store_dwordx4 v135, v[248:251], s[90:91] offset:0
	global_store_dwordx4 v135, v[32:35], s[90:91] offset:1024
	global_store_dwordx4 v135, v[36:39], s[90:91] offset:2048
	global_store_dwordx4 v135, v[20:23], s[90:91] offset:3072
	s_add_u32 s90, s90, 0x1000000
	s_addc_u32 s91, s91, 0
	s_waitcnt vmcnt(24)
	v_lshlrev_b32_e32 v126, 16, v24
	v_and_b32_e32 v127, 0xffff0000, v24
	v_lshlrev_b32_e32 v128, 16, v25
	v_and_b32_e32 v129, 0xffff0000, v25
	v_lshlrev_b32_e32 v130, 16, v26
	v_and_b32_e32 v131, 0xffff0000, v26
	v_lshlrev_b32_e32 v132, 16, v27
	v_and_b32_e32 v133, 0xffff0000, v27
	v_lshlrev_b32_e32 v240, 16, v8
	v_and_b32_e32 v241, 0xffff0000, v8
	v_lshlrev_b32_e32 v242, 16, v9
	v_and_b32_e32 v243, 0xffff0000, v9
	v_lshlrev_b32_e32 v244, 16, v10
	v_and_b32_e32 v245, 0xffff0000, v10
	v_lshlrev_b32_e32 v246, 16, v11
	v_and_b32_e32 v247, 0xffff0000, v11
	v_lshlrev_b32_e32 v248, 16, v220
	v_and_b32_e32 v249, 0xffff0000, v220
	v_lshlrev_b32_e32 v250, 16, v221
	v_and_b32_e32 v251, 0xffff0000, v221
	v_lshlrev_b32_e32 v32, 16, v222
	v_and_b32_e32 v33, 0xffff0000, v222
	v_lshlrev_b32_e32 v34, 16, v223
	v_and_b32_e32 v35, 0xffff0000, v223
	v_lshlrev_b32_e32 v36, 16, v224
	v_and_b32_e32 v37, 0xffff0000, v224
	v_lshlrev_b32_e32 v38, 16, v225
	v_and_b32_e32 v39, 0xffff0000, v225
	v_lshlrev_b32_e32 v20, 16, v226
	v_and_b32_e32 v21, 0xffff0000, v226
	v_lshlrev_b32_e32 v22, 16, v227
	v_and_b32_e32 v23, 0xffff0000, v227
	v_pk_add_f32 v[228:229], v[126:127], v[128:129]
	v_pk_add_f32 v[228:229], v[228:229], v[130:131]
	v_pk_add_f32 v[228:229], v[228:229], v[132:133]
	v_pk_add_f32 v[228:229], v[228:229], v[240:241]
	v_pk_add_f32 v[228:229], v[228:229], v[242:243]
	v_pk_add_f32 v[228:229], v[228:229], v[244:245]
	v_pk_add_f32 v[228:229], v[228:229], v[246:247]
	v_pk_add_f32 v[228:229], v[228:229], v[248:249]
	v_pk_add_f32 v[228:229], v[228:229], v[250:251]
	v_pk_add_f32 v[228:229], v[228:229], v[32:33]
	v_pk_add_f32 v[228:229], v[228:229], v[34:35]
	v_pk_add_f32 v[228:229], v[228:229], v[36:37]
	v_pk_add_f32 v[228:229], v[228:229], v[38:39]
	v_pk_add_f32 v[228:229], v[228:229], v[20:21]
	v_pk_add_f32 v[228:229], v[228:229], v[22:23]
	v_add_f32_e32 v228, v228, v229
	s_nop 1
	v_add_f32_dpp v228, v228, v228 quad_perm:[1,0,3,2] row_mask:0xf bank_mask:0xf bound_ctrl:1
	s_nop 1
	v_add_f32_dpp v228, v228, v228 quad_perm:[2,3,0,1] row_mask:0xf bank_mask:0xf bound_ctrl:1
	s_nop 1
	v_add_f32_dpp v228, v228, v228 row_half_mirror row_mask:0xf bank_mask:0xf bound_ctrl:1
	s_nop 1
	v_add_f32_dpp v228, v228, v228 row_mirror row_mask:0xf bank_mask:0xf bound_ctrl:1
	v_mov_b32_e32 v2, v228
	s_nop 1
	v_permlane16_swap_b32 v228, v2
	s_nop 0
	v_add_f32_e32 v228, v228, v2
	v_mov_b32_e32 v2, v228
	s_nop 1
	v_permlane32_swap_b32 v228, v2
	s_nop 0
	v_add_f32_e32 v228, v228, v2
	v_mul_f32_e32 v134, 0x3a000000, v228
	v_pk_add_f32 v[126:127], v[126:127], v[134:135] op_sel_hi:[1,0] neg_lo:[0,1] neg_hi:[0,1]
	v_pk_add_f32 v[128:129], v[128:129], v[134:135] op_sel_hi:[1,0] neg_lo:[0,1] neg_hi:[0,1]
	v_pk_add_f32 v[130:131], v[130:131], v[134:135] op_sel_hi:[1,0] neg_lo:[0,1] neg_hi:[0,1]
	v_pk_add_f32 v[132:133], v[132:133], v[134:135] op_sel_hi:[1,0] neg_lo:[0,1] neg_hi:[0,1]
	v_pk_add_f32 v[240:241], v[240:241], v[134:135] op_sel_hi:[1,0] neg_lo:[0,1] neg_hi:[0,1]
	v_pk_add_f32 v[242:243], v[242:243], v[134:135] op_sel_hi:[1,0] neg_lo:[0,1] neg_hi:[0,1]
	v_pk_add_f32 v[244:245], v[244:245], v[134:135] op_sel_hi:[1,0] neg_lo:[0,1] neg_hi:[0,1]
	v_pk_add_f32 v[246:247], v[246:247], v[134:135] op_sel_hi:[1,0] neg_lo:[0,1] neg_hi:[0,1]
	v_pk_add_f32 v[248:249], v[248:249], v[134:135] op_sel_hi:[1,0] neg_lo:[0,1] neg_hi:[0,1]
	v_pk_add_f32 v[250:251], v[250:251], v[134:135] op_sel_hi:[1,0] neg_lo:[0,1] neg_hi:[0,1]
	v_pk_add_f32 v[32:33], v[32:33], v[134:135] op_sel_hi:[1,0] neg_lo:[0,1] neg_hi:[0,1]
	v_pk_add_f32 v[34:35], v[34:35], v[134:135] op_sel_hi:[1,0] neg_lo:[0,1] neg_hi:[0,1]
	v_pk_add_f32 v[36:37], v[36:37], v[134:135] op_sel_hi:[1,0] neg_lo:[0,1] neg_hi:[0,1]
	v_pk_add_f32 v[38:39], v[38:39], v[134:135] op_sel_hi:[1,0] neg_lo:[0,1] neg_hi:[0,1]
	v_pk_add_f32 v[20:21], v[20:21], v[134:135] op_sel_hi:[1,0] neg_lo:[0,1] neg_hi:[0,1]
	v_pk_add_f32 v[22:23], v[22:23], v[134:135] op_sel_hi:[1,0] neg_lo:[0,1] neg_hi:[0,1]
	v_pk_mul_f32 v[228:229], v[126:127], v[126:127]
	v_pk_fma_f32 v[228:229], v[128:129], v[128:129], v[228:229]
	v_pk_fma_f32 v[228:229], v[130:131], v[130:131], v[228:229]
	v_pk_fma_f32 v[228:229], v[132:133], v[132:133], v[228:229]
	v_pk_fma_f32 v[228:229], v[240:241], v[240:241], v[228:229]
	v_pk_fma_f32 v[228:229], v[242:243], v[242:243], v[228:229]
	v_pk_fma_f32 v[228:229], v[244:245], v[244:245], v[228:229]
	v_pk_fma_f32 v[228:229], v[246:247], v[246:247], v[228:229]
	v_pk_fma_f32 v[228:229], v[248:249], v[248:249], v[228:229]
	v_pk_fma_f32 v[228:229], v[250:251], v[250:251], v[228:229]
	v_pk_fma_f32 v[228:229], v[32:33], v[32:33], v[228:229]
	v_pk_fma_f32 v[228:229], v[34:35], v[34:35], v[228:229]
	v_pk_fma_f32 v[228:229], v[36:37], v[36:37], v[228:229]
	v_pk_fma_f32 v[228:229], v[38:39], v[38:39], v[228:229]
	v_pk_fma_f32 v[228:229], v[20:21], v[20:21], v[228:229]
	v_pk_fma_f32 v[228:229], v[22:23], v[22:23], v[228:229]
	v_add_f32_e32 v228, v228, v229
	s_nop 1
	v_add_f32_dpp v228, v228, v228 quad_perm:[1,0,3,2] row_mask:0xf bank_mask:0xf bound_ctrl:1
	s_nop 1
	v_add_f32_dpp v228, v228, v228 quad_perm:[2,3,0,1] row_mask:0xf bank_mask:0xf bound_ctrl:1
	s_nop 1
	v_add_f32_dpp v228, v228, v228 row_half_mirror row_mask:0xf bank_mask:0xf bound_ctrl:1
	s_nop 1
	v_add_f32_dpp v228, v228, v228 row_mirror row_mask:0xf bank_mask:0xf bound_ctrl:1
	v_mov_b32_e32 v2, v228
	s_nop 1
	v_permlane16_swap_b32 v228, v2
	s_nop 0
	v_add_f32_e32 v228, v228, v2
	v_mov_b32_e32 v2, v228
	s_nop 1
	v_permlane32_swap_b32 v228, v2
	s_nop 0
	v_add_f32_e32 v228, v228, v2
	v_mul_f32_e32 v0, 0x3a000000, v228
	v_add_f32_e32 v0, 0x3727c5ac, v0
	v_rsq_f32_e32 v0, v0
	s_nop 0
	v_pk_mul_f32 v[228:229], v[140:141], v[0:1] op_sel_hi:[1,0]
	v_pk_fma_f32 v[126:127], v[126:127], v[228:229], v[172:173]
	v_pk_mul_f32 v[228:229], v[142:143], v[0:1] op_sel_hi:[1,0]
	v_pk_fma_f32 v[128:129], v[128:129], v[228:229], v[174:175]
	v_pk_mul_f32 v[228:229], v[144:145], v[0:1] op_sel_hi:[1,0]
	v_pk_fma_f32 v[130:131], v[130:131], v[228:229], v[176:177]
	v_pk_mul_f32 v[228:229], v[146:147], v[0:1] op_sel_hi:[1,0]
	v_pk_fma_f32 v[132:133], v[132:133], v[228:229], v[178:179]
	v_pk_mul_f32 v[228:229], v[148:149], v[0:1] op_sel_hi:[1,0]
	v_pk_fma_f32 v[240:241], v[240:241], v[228:229], v[180:181]
	v_pk_mul_f32 v[228:229], v[150:151], v[0:1] op_sel_hi:[1,0]
	v_pk_fma_f32 v[242:243], v[242:243], v[228:229], v[182:183]
	v_pk_mul_f32 v[228:229], v[152:153], v[0:1] op_sel_hi:[1,0]
	v_pk_fma_f32 v[244:245], v[244:245], v[228:229], v[184:185]
	v_pk_mul_f32 v[228:229], v[154:155], v[0:1] op_sel_hi:[1,0]
	v_pk_fma_f32 v[246:247], v[246:247], v[228:229], v[186:187]
	v_pk_mul_f32 v[228:229], v[156:157], v[0:1] op_sel_hi:[1,0]
	v_pk_fma_f32 v[248:249], v[248:249], v[228:229], v[188:189]
	v_pk_mul_f32 v[228:229], v[158:159], v[0:1] op_sel_hi:[1,0]
	v_pk_fma_f32 v[250:251], v[250:251], v[228:229], v[190:191]
	v_pk_mul_f32 v[228:229], v[160:161], v[0:1] op_sel_hi:[1,0]
	v_pk_fma_f32 v[32:33], v[32:33], v[228:229], v[192:193]
	v_pk_mul_f32 v[228:229], v[162:163], v[0:1] op_sel_hi:[1,0]
	v_pk_fma_f32 v[34:35], v[34:35], v[228:229], v[194:195]
	v_pk_mul_f32 v[228:229], v[164:165], v[0:1] op_sel_hi:[1,0]
	v_pk_fma_f32 v[36:37], v[36:37], v[228:229], v[196:197]
	v_pk_mul_f32 v[228:229], v[166:167], v[0:1] op_sel_hi:[1,0]
	v_pk_fma_f32 v[38:39], v[38:39], v[228:229], v[198:199]
	v_pk_mul_f32 v[228:229], v[168:169], v[0:1] op_sel_hi:[1,0]
	v_pk_fma_f32 v[20:21], v[20:21], v[228:229], v[200:201]
	v_pk_mul_f32 v[228:229], v[170:171], v[0:1] op_sel_hi:[1,0]
	v_pk_fma_f32 v[22:23], v[22:23], v[228:229], v[202:203]
	global_store_dwordx4 v75, v[126:129], s[90:91] offset:0
	global_store_dwordx4 v75, v[130:133], s[90:91] offset:1024
	global_store_dwordx4 v75, v[240:243], s[90:91] offset:2048
	global_store_dwordx4 v75, v[244:247], s[90:91] offset:3072
	global_store_dwordx4 v135, v[248:251], s[90:91] offset:0
	global_store_dwordx4 v135, v[32:35], s[90:91] offset:1024
	global_store_dwordx4 v135, v[36:39], s[90:91] offset:2048
	global_store_dwordx4 v135, v[20:23], s[90:91] offset:3072
	s_add_u32 s90, s90, 0x1000000
	s_addc_u32 s91, s91, 0
	s_waitcnt vmcnt(16)
	v_lshlrev_b32_e32 v126, 16, v204
	v_and_b32_e32 v127, 0xffff0000, v204
	v_lshlrev_b32_e32 v128, 16, v205
	v_and_b32_e32 v129, 0xffff0000, v205
	v_lshlrev_b32_e32 v130, 16, v206
	v_and_b32_e32 v131, 0xffff0000, v206
	v_lshlrev_b32_e32 v132, 16, v207
	v_and_b32_e32 v133, 0xffff0000, v207
	v_lshlrev_b32_e32 v240, 16, v208
	v_and_b32_e32 v241, 0xffff0000, v208
	v_lshlrev_b32_e32 v242, 16, v209
	v_and_b32_e32 v243, 0xffff0000, v209
	v_lshlrev_b32_e32 v244, 16, v210
	v_and_b32_e32 v245, 0xffff0000, v210
	v_lshlrev_b32_e32 v246, 16, v211
	v_and_b32_e32 v247, 0xffff0000, v211
	v_lshlrev_b32_e32 v248, 16, v212
	v_and_b32_e32 v249, 0xffff0000, v212
	v_lshlrev_b32_e32 v250, 16, v213
	v_and_b32_e32 v251, 0xffff0000, v213
	v_lshlrev_b32_e32 v32, 16, v214
	v_and_b32_e32 v33, 0xffff0000, v214
	v_lshlrev_b32_e32 v34, 16, v215
	v_and_b32_e32 v35, 0xffff0000, v215
	v_lshlrev_b32_e32 v36, 16, v216
	v_and_b32_e32 v37, 0xffff0000, v216
	v_lshlrev_b32_e32 v38, 16, v217
	v_and_b32_e32 v39, 0xffff0000, v217
	v_lshlrev_b32_e32 v20, 16, v218
	v_and_b32_e32 v21, 0xffff0000, v218
	v_lshlrev_b32_e32 v22, 16, v219
	v_and_b32_e32 v23, 0xffff0000, v219
	v_pk_add_f32 v[228:229], v[126:127], v[128:129]
	v_pk_add_f32 v[228:229], v[228:229], v[130:131]
	v_pk_add_f32 v[228:229], v[228:229], v[132:133]
	v_pk_add_f32 v[228:229], v[228:229], v[240:241]
	v_pk_add_f32 v[228:229], v[228:229], v[242:243]
	v_pk_add_f32 v[228:229], v[228:229], v[244:245]
	v_pk_add_f32 v[228:229], v[228:229], v[246:247]
	v_pk_add_f32 v[228:229], v[228:229], v[248:249]
	v_pk_add_f32 v[228:229], v[228:229], v[250:251]
	v_pk_add_f32 v[228:229], v[228:229], v[32:33]
	v_pk_add_f32 v[228:229], v[228:229], v[34:35]
	v_pk_add_f32 v[228:229], v[228:229], v[36:37]
	v_pk_add_f32 v[228:229], v[228:229], v[38:39]
	v_pk_add_f32 v[228:229], v[228:229], v[20:21]
	v_pk_add_f32 v[228:229], v[228:229], v[22:23]
	v_add_f32_e32 v228, v228, v229
	s_nop 1
	v_add_f32_dpp v228, v228, v228 quad_perm:[1,0,3,2] row_mask:0xf bank_mask:0xf bound_ctrl:1
	s_nop 1
	v_add_f32_dpp v228, v228, v228 quad_perm:[2,3,0,1] row_mask:0xf bank_mask:0xf bound_ctrl:1
	s_nop 1
	v_add_f32_dpp v228, v228, v228 row_half_mirror row_mask:0xf bank_mask:0xf bound_ctrl:1
	s_nop 1
	v_add_f32_dpp v228, v228, v228 row_mirror row_mask:0xf bank_mask:0xf bound_ctrl:1
	v_mov_b32_e32 v2, v228
	s_nop 1
	v_permlane16_swap_b32 v228, v2
	s_nop 0
	v_add_f32_e32 v228, v228, v2
	v_mov_b32_e32 v2, v228
	s_nop 1
	v_permlane32_swap_b32 v228, v2
	s_nop 0
	v_add_f32_e32 v228, v228, v2
	v_mul_f32_e32 v134, 0x3a000000, v228
	v_pk_add_f32 v[126:127], v[126:127], v[134:135] op_sel_hi:[1,0] neg_lo:[0,1] neg_hi:[0,1]
	v_pk_add_f32 v[128:129], v[128:129], v[134:135] op_sel_hi:[1,0] neg_lo:[0,1] neg_hi:[0,1]
	v_pk_add_f32 v[130:131], v[130:131], v[134:135] op_sel_hi:[1,0] neg_lo:[0,1] neg_hi:[0,1]
	v_pk_add_f32 v[132:133], v[132:133], v[134:135] op_sel_hi:[1,0] neg_lo:[0,1] neg_hi:[0,1]
	v_pk_add_f32 v[240:241], v[240:241], v[134:135] op_sel_hi:[1,0] neg_lo:[0,1] neg_hi:[0,1]
	v_pk_add_f32 v[242:243], v[242:243], v[134:135] op_sel_hi:[1,0] neg_lo:[0,1] neg_hi:[0,1]
	v_pk_add_f32 v[244:245], v[244:245], v[134:135] op_sel_hi:[1,0] neg_lo:[0,1] neg_hi:[0,1]
	v_pk_add_f32 v[246:247], v[246:247], v[134:135] op_sel_hi:[1,0] neg_lo:[0,1] neg_hi:[0,1]
	v_pk_add_f32 v[248:249], v[248:249], v[134:135] op_sel_hi:[1,0] neg_lo:[0,1] neg_hi:[0,1]
	v_pk_add_f32 v[250:251], v[250:251], v[134:135] op_sel_hi:[1,0] neg_lo:[0,1] neg_hi:[0,1]
	v_pk_add_f32 v[32:33], v[32:33], v[134:135] op_sel_hi:[1,0] neg_lo:[0,1] neg_hi:[0,1]
	v_pk_add_f32 v[34:35], v[34:35], v[134:135] op_sel_hi:[1,0] neg_lo:[0,1] neg_hi:[0,1]
	v_pk_add_f32 v[36:37], v[36:37], v[134:135] op_sel_hi:[1,0] neg_lo:[0,1] neg_hi:[0,1]
	v_pk_add_f32 v[38:39], v[38:39], v[134:135] op_sel_hi:[1,0] neg_lo:[0,1] neg_hi:[0,1]
	v_pk_add_f32 v[20:21], v[20:21], v[134:135] op_sel_hi:[1,0] neg_lo:[0,1] neg_hi:[0,1]
	v_pk_add_f32 v[22:23], v[22:23], v[134:135] op_sel_hi:[1,0] neg_lo:[0,1] neg_hi:[0,1]
	v_pk_mul_f32 v[228:229], v[126:127], v[126:127]
	v_pk_fma_f32 v[228:229], v[128:129], v[128:129], v[228:229]
	v_pk_fma_f32 v[228:229], v[130:131], v[130:131], v[228:229]
	v_pk_fma_f32 v[228:229], v[132:133], v[132:133], v[228:229]
	v_pk_fma_f32 v[228:229], v[240:241], v[240:241], v[228:229]
	v_pk_fma_f32 v[228:229], v[242:243], v[242:243], v[228:229]
	v_pk_fma_f32 v[228:229], v[244:245], v[244:245], v[228:229]
	v_pk_fma_f32 v[228:229], v[246:247], v[246:247], v[228:229]
	v_pk_fma_f32 v[228:229], v[248:249], v[248:249], v[228:229]
	v_pk_fma_f32 v[228:229], v[250:251], v[250:251], v[228:229]
	v_pk_fma_f32 v[228:229], v[32:33], v[32:33], v[228:229]
	v_pk_fma_f32 v[228:229], v[34:35], v[34:35], v[228:229]
	v_pk_fma_f32 v[228:229], v[36:37], v[36:37], v[228:229]
	v_pk_fma_f32 v[228:229], v[38:39], v[38:39], v[228:229]
	v_pk_fma_f32 v[228:229], v[20:21], v[20:21], v[228:229]
	v_pk_fma_f32 v[228:229], v[22:23], v[22:23], v[228:229]
	v_add_f32_e32 v228, v228, v229
	s_nop 1
	v_add_f32_dpp v228, v228, v228 quad_perm:[1,0,3,2] row_mask:0xf bank_mask:0xf bound_ctrl:1
	s_nop 1
	v_add_f32_dpp v228, v228, v228 quad_perm:[2,3,0,1] row_mask:0xf bank_mask:0xf bound_ctrl:1
	s_nop 1
	v_add_f32_dpp v228, v228, v228 row_half_mirror row_mask:0xf bank_mask:0xf bound_ctrl:1
	s_nop 1
	v_add_f32_dpp v228, v228, v228 row_mirror row_mask:0xf bank_mask:0xf bound_ctrl:1
	v_mov_b32_e32 v2, v228
	s_nop 1
	v_permlane16_swap_b32 v228, v2
	s_nop 0
	v_add_f32_e32 v228, v228, v2
	v_mov_b32_e32 v2, v228
	s_nop 1
	v_permlane32_swap_b32 v228, v2
	s_nop 0
	v_add_f32_e32 v228, v228, v2
	v_mul_f32_e32 v0, 0x3a000000, v228
	v_add_f32_e32 v0, 0x3727c5ac, v0
	v_rsq_f32_e32 v0, v0
	s_nop 0
	v_pk_mul_f32 v[228:229], v[140:141], v[0:1] op_sel_hi:[1,0]
	v_pk_fma_f32 v[126:127], v[126:127], v[228:229], v[172:173]
	v_pk_mul_f32 v[228:229], v[142:143], v[0:1] op_sel_hi:[1,0]
	v_pk_fma_f32 v[128:129], v[128:129], v[228:229], v[174:175]
	v_pk_mul_f32 v[228:229], v[144:145], v[0:1] op_sel_hi:[1,0]
	v_pk_fma_f32 v[130:131], v[130:131], v[228:229], v[176:177]
	v_pk_mul_f32 v[228:229], v[146:147], v[0:1] op_sel_hi:[1,0]
	v_pk_fma_f32 v[132:133], v[132:133], v[228:229], v[178:179]
	v_pk_mul_f32 v[228:229], v[148:149], v[0:1] op_sel_hi:[1,0]
	v_pk_fma_f32 v[240:241], v[240:241], v[228:229], v[180:181]
	v_pk_mul_f32 v[228:229], v[150:151], v[0:1] op_sel_hi:[1,0]
	v_pk_fma_f32 v[242:243], v[242:243], v[228:229], v[182:183]
	v_pk_mul_f32 v[228:229], v[152:153], v[0:1] op_sel_hi:[1,0]
	v_pk_fma_f32 v[244:245], v[244:245], v[228:229], v[184:185]
	v_pk_mul_f32 v[228:229], v[154:155], v[0:1] op_sel_hi:[1,0]
	v_pk_fma_f32 v[246:247], v[246:247], v[228:229], v[186:187]
	v_pk_mul_f32 v[228:229], v[156:157], v[0:1] op_sel_hi:[1,0]
	v_pk_fma_f32 v[248:249], v[248:249], v[228:229], v[188:189]
	v_pk_mul_f32 v[228:229], v[158:159], v[0:1] op_sel_hi:[1,0]
	v_pk_fma_f32 v[250:251], v[250:251], v[228:229], v[190:191]
	v_pk_mul_f32 v[228:229], v[160:161], v[0:1] op_sel_hi:[1,0]
	v_pk_fma_f32 v[32:33], v[32:33], v[228:229], v[192:193]
	v_pk_mul_f32 v[228:229], v[162:163], v[0:1] op_sel_hi:[1,0]
	v_pk_fma_f32 v[34:35], v[34:35], v[228:229], v[194:195]
	v_pk_mul_f32 v[228:229], v[164:165], v[0:1] op_sel_hi:[1,0]
	v_pk_fma_f32 v[36:37], v[36:37], v[228:229], v[196:197]
	v_pk_mul_f32 v[228:229], v[166:167], v[0:1] op_sel_hi:[1,0]
	v_pk_fma_f32 v[38:39], v[38:39], v[228:229], v[198:199]
	v_pk_mul_f32 v[228:229], v[168:169], v[0:1] op_sel_hi:[1,0]
	v_pk_fma_f32 v[20:21], v[20:21], v[228:229], v[200:201]
	v_pk_mul_f32 v[228:229], v[170:171], v[0:1] op_sel_hi:[1,0]
	v_pk_fma_f32 v[22:23], v[22:23], v[228:229], v[202:203]
	global_store_dwordx4 v75, v[126:129], s[90:91] offset:0
	global_store_dwordx4 v75, v[130:133], s[90:91] offset:1024
	global_store_dwordx4 v75, v[240:243], s[90:91] offset:2048
	global_store_dwordx4 v75, v[244:247], s[90:91] offset:3072
	global_store_dwordx4 v135, v[248:251], s[90:91] offset:0
	global_store_dwordx4 v135, v[32:35], s[90:91] offset:1024
	global_store_dwordx4 v135, v[36:39], s[90:91] offset:2048
	global_store_dwordx4 v135, v[20:23], s[90:91] offset:3072
	s_add_u32 s90, s90, 0x1000000
	s_addc_u32 s91, s91, 0
